# all per-segment s_setprio flips of the GEMM K-loops removed (timing-only change)
# speedup vs baseline: 1.0080x; 1.0080x over previous
; #define PG8_STAGE_T(bufoff, gbase, voff, AUX) do { _Pragma("unroll") for (int _i = 0; _i < 2; ++_i) \
;         __builtin_amdgcn_global_load_lds((const unsigned*)((const char*)(gbase) + (voff)[_i]), (PG8_LAS unsigned*)(lds + (bufoff) + ldsw + _i * 8192), 16, 0, AUX); } while (0)
; #define PG8_LDA(dst, b, h) do { _Pragma("unroll") for (int m = 0; m < 4; ++m) _Pragma("unroll") for (int k = 0; k < 2; ++k) dst[m][k] = *(const PG8_LAS bf16x8*)(lds + PG8_SA(b, h) + aoff + m * 2048 + k * 1024); } while (0)
; #define PG8_LDB(dst, b, h) do { _Pragma("unroll") for (int n = 0; n < 2; ++n) _Pragma("unroll") for (int k = 0; k < 2; ++k) dst[n][k] = *(const PG8_LAS bf16x8*)(lds + PG8_SB(b, h) + boff + n * 2048 + k * 1024); } while (0)
; #define PG8_MMA(ai, bj, At, Bt) do { __builtin_amdgcn_s_setprio(1); _Pragma("unroll") for (int m = 0; m < 4; ++m) _Pragma("unroll") for (int n = 0; n < 2; ++n) _Pragma("unroll") for (int k = 0; k < 2; ++k) \
;         acc[ai][bj][m][n] = __builtin_amdgcn_mfma_f32_16x16x32_bf16(Bt[n][k], At[m][k], acc[ai][bj][m][n], 0, 0, 0); __builtin_amdgcn_s_setprio(0); } while (0)
; #define PG8_WAIT_V(n) asm volatile("s_waitcnt vmcnt(" #n ")" ::: "memory")
; #define PG8_WAIT_L(n) asm volatile("s_waitcnt lgkmcnt(" #n ")" ::: "memory")
; #define PG8_BAR __builtin_amdgcn_s_barrier()
; #define PG8_SCHED __builtin_amdgcn_sched_barrier(0)
;     ...
;             PG8_LDB(B0, 0, 0); PG8_LDB(B1, 0, 1); PG8_SCHED; PG8_LDA(At, 0, 0); if (!pe) { PG8_STAGE_T(PG8_SA(1, 1), a1 + hstep, voffA, AUX_A); }
;             if (!pe) { PG8_WAIT_V(8); } PG8_WAIT_L(0); PG8_BAR; PG8_MMA(0, 0, At, B0); PG8_MMA(0, 1, At, B1); PG8_BAR; PG8_SCHED;
;             PG8_LDA(At, 0, 1); PG8_STAGE_T(PG8_SB(0, 0), b2, voffB, AUX_B); PG8_STAGE_T(PG8_SB(0, 1), b2 + hstep, voffB, AUX_B); PG8_STAGE_T(PG8_SA(0, 0), a2, voffA, AUX_A);
;             if (!pe) { PG8_WAIT_V(8); } PG8_WAIT_L(0); PG8_BAR; PG8_MMA(1, 0, At, B0); PG8_MMA(1, 1, At, B1); PG8_BAR; PG8_SCHED;
.LBB0_244:
	ds_read_b128 v[146:149], v166
	ds_read_b128 v[162:165], v166 offset:1024
	ds_read_b128 v[170:173], v166 offset:2048
	ds_read_b128 v[174:177], v166 offset:3072
	ds_read_b128 v[178:181], v167
	ds_read_b128 v[182:185], v167 offset:1024
	ds_read_b128 v[186:189], v167 offset:2048
	ds_read_b128 v[190:193], v167 offset:3072
	s_add_u32 s44, s40, 0xfffc0080
	s_addc_u32 s45, s41, -1
	s_cmp_eq_u32 s70, 12
	s_cselect_b32 s49, s21, s45
	s_cselect_b32 s48, s37, s44
	s_cselect_b32 s45, s23, s69
	s_cselect_b32 s44, s67, s68
	v_lshl_add_u64 v[150:151], s[40:41], 0, v[136:137]
	s_add_i32 m0, s51, 0xc000
	ds_read_b128 v[196:199], v168
	ds_read_b128 v[200:203], v168 offset:1024
	ds_read_b128 v[204:207], v168 offset:2048
	ds_read_b128 v[208:211], v168 offset:3072
	ds_read_b128 v[212:215], v168 offset:4096
	ds_read_b128 v[216:219], v168 offset:5120
	ds_read_b128 v[220:223], v168 offset:6144
	ds_read_b128 v[224:227], v168 offset:7168
	global_load_lds_dwordx4 v[150:151], off
	v_lshl_add_u64 v[150:151], s[40:41], 0, v[138:139]
	s_add_i32 m0, s51, 0xe000
	s_nop 0
	global_load_lds_dwordx4 v[150:151], off
	s_waitcnt vmcnt(8)
	s_waitcnt lgkmcnt(0)
	s_barrier
	s_waitcnt lgkmcnt(0)
	v_mfma_f32_16x16x32_bf16 v[124:127], v[146:149], v[196:199], v[124:127]
	v_mfma_f32_16x16x32_bf16 v[120:123], v[170:173], v[196:199], v[120:123]
	v_mfma_f32_16x16x32_bf16 v[108:111], v[146:149], v[204:207], v[108:111]
	v_mfma_f32_16x16x32_bf16 v[104:107], v[170:173], v[204:207], v[104:107]
	v_mfma_f32_16x16x32_bf16 v[92:95], v[146:149], v[212:215], v[92:95]
	v_mfma_f32_16x16x32_bf16 v[88:91], v[170:173], v[212:215], v[88:91]
	v_mfma_f32_16x16x32_bf16 v[76:79], v[146:149], v[220:223], v[76:79]
	v_mfma_f32_16x16x32_bf16 v[72:75], v[170:173], v[220:223], v[72:75]
	v_mfma_f32_16x16x32_bf16 v[124:127], v[162:165], v[200:203], v[124:127]
	v_mfma_f32_16x16x32_bf16 v[120:123], v[174:177], v[200:203], v[120:123]
	v_mfma_f32_16x16x32_bf16 v[108:111], v[162:165], v[208:211], v[108:111]
	v_mfma_f32_16x16x32_bf16 v[104:107], v[174:177], v[208:211], v[104:107]
	v_mfma_f32_16x16x32_bf16 v[92:95], v[162:165], v[216:219], v[92:95]
	v_mfma_f32_16x16x32_bf16 v[88:91], v[174:177], v[216:219], v[88:91]
	v_mfma_f32_16x16x32_bf16 v[76:79], v[162:165], v[224:227], v[76:79]
	v_mfma_f32_16x16x32_bf16 v[72:75], v[174:177], v[224:227], v[72:75]
	v_mfma_f32_16x16x32_bf16 v[116:119], v[178:181], v[196:199], v[116:119]
	v_mfma_f32_16x16x32_bf16 v[112:115], v[186:189], v[196:199], v[112:115]
	v_mfma_f32_16x16x32_bf16 v[100:103], v[178:181], v[204:207], v[100:103]
	v_mfma_f32_16x16x32_bf16 v[96:99], v[186:189], v[204:207], v[96:99]
	v_mfma_f32_16x16x32_bf16 v[84:87], v[178:181], v[212:215], v[84:87]
	v_mfma_f32_16x16x32_bf16 v[80:83], v[186:189], v[212:215], v[80:83]
	v_mfma_f32_16x16x32_bf16 v[68:71], v[178:181], v[220:223], v[68:71]
	v_mfma_f32_16x16x32_bf16 v[64:67], v[186:189], v[220:223], v[64:67]
	v_mfma_f32_16x16x32_bf16 v[116:119], v[182:185], v[200:203], v[116:119]
	v_mfma_f32_16x16x32_bf16 v[112:115], v[190:193], v[200:203], v[112:115]
	v_mfma_f32_16x16x32_bf16 v[100:103], v[182:185], v[208:211], v[100:103]
	v_mfma_f32_16x16x32_bf16 v[96:99], v[190:193], v[208:211], v[96:99]
	v_mfma_f32_16x16x32_bf16 v[84:87], v[182:185], v[216:219], v[84:87]
	v_mfma_f32_16x16x32_bf16 v[80:83], v[190:193], v[216:219], v[80:83]
	v_mfma_f32_16x16x32_bf16 v[68:71], v[182:185], v[224:227], v[68:71]
	v_mfma_f32_16x16x32_bf16 v[64:67], v[190:193], v[224:227], v[64:67]
	s_barrier
	s_add_i32 s71, s58, s9
	v_lshl_add_u64 v[150:151], s[44:45], 0, v[132:133]
	s_mov_b32 m0, s71
	ds_read_b128 v[196:199], v168 offset:16384
	ds_read_b128 v[200:203], v168 offset:17408
	ds_read_b128 v[204:207], v168 offset:18432
	ds_read_b128 v[208:211], v168 offset:19456
	ds_read_b128 v[212:215], v168 offset:20480
	ds_read_b128 v[216:219], v168 offset:21504
	ds_read_b128 v[220:223], v168 offset:22528
	ds_read_b128 v[224:227], v168 offset:23552
	global_load_lds_dwordx4 v[150:151], off
	s_add_i32 m0, s71, 0x2000
	s_add_u32 s76, s44, 0x40000
	v_lshl_add_u64 v[154:155], s[44:45], 0, v[128:129]
	s_addc_u32 s77, s45, 0
	s_add_i32 s71, s59, s9
	global_load_lds_dwordx4 v[154:155], off
	v_lshl_add_u64 v[158:159], s[76:77], 0, v[132:133]
	s_mov_b32 m0, s71
	v_lshl_add_u64 v[228:229], s[48:49], 0, v[130:131]
	global_load_lds_dwordx4 v[158:159], off
	v_lshl_add_u64 v[158:159], s[76:77], 0, v[128:129]
	s_add_i32 m0, s71, 0x2000
	s_nop 0
	global_load_lds_dwordx4 v[158:159], off
	v_lshl_add_u64 v[158:159], s[48:49], 0, v[134:135]
	s_mov_b32 m0, s51
	s_nop 0
	global_load_lds_dwordx4 v[158:159], off
	s_mov_b32 m0, s52
	s_nop 0
	global_load_lds_dwordx4 v[228:229], off
	s_waitcnt vmcnt(8)
	s_waitcnt lgkmcnt(0)
	s_barrier
; #define PG8_STAGE_T(bufoff, gbase, voff, AUX) do { _Pragma("unroll") for (int _i = 0; _i < 2; ++_i) \
;         __builtin_amdgcn_global_load_lds((const unsigned*)((const char*)(gbase) + (voff)[_i]), (PG8_LAS unsigned*)(lds + (bufoff) + ldsw + _i * 8192), 16, 0, AUX); } while (0)
; #define PG8_LDA(dst, b, h) do { _Pragma("unroll") for (int m = 0; m < 4; ++m) _Pragma("unroll") for (int k = 0; k < 2; ++k) dst[m][k] = *(const PG8_LAS bf16x8*)(lds + PG8_SA(b, h) + aoff + m * 2048 + k * 1024); } while (0)
; #define PG8_LDB(dst, b, h) do { _Pragma("unroll") for (int n = 0; n < 2; ++n) _Pragma("unroll") for (int k = 0; k < 2; ++k) dst[n][k] = *(const PG8_LAS bf16x8*)(lds + PG8_SB(b, h) + boff + n * 2048 + k * 1024); } while (0)
; #define PG8_MMA(ai, bj, At, Bt) do { __builtin_amdgcn_s_setprio(1); _Pragma("unroll") for (int m = 0; m < 4; ++m) _Pragma("unroll") for (int n = 0; n < 2; ++n) _Pragma("unroll") for (int k = 0; k < 2; ++k) \
;         acc[ai][bj][m][n] = __builtin_amdgcn_mfma_f32_16x16x32_bf16(Bt[n][k], At[m][k], acc[ai][bj][m][n], 0, 0, 0); __builtin_amdgcn_s_setprio(0); } while (0)
; #define PG8_WAIT_V(n) asm volatile("s_waitcnt vmcnt(" #n ")" ::: "memory")
; #define PG8_WAIT_L(n) asm volatile("s_waitcnt lgkmcnt(" #n ")" ::: "memory")
; #define PG8_BAR __builtin_amdgcn_s_barrier()
; #define PG8_SCHED __builtin_amdgcn_sched_barrier(0)
;     ...
;             if (!pe) { PG8_WAIT_V(8); } PG8_WAIT_L(0); PG8_BAR; PG8_MMA(1, 0, At, B0); PG8_MMA(1, 1, At, B1); PG8_BAR; PG8_SCHED;
;             PG8_LDB(B0, 1, 0); PG8_LDB(B1, 1, 1); PG8_SCHED; PG8_LDA(At, 1, 0); PG8_STAGE_T(PG8_SA(0, 1), a2 + hstep, voffA, AUX_A);
;             if (!pe) { PG8_WAIT_V(8); } PG8_WAIT_L(0); PG8_BAR; PG8_MMA(0, 0, At, B0); PG8_MMA(0, 1, At, B1); PG8_BAR; PG8_SCHED;
	s_waitcnt lgkmcnt(0)
	v_mfma_f32_16x16x32_bf16 v[60:63], v[146:149], v[196:199], v[60:63]
	v_mfma_f32_16x16x32_bf16 v[56:59], v[170:173], v[196:199], v[56:59]
	v_mfma_f32_16x16x32_bf16 v[44:47], v[146:149], v[204:207], v[44:47]
	v_mfma_f32_16x16x32_bf16 v[40:43], v[170:173], v[204:207], v[40:43]
	v_mfma_f32_16x16x32_bf16 v[28:31], v[146:149], v[212:215], v[28:31]
	v_mfma_f32_16x16x32_bf16 v[24:27], v[170:173], v[212:215], v[24:27]
	v_mfma_f32_16x16x32_bf16 v[12:15], v[146:149], v[220:223], v[12:15]
	v_mfma_f32_16x16x32_bf16 v[8:11], v[170:173], v[220:223], v[8:11]
	v_mfma_f32_16x16x32_bf16 v[60:63], v[162:165], v[200:203], v[60:63]
	v_mfma_f32_16x16x32_bf16 v[56:59], v[174:177], v[200:203], v[56:59]
	v_mfma_f32_16x16x32_bf16 v[44:47], v[162:165], v[208:211], v[44:47]
	v_mfma_f32_16x16x32_bf16 v[40:43], v[174:177], v[208:211], v[40:43]
	v_mfma_f32_16x16x32_bf16 v[28:31], v[162:165], v[216:219], v[28:31]
	v_mfma_f32_16x16x32_bf16 v[24:27], v[174:177], v[216:219], v[24:27]
	v_mfma_f32_16x16x32_bf16 v[12:15], v[162:165], v[224:227], v[12:15]
	v_mfma_f32_16x16x32_bf16 v[8:11], v[174:177], v[224:227], v[8:11]
	v_mfma_f32_16x16x32_bf16 v[52:55], v[178:181], v[196:199], v[52:55]
	v_mfma_f32_16x16x32_bf16 v[48:51], v[186:189], v[196:199], v[48:51]
	v_mfma_f32_16x16x32_bf16 v[36:39], v[178:181], v[204:207], v[36:39]
	v_mfma_f32_16x16x32_bf16 v[32:35], v[186:189], v[204:207], v[32:35]
	v_mfma_f32_16x16x32_bf16 v[20:23], v[178:181], v[212:215], v[20:23]
	v_mfma_f32_16x16x32_bf16 v[16:19], v[186:189], v[212:215], v[16:19]
	v_mfma_f32_16x16x32_bf16 v[4:7], v[178:181], v[220:223], v[4:7]
	v_mfma_f32_16x16x32_bf16 v[0:3], v[186:189], v[220:223], v[0:3]
	v_mfma_f32_16x16x32_bf16 v[52:55], v[182:185], v[200:203], v[52:55]
	v_mfma_f32_16x16x32_bf16 v[48:51], v[190:193], v[200:203], v[48:51]
	v_mfma_f32_16x16x32_bf16 v[36:39], v[182:185], v[208:211], v[36:39]
	v_mfma_f32_16x16x32_bf16 v[32:35], v[190:193], v[208:211], v[32:35]
	v_mfma_f32_16x16x32_bf16 v[20:23], v[182:185], v[216:219], v[20:23]
	v_mfma_f32_16x16x32_bf16 v[16:19], v[190:193], v[216:219], v[16:19]
	v_mfma_f32_16x16x32_bf16 v[4:7], v[182:185], v[224:227], v[4:7]
	v_mfma_f32_16x16x32_bf16 v[0:3], v[190:193], v[224:227], v[0:3]
	s_barrier
	s_add_i32 s71, 0, 0x18000
	v_add_u32_e32 v144, s71, v153
	s_add_i32 s76, 0, 0x1c000
	ds_read_b128 v[146:149], v144
	ds_read_b128 v[162:165], v144 offset:1024
	ds_read_b128 v[170:173], v144 offset:2048
	ds_read_b128 v[174:177], v144 offset:3072
	v_add_u32_e32 v144, s76, v153
	ds_read_b128 v[178:181], v144
	ds_read_b128 v[182:185], v144 offset:1024
	ds_read_b128 v[186:189], v144 offset:2048
	ds_read_b128 v[190:193], v144 offset:3072
	s_add_u32 s48, s48, 0x40000
	s_addc_u32 s49, s49, 0
	s_mov_b32 m0, s53
	v_lshl_add_u64 v[230:231], s[48:49], 0, v[134:135]
	ds_read_b128 v[196:199], v168 offset:32768
	ds_read_b128 v[200:203], v168 offset:33792
	ds_read_b128 v[204:207], v168 offset:34816
	ds_read_b128 v[208:211], v168 offset:35840
	ds_read_b128 v[212:215], v168 offset:36864
	ds_read_b128 v[216:219], v168 offset:37888
	ds_read_b128 v[220:223], v168 offset:38912
	ds_read_b128 v[224:227], v168 offset:39936
	global_load_lds_dwordx4 v[230:231], off
	v_lshl_add_u64 v[230:231], s[48:49], 0, v[130:131]
	s_mov_b32 m0, s54
	s_nop 0
	global_load_lds_dwordx4 v[230:231], off
	s_waitcnt vmcnt(8)
	s_waitcnt lgkmcnt(0)
	s_barrier
	s_waitcnt lgkmcnt(0)
	v_mfma_f32_16x16x32_bf16 v[124:127], v[146:149], v[196:199], v[124:127]
	v_mfma_f32_16x16x32_bf16 v[120:123], v[170:173], v[196:199], v[120:123]
	v_mfma_f32_16x16x32_bf16 v[108:111], v[146:149], v[204:207], v[108:111]
	v_mfma_f32_16x16x32_bf16 v[104:107], v[170:173], v[204:207], v[104:107]
	v_mfma_f32_16x16x32_bf16 v[92:95], v[146:149], v[212:215], v[92:95]
	v_mfma_f32_16x16x32_bf16 v[88:91], v[170:173], v[212:215], v[88:91]
	v_mfma_f32_16x16x32_bf16 v[76:79], v[146:149], v[220:223], v[76:79]
	v_mfma_f32_16x16x32_bf16 v[72:75], v[170:173], v[220:223], v[72:75]
	v_mfma_f32_16x16x32_bf16 v[124:127], v[162:165], v[200:203], v[124:127]
	v_mfma_f32_16x16x32_bf16 v[120:123], v[174:177], v[200:203], v[120:123]
	v_mfma_f32_16x16x32_bf16 v[108:111], v[162:165], v[208:211], v[108:111]
	v_mfma_f32_16x16x32_bf16 v[104:107], v[174:177], v[208:211], v[104:107]
	v_mfma_f32_16x16x32_bf16 v[92:95], v[162:165], v[216:219], v[92:95]
	v_mfma_f32_16x16x32_bf16 v[88:91], v[174:177], v[216:219], v[88:91]
	v_mfma_f32_16x16x32_bf16 v[76:79], v[162:165], v[224:227], v[76:79]
	v_mfma_f32_16x16x32_bf16 v[72:75], v[174:177], v[224:227], v[72:75]
	v_mfma_f32_16x16x32_bf16 v[116:119], v[178:181], v[196:199], v[116:119]
	v_mfma_f32_16x16x32_bf16 v[112:115], v[186:189], v[196:199], v[112:115]
	v_mfma_f32_16x16x32_bf16 v[100:103], v[178:181], v[204:207], v[100:103]
	v_mfma_f32_16x16x32_bf16 v[96:99], v[186:189], v[204:207], v[96:99]
	v_mfma_f32_16x16x32_bf16 v[84:87], v[178:181], v[212:215], v[84:87]
	v_mfma_f32_16x16x32_bf16 v[80:83], v[186:189], v[212:215], v[80:83]
	v_mfma_f32_16x16x32_bf16 v[68:71], v[178:181], v[220:223], v[68:71]
	v_mfma_f32_16x16x32_bf16 v[64:67], v[186:189], v[220:223], v[64:67]
	v_mfma_f32_16x16x32_bf16 v[116:119], v[182:185], v[200:203], v[116:119]
	v_mfma_f32_16x16x32_bf16 v[112:115], v[190:193], v[200:203], v[112:115]
	v_mfma_f32_16x16x32_bf16 v[100:103], v[182:185], v[208:211], v[100:103]
	v_mfma_f32_16x16x32_bf16 v[96:99], v[190:193], v[208:211], v[96:99]
	v_mfma_f32_16x16x32_bf16 v[84:87], v[182:185], v[216:219], v[84:87]
	v_mfma_f32_16x16x32_bf16 v[80:83], v[190:193], v[216:219], v[80:83]
	v_mfma_f32_16x16x32_bf16 v[68:71], v[182:185], v[224:227], v[68:71]
	v_mfma_f32_16x16x32_bf16 v[64:67], v[190:193], v[224:227], v[64:67]
	s_barrier
; #define PG8_STAGE_T(bufoff, gbase, voff, AUX) do { _Pragma("unroll") for (int _i = 0; _i < 2; ++_i) \
;         __builtin_amdgcn_global_load_lds((const unsigned*)((const char*)(gbase) + (voff)[_i]), (PG8_LAS unsigned*)(lds + (bufoff) + ldsw + _i * 8192), 16, 0, AUX); } while (0)
; #define PG8_LDA(dst, b, h) do { _Pragma("unroll") for (int m = 0; m < 4; ++m) _Pragma("unroll") for (int k = 0; k < 2; ++k) dst[m][k] = *(const PG8_LAS bf16x8*)(lds + PG8_SA(b, h) + aoff + m * 2048 + k * 1024); } while (0)
; #define PG8_MMA(ai, bj, At, Bt) do { __builtin_amdgcn_s_setprio(1); _Pragma("unroll") for (int m = 0; m < 4; ++m) _Pragma("unroll") for (int n = 0; n < 2; ++n) _Pragma("unroll") for (int k = 0; k < 2; ++k) \
;         acc[ai][bj][m][n] = __builtin_amdgcn_mfma_f32_16x16x32_bf16(Bt[n][k], At[m][k], acc[ai][bj][m][n], 0, 0, 0); __builtin_amdgcn_s_setprio(0); } while (0)
; #define PG8_WAIT_V(n) asm volatile("s_waitcnt vmcnt(" #n ")" ::: "memory")
; #define PG8_WAIT_L(n) asm volatile("s_waitcnt lgkmcnt(" #n ")" ::: "memory")
; #define PG8_BAR __builtin_amdgcn_s_barrier()
; #define PG8_SCHED __builtin_amdgcn_sched_barrier(0)
;     ...
;             PG8_LDA(At, 1, 1); PG8_STAGE_T(PG8_SB(1, 0), b3, voffB, AUX_B); PG8_STAGE_T(PG8_SB(1, 1), b3 + hstep, voffB, AUX_B); PG8_STAGE_T(PG8_SA(1, 0), a3, voffA, AUX_A);
;             PG8_WAIT_V(8); PG8_WAIT_L(0); PG8_BAR; PG8_MMA(1, 0, At, B0); PG8_MMA(1, 1, At, B1); PG8_BAR; PG8_SCHED;
	s_add_i32 s48, s71, s9
	v_lshl_add_u64 v[150:151], v[150:151], 0, s[14:15]
	s_mov_b32 m0, s48
	ds_read_b128 v[196:199], v168 offset:49152
	ds_read_b128 v[200:203], v168 offset:50176
	ds_read_b128 v[204:207], v168 offset:51200
	ds_read_b128 v[208:211], v168 offset:52224
	ds_read_b128 v[212:215], v168 offset:53248
	ds_read_b128 v[216:219], v168 offset:54272
	ds_read_b128 v[220:223], v168 offset:55296
	ds_read_b128 v[224:227], v168 offset:56320
	global_load_lds_dwordx4 v[150:151], off
	s_add_i32 m0, s48, 0x2000
	s_add_u32 s44, s44, 0x40080
	v_lshl_add_u64 v[150:151], v[154:155], 0, s[14:15]
	s_addc_u32 s45, s45, 0
	s_add_i32 s48, s76, s9
	global_load_lds_dwordx4 v[150:151], off
	v_lshl_add_u64 v[150:151], s[44:45], 0, v[132:133]
	s_mov_b32 m0, s48
	s_nop 0
	global_load_lds_dwordx4 v[150:151], off
	v_lshl_add_u64 v[150:151], s[44:45], 0, v[128:129]
	s_add_i32 m0, s48, 0x2000
	s_nop 0
	global_load_lds_dwordx4 v[150:151], off
	v_lshl_add_u64 v[150:151], v[158:159], 0, s[14:15]
	s_mov_b32 m0, s56
	s_nop 0
	global_load_lds_dwordx4 v[150:151], off
	v_lshl_add_u64 v[150:151], v[228:229], 0, s[14:15]
	s_mov_b32 m0, s57
	s_nop 0
	global_load_lds_dwordx4 v[150:151], off
	s_waitcnt vmcnt(8)
	s_waitcnt lgkmcnt(0)
	s_barrier
	s_waitcnt lgkmcnt(0)
	v_mfma_f32_16x16x32_bf16 v[60:63], v[146:149], v[196:199], v[60:63]
	v_mfma_f32_16x16x32_bf16 v[56:59], v[170:173], v[196:199], v[56:59]
	v_mfma_f32_16x16x32_bf16 v[44:47], v[146:149], v[204:207], v[44:47]
	v_mfma_f32_16x16x32_bf16 v[40:43], v[170:173], v[204:207], v[40:43]
	v_mfma_f32_16x16x32_bf16 v[28:31], v[146:149], v[212:215], v[28:31]
	v_mfma_f32_16x16x32_bf16 v[24:27], v[170:173], v[212:215], v[24:27]
	v_mfma_f32_16x16x32_bf16 v[12:15], v[146:149], v[220:223], v[12:15]
	v_mfma_f32_16x16x32_bf16 v[8:11], v[170:173], v[220:223], v[8:11]
	v_mfma_f32_16x16x32_bf16 v[60:63], v[162:165], v[200:203], v[60:63]
	v_mfma_f32_16x16x32_bf16 v[56:59], v[174:177], v[200:203], v[56:59]
	v_mfma_f32_16x16x32_bf16 v[44:47], v[162:165], v[208:211], v[44:47]
	v_mfma_f32_16x16x32_bf16 v[40:43], v[174:177], v[208:211], v[40:43]
	v_mfma_f32_16x16x32_bf16 v[28:31], v[162:165], v[216:219], v[28:31]
	v_mfma_f32_16x16x32_bf16 v[24:27], v[174:177], v[216:219], v[24:27]
	v_mfma_f32_16x16x32_bf16 v[12:15], v[162:165], v[224:227], v[12:15]
	v_mfma_f32_16x16x32_bf16 v[8:11], v[174:177], v[224:227], v[8:11]
	v_mfma_f32_16x16x32_bf16 v[52:55], v[178:181], v[196:199], v[52:55]
	v_mfma_f32_16x16x32_bf16 v[48:51], v[186:189], v[196:199], v[48:51]
	v_mfma_f32_16x16x32_bf16 v[36:39], v[178:181], v[204:207], v[36:39]
	v_mfma_f32_16x16x32_bf16 v[32:35], v[186:189], v[204:207], v[32:35]
	v_mfma_f32_16x16x32_bf16 v[20:23], v[178:181], v[212:215], v[20:23]
	v_mfma_f32_16x16x32_bf16 v[16:19], v[186:189], v[212:215], v[16:19]
	v_mfma_f32_16x16x32_bf16 v[4:7], v[178:181], v[220:223], v[4:7]
	v_mfma_f32_16x16x32_bf16 v[0:3], v[186:189], v[220:223], v[0:3]
	v_mfma_f32_16x16x32_bf16 v[52:55], v[182:185], v[200:203], v[52:55]
	v_mfma_f32_16x16x32_bf16 v[48:51], v[190:193], v[200:203], v[48:51]
	v_mfma_f32_16x16x32_bf16 v[36:39], v[182:185], v[208:211], v[36:39]
	v_mfma_f32_16x16x32_bf16 v[32:35], v[190:193], v[208:211], v[32:35]
	v_mfma_f32_16x16x32_bf16 v[20:23], v[182:185], v[216:219], v[20:23]
	v_mfma_f32_16x16x32_bf16 v[16:19], v[190:193], v[216:219], v[16:19]
	v_mfma_f32_16x16x32_bf16 v[4:7], v[182:185], v[224:227], v[4:7]
	v_mfma_f32_16x16x32_bf16 v[0:3], v[190:193], v[224:227], v[0:3]
	s_barrier
	s_add_i32 s70, s70, 2
	s_add_u32 s40, s40, 0x100
	s_addc_u32 s41, s41, 0
	s_add_u32 s68, s68, 0x100
	s_addc_u32 s69, s69, 0
	s_cmp_gt_u32 s70, 13
	s_cbranch_scc0 .LBB0_244
	s_and_b64 vcc, exec, s[18:19]
	s_cbranch_vccz .LBB0_247
	s_barrier

; #define PG8_STAGE_T(bufoff, gbase, voff, AUX) do { _Pragma("unroll") for (int _i = 0; _i < 2; ++_i) \
;         __builtin_amdgcn_global_load_lds((const unsigned*)((const char*)(gbase) + (voff)[_i]), (PG8_LAS unsigned*)(lds + (bufoff) + ldsw + _i * 8192), 16, 0, AUX); } while (0)
; #define PG8_LDA(dst, b, h) do { _Pragma("unroll") for (int m = 0; m < 4; ++m) _Pragma("unroll") for (int k = 0; k < 2; ++k) dst[m][k] = *(const PG8_LAS bf16x8*)(lds + PG8_SA(b, h) + aoff + m * 2048 + k * 1024); } while (0)
; #define PG8_LDB(dst, b, h) do { _Pragma("unroll") for (int n = 0; n < 2; ++n) _Pragma("unroll") for (int k = 0; k < 2; ++k) dst[n][k] = *(const PG8_LAS bf16x8*)(lds + PG8_SB(b, h) + boff + n * 2048 + k * 1024); } while (0)
; #define PG8_MMA(ai, bj, At, Bt) do { __builtin_amdgcn_s_setprio(1); _Pragma("unroll") for (int m = 0; m < 4; ++m) _Pragma("unroll") for (int n = 0; n < 2; ++n) _Pragma("unroll") for (int k = 0; k < 2; ++k) \
;         acc[ai][bj][m][n] = __builtin_amdgcn_mfma_f32_16x16x32_bf16(Bt[n][k], At[m][k], acc[ai][bj][m][n], 0, 0, 0); __builtin_amdgcn_s_setprio(0); } while (0)
; #define PG8_WAIT_V(n) asm volatile("s_waitcnt vmcnt(" #n ")" ::: "memory")
; #define PG8_WAIT_L(n) asm volatile("s_waitcnt lgkmcnt(" #n ")" ::: "memory")
; #define PG8_BAR __builtin_amdgcn_s_barrier()
; #define PG8_SCHED __builtin_amdgcn_sched_barrier(0)
;     ...
;             PG8_LDB(B0, 0, 0); PG8_LDB(B1, 0, 1); PG8_SCHED; PG8_LDA(At, 0, 0); if (!pe) { PG8_STAGE_T(PG8_SA(1, 1), a1 + hstep, voffA, AUX_A); }
;             if (!pe) { PG8_WAIT_V(8); } PG8_WAIT_L(0); PG8_BAR; PG8_MMA(0, 0, At, B0); PG8_MMA(0, 1, At, B1); PG8_BAR; PG8_SCHED;
;             PG8_LDA(At, 0, 1); PG8_STAGE_T(PG8_SB(0, 0), b2, voffB, AUX_B); PG8_STAGE_T(PG8_SB(0, 1), b2 + hstep, voffB, AUX_B); PG8_STAGE_T(PG8_SA(0, 0), a2, voffA, AUX_A);
;             if (!pe) { PG8_WAIT_V(8); } PG8_WAIT_L(0); PG8_BAR; PG8_MMA(1, 0, At, B0); PG8_MMA(1, 1, At, B1); PG8_BAR; PG8_SCHED;
.LBB0_329:
	ds_read_b128 v[154:157], v149
	ds_read_b128 v[158:161], v149 offset:1024
	ds_read_b128 v[162:165], v149 offset:2048
	ds_read_b128 v[166:169], v149 offset:3072
	ds_read_b128 v[170:173], v150
	ds_read_b128 v[174:177], v150 offset:1024
	ds_read_b128 v[178:181], v150 offset:2048
	ds_read_b128 v[182:185], v150 offset:3072
	s_add_u32 s44, s40, 0xfff50080
	s_addc_u32 s45, s41, -1
	s_cmp_eq_u32 s67, 40
	s_cselect_b32 s49, s5, s45
	s_cselect_b32 s48, s4, s44
	s_cselect_b32 s45, s37, s66
	s_cselect_b32 s44, s36, s63
	v_lshl_add_u64 v[144:145], s[40:41], 0, v[136:137]
	s_add_i32 m0, s9, 0xc000
	ds_read_b128 v[186:189], v151
	ds_read_b128 v[190:193], v151 offset:1024
	ds_read_b128 v[196:199], v151 offset:2048
	ds_read_b128 v[200:203], v151 offset:3072
	ds_read_b128 v[204:207], v151 offset:4096
	ds_read_b128 v[208:211], v151 offset:5120
	ds_read_b128 v[212:215], v151 offset:6144
	ds_read_b128 v[216:219], v151 offset:7168
	global_load_lds_dwordx4 v[144:145], off
	v_lshl_add_u64 v[144:145], s[40:41], 0, v[138:139]
	s_add_i32 m0, s9, 0xe000
	s_nop 0
	global_load_lds_dwordx4 v[144:145], off
	s_waitcnt vmcnt(8)
	s_waitcnt lgkmcnt(0)
	s_barrier
	s_waitcnt lgkmcnt(0)
	v_mfma_f32_16x16x32_bf16 v[124:127], v[154:157], v[186:189], v[124:127]
	v_mfma_f32_16x16x32_bf16 v[120:123], v[162:165], v[186:189], v[120:123]
	v_mfma_f32_16x16x32_bf16 v[108:111], v[154:157], v[196:199], v[108:111]
	v_mfma_f32_16x16x32_bf16 v[104:107], v[162:165], v[196:199], v[104:107]
	v_mfma_f32_16x16x32_bf16 v[92:95], v[154:157], v[204:207], v[92:95]
	v_mfma_f32_16x16x32_bf16 v[88:91], v[162:165], v[204:207], v[88:91]
	v_mfma_f32_16x16x32_bf16 v[76:79], v[154:157], v[212:215], v[76:79]
	v_mfma_f32_16x16x32_bf16 v[72:75], v[162:165], v[212:215], v[72:75]
	v_mfma_f32_16x16x32_bf16 v[124:127], v[158:161], v[190:193], v[124:127]
	v_mfma_f32_16x16x32_bf16 v[120:123], v[166:169], v[190:193], v[120:123]
	v_mfma_f32_16x16x32_bf16 v[108:111], v[158:161], v[200:203], v[108:111]
	v_mfma_f32_16x16x32_bf16 v[104:107], v[166:169], v[200:203], v[104:107]
	v_mfma_f32_16x16x32_bf16 v[92:95], v[158:161], v[208:211], v[92:95]
	v_mfma_f32_16x16x32_bf16 v[88:91], v[166:169], v[208:211], v[88:91]
	v_mfma_f32_16x16x32_bf16 v[76:79], v[158:161], v[216:219], v[76:79]
	v_mfma_f32_16x16x32_bf16 v[72:75], v[166:169], v[216:219], v[72:75]
	v_mfma_f32_16x16x32_bf16 v[116:119], v[170:173], v[186:189], v[116:119]
	v_mfma_f32_16x16x32_bf16 v[112:115], v[178:181], v[186:189], v[112:115]
	v_mfma_f32_16x16x32_bf16 v[100:103], v[170:173], v[196:199], v[100:103]
	v_mfma_f32_16x16x32_bf16 v[96:99], v[178:181], v[196:199], v[96:99]
	v_mfma_f32_16x16x32_bf16 v[84:87], v[170:173], v[204:207], v[84:87]
	v_mfma_f32_16x16x32_bf16 v[80:83], v[178:181], v[204:207], v[80:83]
	v_mfma_f32_16x16x32_bf16 v[68:71], v[170:173], v[212:215], v[68:71]
	v_mfma_f32_16x16x32_bf16 v[64:67], v[178:181], v[212:215], v[64:67]
	v_mfma_f32_16x16x32_bf16 v[116:119], v[174:177], v[190:193], v[116:119]
	v_mfma_f32_16x16x32_bf16 v[112:115], v[182:185], v[190:193], v[112:115]
	v_mfma_f32_16x16x32_bf16 v[100:103], v[174:177], v[200:203], v[100:103]
	v_mfma_f32_16x16x32_bf16 v[96:99], v[182:185], v[200:203], v[96:99]
	v_mfma_f32_16x16x32_bf16 v[84:87], v[174:177], v[208:211], v[84:87]
	v_mfma_f32_16x16x32_bf16 v[80:83], v[182:185], v[208:211], v[80:83]
	v_mfma_f32_16x16x32_bf16 v[68:71], v[174:177], v[216:219], v[68:71]
	v_mfma_f32_16x16x32_bf16 v[64:67], v[182:185], v[216:219], v[64:67]
	s_barrier
	s_add_i32 s68, s56, s8
	v_lshl_add_u64 v[144:145], s[44:45], 0, v[130:131]
	s_mov_b32 m0, s68
	ds_read_b128 v[186:189], v151 offset:16384
	ds_read_b128 v[190:193], v151 offset:17408
	ds_read_b128 v[196:199], v151 offset:18432
	ds_read_b128 v[200:203], v151 offset:19456
	ds_read_b128 v[204:207], v151 offset:20480
	ds_read_b128 v[208:211], v151 offset:21504
	ds_read_b128 v[212:215], v151 offset:22528
	ds_read_b128 v[216:219], v151 offset:23552
	global_load_lds_dwordx4 v[144:145], off
	s_add_i32 m0, s68, 0x2000
	s_add_u32 s68, s44, 0xb0000
	v_lshl_add_u64 v[220:221], s[44:45], 0, v[134:135]
	s_addc_u32 s69, s45, 0
	s_add_i32 s70, s57, s8
	global_load_lds_dwordx4 v[220:221], off
	v_lshl_add_u64 v[222:223], s[68:69], 0, v[130:131]
	s_mov_b32 m0, s70
	v_lshl_add_u64 v[224:225], s[48:49], 0, v[132:133]
	global_load_lds_dwordx4 v[222:223], off
	v_lshl_add_u64 v[222:223], s[68:69], 0, v[134:135]
	s_add_i32 m0, s70, 0x2000
	s_nop 0
	global_load_lds_dwordx4 v[222:223], off
	v_lshl_add_u64 v[222:223], s[48:49], 0, v[128:129]
	s_mov_b32 m0, s9
	s_nop 0
	global_load_lds_dwordx4 v[222:223], off
	s_mov_b32 m0, s50
	s_nop 0
	global_load_lds_dwordx4 v[224:225], off
	s_waitcnt vmcnt(8)
	s_waitcnt lgkmcnt(0)
	s_barrier
; #define PG8_STAGE_T(bufoff, gbase, voff, AUX) do { _Pragma("unroll") for (int _i = 0; _i < 2; ++_i) \
;         __builtin_amdgcn_global_load_lds((const unsigned*)((const char*)(gbase) + (voff)[_i]), (PG8_LAS unsigned*)(lds + (bufoff) + ldsw + _i * 8192), 16, 0, AUX); } while (0)
; #define PG8_LDA(dst, b, h) do { _Pragma("unroll") for (int m = 0; m < 4; ++m) _Pragma("unroll") for (int k = 0; k < 2; ++k) dst[m][k] = *(const PG8_LAS bf16x8*)(lds + PG8_SA(b, h) + aoff + m * 2048 + k * 1024); } while (0)
; #define PG8_LDB(dst, b, h) do { _Pragma("unroll") for (int n = 0; n < 2; ++n) _Pragma("unroll") for (int k = 0; k < 2; ++k) dst[n][k] = *(const PG8_LAS bf16x8*)(lds + PG8_SB(b, h) + boff + n * 2048 + k * 1024); } while (0)
; #define PG8_MMA(ai, bj, At, Bt) do { __builtin_amdgcn_s_setprio(1); _Pragma("unroll") for (int m = 0; m < 4; ++m) _Pragma("unroll") for (int n = 0; n < 2; ++n) _Pragma("unroll") for (int k = 0; k < 2; ++k) \
;         acc[ai][bj][m][n] = __builtin_amdgcn_mfma_f32_16x16x32_bf16(Bt[n][k], At[m][k], acc[ai][bj][m][n], 0, 0, 0); __builtin_amdgcn_s_setprio(0); } while (0)
; #define PG8_WAIT_V(n) asm volatile("s_waitcnt vmcnt(" #n ")" ::: "memory")
; #define PG8_WAIT_L(n) asm volatile("s_waitcnt lgkmcnt(" #n ")" ::: "memory")
; #define PG8_BAR __builtin_amdgcn_s_barrier()
; #define PG8_SCHED __builtin_amdgcn_sched_barrier(0)
;     ...
;             if (!pe) { PG8_WAIT_V(8); } PG8_WAIT_L(0); PG8_BAR; PG8_MMA(1, 0, At, B0); PG8_MMA(1, 1, At, B1); PG8_BAR; PG8_SCHED;
;             PG8_LDB(B0, 1, 0); PG8_LDB(B1, 1, 1); PG8_SCHED; PG8_LDA(At, 1, 0); PG8_STAGE_T(PG8_SA(0, 1), a2 + hstep, voffA, AUX_A);
;             if (!pe) { PG8_WAIT_V(8); } PG8_WAIT_L(0); PG8_BAR; PG8_MMA(0, 0, At, B0); PG8_MMA(0, 1, At, B1); PG8_BAR; PG8_SCHED;
	s_waitcnt lgkmcnt(0)
	v_mfma_f32_16x16x32_bf16 v[60:63], v[154:157], v[186:189], v[60:63]
	v_mfma_f32_16x16x32_bf16 v[56:59], v[162:165], v[186:189], v[56:59]
	v_mfma_f32_16x16x32_bf16 v[44:47], v[154:157], v[196:199], v[44:47]
	v_mfma_f32_16x16x32_bf16 v[40:43], v[162:165], v[196:199], v[40:43]
	v_mfma_f32_16x16x32_bf16 v[28:31], v[154:157], v[204:207], v[28:31]
	v_mfma_f32_16x16x32_bf16 v[24:27], v[162:165], v[204:207], v[24:27]
	v_mfma_f32_16x16x32_bf16 v[12:15], v[154:157], v[212:215], v[12:15]
	v_mfma_f32_16x16x32_bf16 v[8:11], v[162:165], v[212:215], v[8:11]
	v_mfma_f32_16x16x32_bf16 v[60:63], v[158:161], v[190:193], v[60:63]
	v_mfma_f32_16x16x32_bf16 v[56:59], v[166:169], v[190:193], v[56:59]
	v_mfma_f32_16x16x32_bf16 v[44:47], v[158:161], v[200:203], v[44:47]
	v_mfma_f32_16x16x32_bf16 v[40:43], v[166:169], v[200:203], v[40:43]
	v_mfma_f32_16x16x32_bf16 v[28:31], v[158:161], v[208:211], v[28:31]
	v_mfma_f32_16x16x32_bf16 v[24:27], v[166:169], v[208:211], v[24:27]
	v_mfma_f32_16x16x32_bf16 v[12:15], v[158:161], v[216:219], v[12:15]
	v_mfma_f32_16x16x32_bf16 v[8:11], v[166:169], v[216:219], v[8:11]
	v_mfma_f32_16x16x32_bf16 v[52:55], v[170:173], v[186:189], v[52:55]
	v_mfma_f32_16x16x32_bf16 v[48:51], v[178:181], v[186:189], v[48:51]
	v_mfma_f32_16x16x32_bf16 v[36:39], v[170:173], v[196:199], v[36:39]
	v_mfma_f32_16x16x32_bf16 v[32:35], v[178:181], v[196:199], v[32:35]
	v_mfma_f32_16x16x32_bf16 v[20:23], v[170:173], v[204:207], v[20:23]
	v_mfma_f32_16x16x32_bf16 v[16:19], v[178:181], v[204:207], v[16:19]
	v_mfma_f32_16x16x32_bf16 v[4:7], v[170:173], v[212:215], v[4:7]
	v_mfma_f32_16x16x32_bf16 v[0:3], v[178:181], v[212:215], v[0:3]
	v_mfma_f32_16x16x32_bf16 v[52:55], v[174:177], v[190:193], v[52:55]
	v_mfma_f32_16x16x32_bf16 v[48:51], v[182:185], v[190:193], v[48:51]
	v_mfma_f32_16x16x32_bf16 v[36:39], v[174:177], v[200:203], v[36:39]
	v_mfma_f32_16x16x32_bf16 v[32:35], v[182:185], v[200:203], v[32:35]
	v_mfma_f32_16x16x32_bf16 v[20:23], v[174:177], v[208:211], v[20:23]
	v_mfma_f32_16x16x32_bf16 v[16:19], v[182:185], v[208:211], v[16:19]
	v_mfma_f32_16x16x32_bf16 v[4:7], v[174:177], v[216:219], v[4:7]
	v_mfma_f32_16x16x32_bf16 v[0:3], v[182:185], v[216:219], v[0:3]
	s_barrier
	s_add_i32 s68, 0, 0x18000
	v_add_u32_e32 v153, s68, v147
	s_add_i32 s69, 0, 0x1c000
	ds_read_b128 v[154:157], v153
	ds_read_b128 v[158:161], v153 offset:1024
	ds_read_b128 v[162:165], v153 offset:2048
	ds_read_b128 v[166:169], v153 offset:3072
	v_add_u32_e32 v153, s69, v147
	ds_read_b128 v[170:173], v153
	ds_read_b128 v[174:177], v153 offset:1024
	ds_read_b128 v[178:181], v153 offset:2048
	ds_read_b128 v[182:185], v153 offset:3072
	s_add_u32 s48, s48, 0xb0000
	s_addc_u32 s49, s49, 0
	s_mov_b32 m0, s51
	v_lshl_add_u64 v[226:227], s[48:49], 0, v[128:129]
	ds_read_b128 v[186:189], v151 offset:32768
	ds_read_b128 v[190:193], v151 offset:33792
	ds_read_b128 v[196:199], v151 offset:34816
	ds_read_b128 v[200:203], v151 offset:35840
	ds_read_b128 v[204:207], v151 offset:36864
	ds_read_b128 v[208:211], v151 offset:37888
	ds_read_b128 v[212:215], v151 offset:38912
	ds_read_b128 v[216:219], v151 offset:39936
	global_load_lds_dwordx4 v[226:227], off
	v_lshl_add_u64 v[226:227], s[48:49], 0, v[132:133]
	s_mov_b32 m0, s52
	s_nop 0
	global_load_lds_dwordx4 v[226:227], off
	s_waitcnt vmcnt(8)
	s_waitcnt lgkmcnt(0)
	s_barrier
	s_waitcnt lgkmcnt(0)
	v_mfma_f32_16x16x32_bf16 v[124:127], v[154:157], v[186:189], v[124:127]
	v_mfma_f32_16x16x32_bf16 v[120:123], v[162:165], v[186:189], v[120:123]
	v_mfma_f32_16x16x32_bf16 v[108:111], v[154:157], v[196:199], v[108:111]
	v_mfma_f32_16x16x32_bf16 v[104:107], v[162:165], v[196:199], v[104:107]
	v_mfma_f32_16x16x32_bf16 v[92:95], v[154:157], v[204:207], v[92:95]
	v_mfma_f32_16x16x32_bf16 v[88:91], v[162:165], v[204:207], v[88:91]
	v_mfma_f32_16x16x32_bf16 v[76:79], v[154:157], v[212:215], v[76:79]
	v_mfma_f32_16x16x32_bf16 v[72:75], v[162:165], v[212:215], v[72:75]
	v_mfma_f32_16x16x32_bf16 v[124:127], v[158:161], v[190:193], v[124:127]
	v_mfma_f32_16x16x32_bf16 v[120:123], v[166:169], v[190:193], v[120:123]
	v_mfma_f32_16x16x32_bf16 v[108:111], v[158:161], v[200:203], v[108:111]
	v_mfma_f32_16x16x32_bf16 v[104:107], v[166:169], v[200:203], v[104:107]
	v_mfma_f32_16x16x32_bf16 v[92:95], v[158:161], v[208:211], v[92:95]
	v_mfma_f32_16x16x32_bf16 v[88:91], v[166:169], v[208:211], v[88:91]
	v_mfma_f32_16x16x32_bf16 v[76:79], v[158:161], v[216:219], v[76:79]
	v_mfma_f32_16x16x32_bf16 v[72:75], v[166:169], v[216:219], v[72:75]
	v_mfma_f32_16x16x32_bf16 v[116:119], v[170:173], v[186:189], v[116:119]
	v_mfma_f32_16x16x32_bf16 v[112:115], v[178:181], v[186:189], v[112:115]
	v_mfma_f32_16x16x32_bf16 v[100:103], v[170:173], v[196:199], v[100:103]
	v_mfma_f32_16x16x32_bf16 v[96:99], v[178:181], v[196:199], v[96:99]
	v_mfma_f32_16x16x32_bf16 v[84:87], v[170:173], v[204:207], v[84:87]
	v_mfma_f32_16x16x32_bf16 v[80:83], v[178:181], v[204:207], v[80:83]
	v_mfma_f32_16x16x32_bf16 v[68:71], v[170:173], v[212:215], v[68:71]
	v_mfma_f32_16x16x32_bf16 v[64:67], v[178:181], v[212:215], v[64:67]
	v_mfma_f32_16x16x32_bf16 v[116:119], v[174:177], v[190:193], v[116:119]
	v_mfma_f32_16x16x32_bf16 v[112:115], v[182:185], v[190:193], v[112:115]
	v_mfma_f32_16x16x32_bf16 v[100:103], v[174:177], v[200:203], v[100:103]
	v_mfma_f32_16x16x32_bf16 v[96:99], v[182:185], v[200:203], v[96:99]
	v_mfma_f32_16x16x32_bf16 v[84:87], v[174:177], v[208:211], v[84:87]
	v_mfma_f32_16x16x32_bf16 v[80:83], v[182:185], v[208:211], v[80:83]
	v_mfma_f32_16x16x32_bf16 v[68:71], v[174:177], v[216:219], v[68:71]
	v_mfma_f32_16x16x32_bf16 v[64:67], v[182:185], v[216:219], v[64:67]
	s_barrier
; #define PG8_STAGE_T(bufoff, gbase, voff, AUX) do { _Pragma("unroll") for (int _i = 0; _i < 2; ++_i) \
;         __builtin_amdgcn_global_load_lds((const unsigned*)((const char*)(gbase) + (voff)[_i]), (PG8_LAS unsigned*)(lds + (bufoff) + ldsw + _i * 8192), 16, 0, AUX); } while (0)
; #define PG8_LDA(dst, b, h) do { _Pragma("unroll") for (int m = 0; m < 4; ++m) _Pragma("unroll") for (int k = 0; k < 2; ++k) dst[m][k] = *(const PG8_LAS bf16x8*)(lds + PG8_SA(b, h) + aoff + m * 2048 + k * 1024); } while (0)
; #define PG8_MMA(ai, bj, At, Bt) do { __builtin_amdgcn_s_setprio(1); _Pragma("unroll") for (int m = 0; m < 4; ++m) _Pragma("unroll") for (int n = 0; n < 2; ++n) _Pragma("unroll") for (int k = 0; k < 2; ++k) \
;         acc[ai][bj][m][n] = __builtin_amdgcn_mfma_f32_16x16x32_bf16(Bt[n][k], At[m][k], acc[ai][bj][m][n], 0, 0, 0); __builtin_amdgcn_s_setprio(0); } while (0)
; #define PG8_WAIT_V(n) asm volatile("s_waitcnt vmcnt(" #n ")" ::: "memory")
; #define PG8_WAIT_L(n) asm volatile("s_waitcnt lgkmcnt(" #n ")" ::: "memory")
; #define PG8_BAR __builtin_amdgcn_s_barrier()
; #define PG8_SCHED __builtin_amdgcn_sched_barrier(0)
;     ...
;             PG8_LDA(At, 1, 1); PG8_STAGE_T(PG8_SB(1, 0), b3, voffB, AUX_B); PG8_STAGE_T(PG8_SB(1, 1), b3 + hstep, voffB, AUX_B); PG8_STAGE_T(PG8_SA(1, 0), a3, voffA, AUX_A);
;             PG8_WAIT_V(8); PG8_WAIT_L(0); PG8_BAR; PG8_MMA(1, 0, At, B0); PG8_MMA(1, 1, At, B1); PG8_BAR; PG8_SCHED;
	s_add_i32 s48, s68, s8
	v_lshl_add_u64 v[144:145], v[144:145], 0, s[24:25]
	s_mov_b32 m0, s48
	ds_read_b128 v[186:189], v151 offset:49152
	ds_read_b128 v[190:193], v151 offset:50176
	ds_read_b128 v[196:199], v151 offset:51200
	ds_read_b128 v[200:203], v151 offset:52224
	ds_read_b128 v[204:207], v151 offset:53248
	ds_read_b128 v[208:211], v151 offset:54272
	ds_read_b128 v[212:215], v151 offset:55296
	ds_read_b128 v[216:219], v151 offset:56320
	global_load_lds_dwordx4 v[144:145], off
	s_add_i32 m0, s48, 0x2000
	s_add_u32 s44, s44, 0xb0080
	v_lshl_add_u64 v[144:145], v[220:221], 0, s[24:25]
	s_addc_u32 s45, s45, 0
	s_add_i32 s48, s69, s8
	global_load_lds_dwordx4 v[144:145], off
	v_lshl_add_u64 v[144:145], s[44:45], 0, v[130:131]
	s_mov_b32 m0, s48
	s_nop 0
	global_load_lds_dwordx4 v[144:145], off
	v_lshl_add_u64 v[144:145], s[44:45], 0, v[134:135]
	s_add_i32 m0, s48, 0x2000
	s_nop 0
	global_load_lds_dwordx4 v[144:145], off
	v_lshl_add_u64 v[144:145], v[222:223], 0, s[24:25]
	s_mov_b32 m0, s53
	s_nop 0
	global_load_lds_dwordx4 v[144:145], off
	v_lshl_add_u64 v[144:145], v[224:225], 0, s[24:25]
	s_mov_b32 m0, s54
	s_nop 0
	global_load_lds_dwordx4 v[144:145], off
	s_waitcnt vmcnt(8)
	s_waitcnt lgkmcnt(0)
	s_barrier
	s_waitcnt lgkmcnt(0)
	v_mfma_f32_16x16x32_bf16 v[60:63], v[154:157], v[186:189], v[60:63]
	v_mfma_f32_16x16x32_bf16 v[56:59], v[162:165], v[186:189], v[56:59]
	v_mfma_f32_16x16x32_bf16 v[44:47], v[154:157], v[196:199], v[44:47]
	v_mfma_f32_16x16x32_bf16 v[40:43], v[162:165], v[196:199], v[40:43]
	v_mfma_f32_16x16x32_bf16 v[28:31], v[154:157], v[204:207], v[28:31]
	v_mfma_f32_16x16x32_bf16 v[24:27], v[162:165], v[204:207], v[24:27]
	v_mfma_f32_16x16x32_bf16 v[12:15], v[154:157], v[212:215], v[12:15]
	v_mfma_f32_16x16x32_bf16 v[8:11], v[162:165], v[212:215], v[8:11]
	v_mfma_f32_16x16x32_bf16 v[60:63], v[158:161], v[190:193], v[60:63]
	v_mfma_f32_16x16x32_bf16 v[56:59], v[166:169], v[190:193], v[56:59]
	v_mfma_f32_16x16x32_bf16 v[44:47], v[158:161], v[200:203], v[44:47]
	v_mfma_f32_16x16x32_bf16 v[40:43], v[166:169], v[200:203], v[40:43]
	v_mfma_f32_16x16x32_bf16 v[28:31], v[158:161], v[208:211], v[28:31]
	v_mfma_f32_16x16x32_bf16 v[24:27], v[166:169], v[208:211], v[24:27]
	v_mfma_f32_16x16x32_bf16 v[12:15], v[158:161], v[216:219], v[12:15]
	v_mfma_f32_16x16x32_bf16 v[8:11], v[166:169], v[216:219], v[8:11]
	v_mfma_f32_16x16x32_bf16 v[52:55], v[170:173], v[186:189], v[52:55]
	v_mfma_f32_16x16x32_bf16 v[48:51], v[178:181], v[186:189], v[48:51]
	v_mfma_f32_16x16x32_bf16 v[36:39], v[170:173], v[196:199], v[36:39]
	v_mfma_f32_16x16x32_bf16 v[32:35], v[178:181], v[196:199], v[32:35]
	v_mfma_f32_16x16x32_bf16 v[20:23], v[170:173], v[204:207], v[20:23]
	v_mfma_f32_16x16x32_bf16 v[16:19], v[178:181], v[204:207], v[16:19]
	v_mfma_f32_16x16x32_bf16 v[4:7], v[170:173], v[212:215], v[4:7]
	v_mfma_f32_16x16x32_bf16 v[0:3], v[178:181], v[212:215], v[0:3]
	v_mfma_f32_16x16x32_bf16 v[52:55], v[174:177], v[190:193], v[52:55]
	v_mfma_f32_16x16x32_bf16 v[48:51], v[182:185], v[190:193], v[48:51]
	v_mfma_f32_16x16x32_bf16 v[36:39], v[174:177], v[200:203], v[36:39]
	v_mfma_f32_16x16x32_bf16 v[32:35], v[182:185], v[200:203], v[32:35]
	v_mfma_f32_16x16x32_bf16 v[20:23], v[174:177], v[208:211], v[20:23]
	v_mfma_f32_16x16x32_bf16 v[16:19], v[182:185], v[208:211], v[16:19]
	v_mfma_f32_16x16x32_bf16 v[4:7], v[174:177], v[216:219], v[4:7]
	v_mfma_f32_16x16x32_bf16 v[0:3], v[182:185], v[216:219], v[0:3]
	s_barrier
	s_add_i32 s67, s67, 2
	s_add_u32 s40, s40, 0x100
	s_addc_u32 s41, s41, 0
	s_add_u32 s63, s63, 0x100
	s_addc_u32 s66, s66, 0
	s_cmp_gt_u32 s67, 41
	s_cbranch_scc0 .LBB0_329
	s_and_b64 vcc, exec, s[26:27]
	s_cbranch_vccz .LBB0_332
	s_barrier

; #define PG8_STAGE_T(bufoff, gbase, voff, AUX) do { _Pragma("unroll") for (int _i = 0; _i < 2; ++_i) \
;         __builtin_amdgcn_global_load_lds((const unsigned*)((const char*)(gbase) + (voff)[_i]), (PG8_LAS unsigned*)(lds + (bufoff) + ldsw + _i * 8192), 16, 0, AUX); } while (0)
; #define PG8_LDA(dst, b, h) do { _Pragma("unroll") for (int m = 0; m < 4; ++m) _Pragma("unroll") for (int k = 0; k < 2; ++k) dst[m][k] = *(const PG8_LAS bf16x8*)(lds + PG8_SA(b, h) + aoff + m * 2048 + k * 1024); } while (0)
; #define PG8_LDB(dst, b, h) do { _Pragma("unroll") for (int n = 0; n < 2; ++n) _Pragma("unroll") for (int k = 0; k < 2; ++k) dst[n][k] = *(const PG8_LAS bf16x8*)(lds + PG8_SB(b, h) + boff + n * 2048 + k * 1024); } while (0)
; #define PG8_MMA(ai, bj, At, Bt) do { __builtin_amdgcn_s_setprio(1); _Pragma("unroll") for (int m = 0; m < 4; ++m) _Pragma("unroll") for (int n = 0; n < 2; ++n) _Pragma("unroll") for (int k = 0; k < 2; ++k) \
;         acc[ai][bj][m][n] = __builtin_amdgcn_mfma_f32_16x16x32_bf16(Bt[n][k], At[m][k], acc[ai][bj][m][n], 0, 0, 0); __builtin_amdgcn_s_setprio(0); } while (0)
; #define PG8_WAIT_V(n) asm volatile("s_waitcnt vmcnt(" #n ")" ::: "memory")
; #define PG8_WAIT_L(n) asm volatile("s_waitcnt lgkmcnt(" #n ")" ::: "memory")
; #define PG8_BAR __builtin_amdgcn_s_barrier()
; #define PG8_SCHED __builtin_amdgcn_sched_barrier(0)
;     ...
;             PG8_LDB(B0, 0, 0); PG8_LDB(B1, 0, 1); PG8_SCHED; PG8_LDA(At, 0, 0); if (!pe) { PG8_STAGE_T(PG8_SA(1, 1), a1 + hstep, voffA, AUX_A); }
;             if (!pe) { PG8_WAIT_V(8); } PG8_WAIT_L(0); PG8_BAR; PG8_MMA(0, 0, At, B0); PG8_MMA(0, 1, At, B1); PG8_BAR; PG8_SCHED;
;             PG8_LDA(At, 0, 1); PG8_STAGE_T(PG8_SB(0, 0), b2, voffB, AUX_B); PG8_STAGE_T(PG8_SB(0, 1), b2 + hstep, voffB, AUX_B); PG8_STAGE_T(PG8_SA(0, 0), a2, voffA, AUX_A);
;             if (!pe) { PG8_WAIT_V(8); } PG8_WAIT_L(0); PG8_BAR; PG8_MMA(1, 0, At, B0); PG8_MMA(1, 1, At, B1); PG8_BAR; PG8_SCHED;
.LBB0_516:
	ds_read_b128 v[146:149], v178
	ds_read_b128 v[150:153], v178 offset:1024
	ds_read_b128 v[154:157], v178 offset:2048
	ds_read_b128 v[158:161], v178 offset:3072
	ds_read_b128 v[162:165], v179
	ds_read_b128 v[166:169], v179 offset:1024
	ds_read_b128 v[170:173], v179 offset:2048
	ds_read_b128 v[182:185], v179 offset:3072
	s_add_u32 s50, s48, 0xfffc0080
	s_addc_u32 s51, s49, -1
	s_cmp_eq_u32 s68, 12
	s_cselect_b32 s53, s5, s51
	s_cselect_b32 s52, s7, s50
	s_cselect_b32 s51, s27, s67
	s_cselect_b32 s50, s37, s66
	v_lshl_add_u64 v[220:221], s[48:49], 0, v[138:139]
	s_add_i32 m0, s9, 0xc000
	ds_read_b128 v[186:189], v180
	ds_read_b128 v[190:193], v180 offset:1024
	ds_read_b128 v[196:199], v180 offset:2048
	ds_read_b128 v[200:203], v180 offset:3072
	ds_read_b128 v[204:207], v180 offset:4096
	ds_read_b128 v[208:211], v180 offset:5120
	ds_read_b128 v[212:215], v180 offset:6144
	ds_read_b128 v[216:219], v180 offset:7168
	global_load_lds_dwordx4 v[220:221], off
	v_lshl_add_u64 v[220:221], s[48:49], 0, v[140:141]
	s_add_i32 m0, s9, 0xe000
	s_nop 0
	global_load_lds_dwordx4 v[220:221], off
	s_waitcnt vmcnt(8)
	s_waitcnt lgkmcnt(0)
	s_barrier
	s_waitcnt lgkmcnt(0)
	v_mfma_f32_16x16x32_bf16 v[124:127], v[146:149], v[186:189], v[124:127]
	v_mfma_f32_16x16x32_bf16 v[120:123], v[154:157], v[186:189], v[120:123]
	v_mfma_f32_16x16x32_bf16 v[108:111], v[146:149], v[196:199], v[108:111]
	v_mfma_f32_16x16x32_bf16 v[104:107], v[154:157], v[196:199], v[104:107]
	v_mfma_f32_16x16x32_bf16 v[92:95], v[146:149], v[204:207], v[92:95]
	v_mfma_f32_16x16x32_bf16 v[88:91], v[154:157], v[204:207], v[88:91]
	v_mfma_f32_16x16x32_bf16 v[76:79], v[146:149], v[212:215], v[76:79]
	v_mfma_f32_16x16x32_bf16 v[72:75], v[154:157], v[212:215], v[72:75]
	v_mfma_f32_16x16x32_bf16 v[124:127], v[150:153], v[190:193], v[124:127]
	v_mfma_f32_16x16x32_bf16 v[120:123], v[158:161], v[190:193], v[120:123]
	v_mfma_f32_16x16x32_bf16 v[108:111], v[150:153], v[200:203], v[108:111]
	v_mfma_f32_16x16x32_bf16 v[104:107], v[158:161], v[200:203], v[104:107]
	v_mfma_f32_16x16x32_bf16 v[92:95], v[150:153], v[208:211], v[92:95]
	v_mfma_f32_16x16x32_bf16 v[88:91], v[158:161], v[208:211], v[88:91]
	v_mfma_f32_16x16x32_bf16 v[76:79], v[150:153], v[216:219], v[76:79]
	v_mfma_f32_16x16x32_bf16 v[72:75], v[158:161], v[216:219], v[72:75]
	v_mfma_f32_16x16x32_bf16 v[116:119], v[162:165], v[186:189], v[116:119]
	v_mfma_f32_16x16x32_bf16 v[112:115], v[170:173], v[186:189], v[112:115]
	v_mfma_f32_16x16x32_bf16 v[100:103], v[162:165], v[196:199], v[100:103]
	v_mfma_f32_16x16x32_bf16 v[96:99], v[170:173], v[196:199], v[96:99]
	v_mfma_f32_16x16x32_bf16 v[84:87], v[162:165], v[204:207], v[84:87]
	v_mfma_f32_16x16x32_bf16 v[80:83], v[170:173], v[204:207], v[80:83]
	v_mfma_f32_16x16x32_bf16 v[68:71], v[162:165], v[212:215], v[68:71]
	v_mfma_f32_16x16x32_bf16 v[64:67], v[170:173], v[212:215], v[64:67]
	v_mfma_f32_16x16x32_bf16 v[116:119], v[166:169], v[190:193], v[116:119]
	v_mfma_f32_16x16x32_bf16 v[112:115], v[182:185], v[190:193], v[112:115]
	v_mfma_f32_16x16x32_bf16 v[100:103], v[166:169], v[200:203], v[100:103]
	v_mfma_f32_16x16x32_bf16 v[96:99], v[182:185], v[200:203], v[96:99]
	v_mfma_f32_16x16x32_bf16 v[84:87], v[166:169], v[208:211], v[84:87]
	v_mfma_f32_16x16x32_bf16 v[80:83], v[182:185], v[208:211], v[80:83]
	v_mfma_f32_16x16x32_bf16 v[68:71], v[166:169], v[216:219], v[68:71]
	v_mfma_f32_16x16x32_bf16 v[64:67], v[182:185], v[216:219], v[64:67]
	s_barrier
	s_add_i32 s69, s61, s8
	v_lshl_add_u64 v[220:221], s[50:51], 0, v[130:131]
	s_mov_b32 m0, s69
	ds_read_b128 v[186:189], v180 offset:16384
	ds_read_b128 v[190:193], v180 offset:17408
	ds_read_b128 v[196:199], v180 offset:18432
	ds_read_b128 v[200:203], v180 offset:19456
	ds_read_b128 v[204:207], v180 offset:20480
	ds_read_b128 v[208:211], v180 offset:21504
	ds_read_b128 v[212:215], v180 offset:22528
	ds_read_b128 v[216:219], v180 offset:23552
	global_load_lds_dwordx4 v[220:221], off
	s_add_i32 m0, s69, 0x2000
	s_add_u32 s70, s50, 0x40000
	v_lshl_add_u64 v[222:223], s[50:51], 0, v[134:135]
	s_addc_u32 s71, s51, 0
	s_add_i32 s69, s62, s8
	global_load_lds_dwordx4 v[222:223], off
	v_lshl_add_u64 v[224:225], s[70:71], 0, v[130:131]
	s_mov_b32 m0, s69
	v_lshl_add_u64 v[226:227], s[52:53], 0, v[132:133]
	global_load_lds_dwordx4 v[224:225], off
	v_lshl_add_u64 v[224:225], s[70:71], 0, v[134:135]
	s_add_i32 m0, s69, 0x2000
	s_nop 0
	global_load_lds_dwordx4 v[224:225], off
	v_lshl_add_u64 v[224:225], s[52:53], 0, v[128:129]
	s_mov_b32 m0, s9
	s_nop 0
	global_load_lds_dwordx4 v[224:225], off
	s_mov_b32 m0, s55
	s_nop 0
	global_load_lds_dwordx4 v[226:227], off
	s_waitcnt vmcnt(8)
	s_waitcnt lgkmcnt(0)
	s_barrier
; #define PG8_STAGE_T(bufoff, gbase, voff, AUX) do { _Pragma("unroll") for (int _i = 0; _i < 2; ++_i) \
;         __builtin_amdgcn_global_load_lds((const unsigned*)((const char*)(gbase) + (voff)[_i]), (PG8_LAS unsigned*)(lds + (bufoff) + ldsw + _i * 8192), 16, 0, AUX); } while (0)
; #define PG8_LDA(dst, b, h) do { _Pragma("unroll") for (int m = 0; m < 4; ++m) _Pragma("unroll") for (int k = 0; k < 2; ++k) dst[m][k] = *(const PG8_LAS bf16x8*)(lds + PG8_SA(b, h) + aoff + m * 2048 + k * 1024); } while (0)
; #define PG8_LDB(dst, b, h) do { _Pragma("unroll") for (int n = 0; n < 2; ++n) _Pragma("unroll") for (int k = 0; k < 2; ++k) dst[n][k] = *(const PG8_LAS bf16x8*)(lds + PG8_SB(b, h) + boff + n * 2048 + k * 1024); } while (0)
; #define PG8_MMA(ai, bj, At, Bt) do { __builtin_amdgcn_s_setprio(1); _Pragma("unroll") for (int m = 0; m < 4; ++m) _Pragma("unroll") for (int n = 0; n < 2; ++n) _Pragma("unroll") for (int k = 0; k < 2; ++k) \
;         acc[ai][bj][m][n] = __builtin_amdgcn_mfma_f32_16x16x32_bf16(Bt[n][k], At[m][k], acc[ai][bj][m][n], 0, 0, 0); __builtin_amdgcn_s_setprio(0); } while (0)
; #define PG8_WAIT_V(n) asm volatile("s_waitcnt vmcnt(" #n ")" ::: "memory")
; #define PG8_WAIT_L(n) asm volatile("s_waitcnt lgkmcnt(" #n ")" ::: "memory")
; #define PG8_BAR __builtin_amdgcn_s_barrier()
; #define PG8_SCHED __builtin_amdgcn_sched_barrier(0)
;     ...
;             if (!pe) { PG8_WAIT_V(8); } PG8_WAIT_L(0); PG8_BAR; PG8_MMA(1, 0, At, B0); PG8_MMA(1, 1, At, B1); PG8_BAR; PG8_SCHED;
;             PG8_LDB(B0, 1, 0); PG8_LDB(B1, 1, 1); PG8_SCHED; PG8_LDA(At, 1, 0); PG8_STAGE_T(PG8_SA(0, 1), a2 + hstep, voffA, AUX_A);
;             if (!pe) { PG8_WAIT_V(8); } PG8_WAIT_L(0); PG8_BAR; PG8_MMA(0, 0, At, B0); PG8_MMA(0, 1, At, B1); PG8_BAR; PG8_SCHED;
	s_waitcnt lgkmcnt(0)
	v_mfma_f32_16x16x32_bf16 v[60:63], v[146:149], v[186:189], v[60:63]
	v_mfma_f32_16x16x32_bf16 v[56:59], v[154:157], v[186:189], v[56:59]
	v_mfma_f32_16x16x32_bf16 v[44:47], v[146:149], v[196:199], v[44:47]
	v_mfma_f32_16x16x32_bf16 v[40:43], v[154:157], v[196:199], v[40:43]
	v_mfma_f32_16x16x32_bf16 v[28:31], v[146:149], v[204:207], v[28:31]
	v_mfma_f32_16x16x32_bf16 v[24:27], v[154:157], v[204:207], v[24:27]
	v_mfma_f32_16x16x32_bf16 v[12:15], v[146:149], v[212:215], v[12:15]
	v_mfma_f32_16x16x32_bf16 v[8:11], v[154:157], v[212:215], v[8:11]
	v_mfma_f32_16x16x32_bf16 v[60:63], v[150:153], v[190:193], v[60:63]
	v_mfma_f32_16x16x32_bf16 v[56:59], v[158:161], v[190:193], v[56:59]
	v_mfma_f32_16x16x32_bf16 v[44:47], v[150:153], v[200:203], v[44:47]
	v_mfma_f32_16x16x32_bf16 v[40:43], v[158:161], v[200:203], v[40:43]
	v_mfma_f32_16x16x32_bf16 v[28:31], v[150:153], v[208:211], v[28:31]
	v_mfma_f32_16x16x32_bf16 v[24:27], v[158:161], v[208:211], v[24:27]
	v_mfma_f32_16x16x32_bf16 v[12:15], v[150:153], v[216:219], v[12:15]
	v_mfma_f32_16x16x32_bf16 v[8:11], v[158:161], v[216:219], v[8:11]
	v_mfma_f32_16x16x32_bf16 v[52:55], v[162:165], v[186:189], v[52:55]
	v_mfma_f32_16x16x32_bf16 v[48:51], v[170:173], v[186:189], v[48:51]
	v_mfma_f32_16x16x32_bf16 v[36:39], v[162:165], v[196:199], v[36:39]
	v_mfma_f32_16x16x32_bf16 v[32:35], v[170:173], v[196:199], v[32:35]
	v_mfma_f32_16x16x32_bf16 v[20:23], v[162:165], v[204:207], v[20:23]
	v_mfma_f32_16x16x32_bf16 v[16:19], v[170:173], v[204:207], v[16:19]
	v_mfma_f32_16x16x32_bf16 v[4:7], v[162:165], v[212:215], v[4:7]
	v_mfma_f32_16x16x32_bf16 v[0:3], v[170:173], v[212:215], v[0:3]
	v_mfma_f32_16x16x32_bf16 v[52:55], v[166:169], v[190:193], v[52:55]
	v_mfma_f32_16x16x32_bf16 v[48:51], v[182:185], v[190:193], v[48:51]
	v_mfma_f32_16x16x32_bf16 v[36:39], v[166:169], v[200:203], v[36:39]
	v_mfma_f32_16x16x32_bf16 v[32:35], v[182:185], v[200:203], v[32:35]
	v_mfma_f32_16x16x32_bf16 v[20:23], v[166:169], v[208:211], v[20:23]
	v_mfma_f32_16x16x32_bf16 v[16:19], v[182:185], v[208:211], v[16:19]
	v_mfma_f32_16x16x32_bf16 v[4:7], v[166:169], v[216:219], v[4:7]
	v_mfma_f32_16x16x32_bf16 v[0:3], v[182:185], v[216:219], v[0:3]
	s_barrier
	s_add_i32 s69, 0, 0x18000
	v_add_u32_e32 v136, s69, v175
	s_add_i32 s70, 0, 0x1c000
	ds_read_b128 v[146:149], v136
	ds_read_b128 v[150:153], v136 offset:1024
	ds_read_b128 v[154:157], v136 offset:2048
	ds_read_b128 v[158:161], v136 offset:3072
	v_add_u32_e32 v136, s70, v175
	ds_read_b128 v[162:165], v136
	ds_read_b128 v[166:169], v136 offset:1024
	ds_read_b128 v[170:173], v136 offset:2048
	ds_read_b128 v[182:185], v136 offset:3072
	s_add_u32 s52, s52, 0x40000
	s_addc_u32 s53, s53, 0
	s_mov_b32 m0, s56
	v_lshl_add_u64 v[228:229], s[52:53], 0, v[128:129]
	ds_read_b128 v[186:189], v180 offset:32768
	ds_read_b128 v[190:193], v180 offset:33792
	ds_read_b128 v[196:199], v180 offset:34816
	ds_read_b128 v[200:203], v180 offset:35840
	ds_read_b128 v[204:207], v180 offset:36864
	ds_read_b128 v[208:211], v180 offset:37888
	ds_read_b128 v[212:215], v180 offset:38912
	ds_read_b128 v[216:219], v180 offset:39936
	global_load_lds_dwordx4 v[228:229], off
	v_lshl_add_u64 v[228:229], s[52:53], 0, v[132:133]
	s_mov_b32 m0, s57
	s_nop 0
	global_load_lds_dwordx4 v[228:229], off
	s_waitcnt vmcnt(8)
	s_waitcnt lgkmcnt(0)
	s_barrier
	s_waitcnt lgkmcnt(0)
	v_mfma_f32_16x16x32_bf16 v[124:127], v[146:149], v[186:189], v[124:127]
	v_mfma_f32_16x16x32_bf16 v[120:123], v[154:157], v[186:189], v[120:123]
	v_mfma_f32_16x16x32_bf16 v[108:111], v[146:149], v[196:199], v[108:111]
	v_mfma_f32_16x16x32_bf16 v[104:107], v[154:157], v[196:199], v[104:107]
	v_mfma_f32_16x16x32_bf16 v[92:95], v[146:149], v[204:207], v[92:95]
	v_mfma_f32_16x16x32_bf16 v[88:91], v[154:157], v[204:207], v[88:91]
	v_mfma_f32_16x16x32_bf16 v[76:79], v[146:149], v[212:215], v[76:79]
	v_mfma_f32_16x16x32_bf16 v[72:75], v[154:157], v[212:215], v[72:75]
	v_mfma_f32_16x16x32_bf16 v[124:127], v[150:153], v[190:193], v[124:127]
	v_mfma_f32_16x16x32_bf16 v[120:123], v[158:161], v[190:193], v[120:123]
	v_mfma_f32_16x16x32_bf16 v[108:111], v[150:153], v[200:203], v[108:111]
	v_mfma_f32_16x16x32_bf16 v[104:107], v[158:161], v[200:203], v[104:107]
	v_mfma_f32_16x16x32_bf16 v[92:95], v[150:153], v[208:211], v[92:95]
	v_mfma_f32_16x16x32_bf16 v[88:91], v[158:161], v[208:211], v[88:91]
	v_mfma_f32_16x16x32_bf16 v[76:79], v[150:153], v[216:219], v[76:79]
	v_mfma_f32_16x16x32_bf16 v[72:75], v[158:161], v[216:219], v[72:75]
	v_mfma_f32_16x16x32_bf16 v[116:119], v[162:165], v[186:189], v[116:119]
	v_mfma_f32_16x16x32_bf16 v[112:115], v[170:173], v[186:189], v[112:115]
	v_mfma_f32_16x16x32_bf16 v[100:103], v[162:165], v[196:199], v[100:103]
	v_mfma_f32_16x16x32_bf16 v[96:99], v[170:173], v[196:199], v[96:99]
	v_mfma_f32_16x16x32_bf16 v[84:87], v[162:165], v[204:207], v[84:87]
	v_mfma_f32_16x16x32_bf16 v[80:83], v[170:173], v[204:207], v[80:83]
	v_mfma_f32_16x16x32_bf16 v[68:71], v[162:165], v[212:215], v[68:71]
	v_mfma_f32_16x16x32_bf16 v[64:67], v[170:173], v[212:215], v[64:67]
	v_mfma_f32_16x16x32_bf16 v[116:119], v[166:169], v[190:193], v[116:119]
	v_mfma_f32_16x16x32_bf16 v[112:115], v[182:185], v[190:193], v[112:115]
	v_mfma_f32_16x16x32_bf16 v[100:103], v[166:169], v[200:203], v[100:103]
	v_mfma_f32_16x16x32_bf16 v[96:99], v[182:185], v[200:203], v[96:99]
	v_mfma_f32_16x16x32_bf16 v[84:87], v[166:169], v[208:211], v[84:87]
	v_mfma_f32_16x16x32_bf16 v[80:83], v[182:185], v[208:211], v[80:83]
	v_mfma_f32_16x16x32_bf16 v[68:71], v[166:169], v[216:219], v[68:71]
	v_mfma_f32_16x16x32_bf16 v[64:67], v[182:185], v[216:219], v[64:67]
	s_barrier
; #define PG8_STAGE_T(bufoff, gbase, voff, AUX) do { _Pragma("unroll") for (int _i = 0; _i < 2; ++_i) \
;         __builtin_amdgcn_global_load_lds((const unsigned*)((const char*)(gbase) + (voff)[_i]), (PG8_LAS unsigned*)(lds + (bufoff) + ldsw + _i * 8192), 16, 0, AUX); } while (0)
; #define PG8_LDA(dst, b, h) do { _Pragma("unroll") for (int m = 0; m < 4; ++m) _Pragma("unroll") for (int k = 0; k < 2; ++k) dst[m][k] = *(const PG8_LAS bf16x8*)(lds + PG8_SA(b, h) + aoff + m * 2048 + k * 1024); } while (0)
; #define PG8_MMA(ai, bj, At, Bt) do { __builtin_amdgcn_s_setprio(1); _Pragma("unroll") for (int m = 0; m < 4; ++m) _Pragma("unroll") for (int n = 0; n < 2; ++n) _Pragma("unroll") for (int k = 0; k < 2; ++k) \
;         acc[ai][bj][m][n] = __builtin_amdgcn_mfma_f32_16x16x32_bf16(Bt[n][k], At[m][k], acc[ai][bj][m][n], 0, 0, 0); __builtin_amdgcn_s_setprio(0); } while (0)
; #define PG8_WAIT_V(n) asm volatile("s_waitcnt vmcnt(" #n ")" ::: "memory")
; #define PG8_WAIT_L(n) asm volatile("s_waitcnt lgkmcnt(" #n ")" ::: "memory")
; #define PG8_BAR __builtin_amdgcn_s_barrier()
; #define PG8_SCHED __builtin_amdgcn_sched_barrier(0)
;     ...
;             PG8_LDA(At, 1, 1); PG8_STAGE_T(PG8_SB(1, 0), b3, voffB, AUX_B); PG8_STAGE_T(PG8_SB(1, 1), b3 + hstep, voffB, AUX_B); PG8_STAGE_T(PG8_SA(1, 0), a3, voffA, AUX_A);
;             PG8_WAIT_V(8); PG8_WAIT_L(0); PG8_BAR; PG8_MMA(1, 0, At, B0); PG8_MMA(1, 1, At, B1); PG8_BAR; PG8_SCHED;
	s_add_i32 s52, s69, s8
	v_lshl_add_u64 v[220:221], v[220:221], 0, s[22:23]
	s_mov_b32 m0, s52
	ds_read_b128 v[186:189], v180 offset:49152
	ds_read_b128 v[190:193], v180 offset:50176
	ds_read_b128 v[196:199], v180 offset:51200
	ds_read_b128 v[200:203], v180 offset:52224
	ds_read_b128 v[204:207], v180 offset:53248
	ds_read_b128 v[208:211], v180 offset:54272
	ds_read_b128 v[212:215], v180 offset:55296
	ds_read_b128 v[216:219], v180 offset:56320
	global_load_lds_dwordx4 v[220:221], off
	s_add_i32 m0, s52, 0x2000
	s_add_u32 s50, s50, 0x40080
	v_lshl_add_u64 v[220:221], v[222:223], 0, s[22:23]
	s_addc_u32 s51, s51, 0
	s_add_i32 s52, s70, s8
	global_load_lds_dwordx4 v[220:221], off
	v_lshl_add_u64 v[220:221], s[50:51], 0, v[130:131]
	s_mov_b32 m0, s52
	s_nop 0
	global_load_lds_dwordx4 v[220:221], off
	v_lshl_add_u64 v[220:221], s[50:51], 0, v[134:135]
	s_add_i32 m0, s52, 0x2000
	s_nop 0
	global_load_lds_dwordx4 v[220:221], off
	v_lshl_add_u64 v[220:221], v[224:225], 0, s[22:23]
	s_mov_b32 m0, s59
	s_nop 0
	global_load_lds_dwordx4 v[220:221], off
	v_lshl_add_u64 v[220:221], v[226:227], 0, s[22:23]
	s_mov_b32 m0, s60
	s_nop 0
	global_load_lds_dwordx4 v[220:221], off
	s_waitcnt vmcnt(8)
	s_waitcnt lgkmcnt(0)
	s_barrier
	s_waitcnt lgkmcnt(0)
	v_mfma_f32_16x16x32_bf16 v[60:63], v[146:149], v[186:189], v[60:63]
	v_mfma_f32_16x16x32_bf16 v[56:59], v[154:157], v[186:189], v[56:59]
	v_mfma_f32_16x16x32_bf16 v[44:47], v[146:149], v[196:199], v[44:47]
	v_mfma_f32_16x16x32_bf16 v[40:43], v[154:157], v[196:199], v[40:43]
	v_mfma_f32_16x16x32_bf16 v[28:31], v[146:149], v[204:207], v[28:31]
	v_mfma_f32_16x16x32_bf16 v[24:27], v[154:157], v[204:207], v[24:27]
	v_mfma_f32_16x16x32_bf16 v[12:15], v[146:149], v[212:215], v[12:15]
	v_mfma_f32_16x16x32_bf16 v[8:11], v[154:157], v[212:215], v[8:11]
	v_mfma_f32_16x16x32_bf16 v[60:63], v[150:153], v[190:193], v[60:63]
	v_mfma_f32_16x16x32_bf16 v[56:59], v[158:161], v[190:193], v[56:59]
	v_mfma_f32_16x16x32_bf16 v[44:47], v[150:153], v[200:203], v[44:47]
	v_mfma_f32_16x16x32_bf16 v[40:43], v[158:161], v[200:203], v[40:43]
	v_mfma_f32_16x16x32_bf16 v[28:31], v[150:153], v[208:211], v[28:31]
	v_mfma_f32_16x16x32_bf16 v[24:27], v[158:161], v[208:211], v[24:27]
	v_mfma_f32_16x16x32_bf16 v[12:15], v[150:153], v[216:219], v[12:15]
	v_mfma_f32_16x16x32_bf16 v[8:11], v[158:161], v[216:219], v[8:11]
	v_mfma_f32_16x16x32_bf16 v[52:55], v[162:165], v[186:189], v[52:55]
	v_mfma_f32_16x16x32_bf16 v[48:51], v[170:173], v[186:189], v[48:51]
	v_mfma_f32_16x16x32_bf16 v[36:39], v[162:165], v[196:199], v[36:39]
	v_mfma_f32_16x16x32_bf16 v[32:35], v[170:173], v[196:199], v[32:35]
	v_mfma_f32_16x16x32_bf16 v[20:23], v[162:165], v[204:207], v[20:23]
	v_mfma_f32_16x16x32_bf16 v[16:19], v[170:173], v[204:207], v[16:19]
	v_mfma_f32_16x16x32_bf16 v[4:7], v[162:165], v[212:215], v[4:7]
	v_mfma_f32_16x16x32_bf16 v[0:3], v[170:173], v[212:215], v[0:3]
	v_mfma_f32_16x16x32_bf16 v[52:55], v[166:169], v[190:193], v[52:55]
	v_mfma_f32_16x16x32_bf16 v[48:51], v[182:185], v[190:193], v[48:51]
	v_mfma_f32_16x16x32_bf16 v[36:39], v[166:169], v[200:203], v[36:39]
	v_mfma_f32_16x16x32_bf16 v[32:35], v[182:185], v[200:203], v[32:35]
	v_mfma_f32_16x16x32_bf16 v[20:23], v[166:169], v[208:211], v[20:23]
	v_mfma_f32_16x16x32_bf16 v[16:19], v[182:185], v[208:211], v[16:19]
	v_mfma_f32_16x16x32_bf16 v[4:7], v[166:169], v[216:219], v[4:7]
	v_mfma_f32_16x16x32_bf16 v[0:3], v[182:185], v[216:219], v[0:3]
	s_barrier
	s_add_i32 s68, s68, 2
	s_add_u32 s48, s48, 0x100
	s_addc_u32 s49, s49, 0
	s_add_u32 s66, s66, 0x100
	s_addc_u32 s67, s67, 0
	s_cmp_gt_u32 s68, 13
	s_cbranch_scc0 .LBB0_516
	s_and_b64 vcc, exec, s[24:25]
	s_cbranch_vccz .LBB0_519
	s_barrier

; #define PG8_STAGE_T(bufoff, gbase, voff, AUX) do { _Pragma("unroll") for (int _i = 0; _i < 2; ++_i) \
;         __builtin_amdgcn_global_load_lds((const unsigned*)((const char*)(gbase) + (voff)[_i]), (PG8_LAS unsigned*)(lds + (bufoff) + ldsw + _i * 8192), 16, 0, AUX); } while (0)
; #define PG8_LDA(dst, b, h) do { _Pragma("unroll") for (int m = 0; m < 4; ++m) _Pragma("unroll") for (int k = 0; k < 2; ++k) dst[m][k] = *(const PG8_LAS bf16x8*)(lds + PG8_SA(b, h) + aoff + m * 2048 + k * 1024); } while (0)
; #define PG8_LDB(dst, b, h) do { _Pragma("unroll") for (int n = 0; n < 2; ++n) _Pragma("unroll") for (int k = 0; k < 2; ++k) dst[n][k] = *(const PG8_LAS bf16x8*)(lds + PG8_SB(b, h) + boff + n * 2048 + k * 1024); } while (0)
; #define PG8_MMA(ai, bj, At, Bt) do { __builtin_amdgcn_s_setprio(1); _Pragma("unroll") for (int m = 0; m < 4; ++m) _Pragma("unroll") for (int n = 0; n < 2; ++n) _Pragma("unroll") for (int k = 0; k < 2; ++k) \
;         acc[ai][bj][m][n] = __builtin_amdgcn_mfma_f32_16x16x32_bf16(Bt[n][k], At[m][k], acc[ai][bj][m][n], 0, 0, 0); __builtin_amdgcn_s_setprio(0); } while (0)
; #define PG8_WAIT_V(n) asm volatile("s_waitcnt vmcnt(" #n ")" ::: "memory")
; #define PG8_WAIT_L(n) asm volatile("s_waitcnt lgkmcnt(" #n ")" ::: "memory")
; #define PG8_BAR __builtin_amdgcn_s_barrier()
; #define PG8_SCHED __builtin_amdgcn_sched_barrier(0)
;     ...
;             PG8_LDB(B0, 0, 0); PG8_LDB(B1, 0, 1); PG8_SCHED; PG8_LDA(At, 0, 0); if (!pe) { PG8_STAGE_T(PG8_SA(1, 1), a1 + hstep, voffA, AUX_A); }
;             if (!pe) { PG8_WAIT_V(8); } PG8_WAIT_L(0); PG8_BAR; PG8_MMA(0, 0, At, B0); PG8_MMA(0, 1, At, B1); PG8_BAR; PG8_SCHED;
;             PG8_LDA(At, 0, 1); PG8_STAGE_T(PG8_SB(0, 0), b2, voffB, AUX_B); PG8_STAGE_T(PG8_SB(0, 1), b2 + hstep, voffB, AUX_B); PG8_STAGE_T(PG8_SA(0, 0), a2, voffA, AUX_A);
;             if (!pe) { PG8_WAIT_V(8); } PG8_WAIT_L(0); PG8_BAR; PG8_MMA(1, 0, At, B0); PG8_MMA(1, 1, At, B1); PG8_BAR; PG8_SCHED;
.LBB0_787:
	ds_read_b128 v[136:139], v163
	ds_read_b128 v[140:143], v163 offset:1024
	ds_read_b128 v[166:169], v163 offset:2048
	ds_read_b128 v[170:173], v163 offset:3072
	ds_read_b128 v[174:177], v164
	ds_read_b128 v[178:181], v164 offset:1024
	ds_read_b128 v[182:185], v164 offset:2048
	ds_read_b128 v[186:189], v164 offset:3072
	s_add_u32 s46, s44, 0xfffc0080
	s_addc_u32 s47, s45, -1
	s_cmp_eq_u32 s65, 12
	s_cselect_b32 s49, s25, s47
	s_cselect_b32 s48, s61, s46
	s_cselect_b32 s47, s37, s64
	s_cselect_b32 s46, s62, s63
	v_lshl_add_u64 v[224:225], s[44:45], 0, v[128:129]
	s_add_i32 m0, s43, 0xc000
	ds_read_b128 v[190:193], v165
	ds_read_b128 v[196:199], v165 offset:1024
	ds_read_b128 v[200:203], v165 offset:2048
	ds_read_b128 v[204:207], v165 offset:3072
	ds_read_b128 v[208:211], v165 offset:4096
	ds_read_b128 v[212:215], v165 offset:5120
	ds_read_b128 v[216:219], v165 offset:6144
	ds_read_b128 v[220:223], v165 offset:7168
	global_load_lds_dwordx4 v[224:225], off
	v_lshl_add_u64 v[224:225], s[44:45], 0, v[130:131]
	s_add_i32 m0, s43, 0xe000
	s_nop 0
	global_load_lds_dwordx4 v[224:225], off
	s_waitcnt vmcnt(8)
	s_waitcnt lgkmcnt(0)
	s_barrier
	s_waitcnt lgkmcnt(0)
	v_mfma_f32_16x16x32_bf16 v[124:127], v[136:139], v[190:193], v[124:127]
	v_mfma_f32_16x16x32_bf16 v[120:123], v[166:169], v[190:193], v[120:123]
	v_mfma_f32_16x16x32_bf16 v[116:119], v[136:139], v[200:203], v[116:119]
	v_mfma_f32_16x16x32_bf16 v[112:115], v[166:169], v[200:203], v[112:115]
	v_mfma_f32_16x16x32_bf16 v[96:99], v[136:139], v[208:211], v[96:99]
	v_mfma_f32_16x16x32_bf16 v[88:91], v[166:169], v[208:211], v[88:91]
	v_mfma_f32_16x16x32_bf16 v[80:83], v[136:139], v[216:219], v[80:83]
	v_mfma_f32_16x16x32_bf16 v[72:75], v[166:169], v[216:219], v[72:75]
	v_mfma_f32_16x16x32_bf16 v[124:127], v[140:143], v[196:199], v[124:127]
	v_mfma_f32_16x16x32_bf16 v[120:123], v[170:173], v[196:199], v[120:123]
	v_mfma_f32_16x16x32_bf16 v[116:119], v[140:143], v[204:207], v[116:119]
	v_mfma_f32_16x16x32_bf16 v[112:115], v[170:173], v[204:207], v[112:115]
	v_mfma_f32_16x16x32_bf16 v[96:99], v[140:143], v[212:215], v[96:99]
	v_mfma_f32_16x16x32_bf16 v[88:91], v[170:173], v[212:215], v[88:91]
	v_mfma_f32_16x16x32_bf16 v[80:83], v[140:143], v[220:223], v[80:83]
	v_mfma_f32_16x16x32_bf16 v[72:75], v[170:173], v[220:223], v[72:75]
	v_mfma_f32_16x16x32_bf16 v[108:111], v[174:177], v[190:193], v[108:111]
	v_mfma_f32_16x16x32_bf16 v[104:107], v[182:185], v[190:193], v[104:107]
	v_mfma_f32_16x16x32_bf16 v[100:103], v[174:177], v[200:203], v[100:103]
	v_mfma_f32_16x16x32_bf16 v[92:95], v[182:185], v[200:203], v[92:95]
	v_mfma_f32_16x16x32_bf16 v[84:87], v[174:177], v[208:211], v[84:87]
	v_mfma_f32_16x16x32_bf16 v[76:79], v[182:185], v[208:211], v[76:79]
	v_mfma_f32_16x16x32_bf16 v[68:71], v[174:177], v[216:219], v[68:71]
	v_mfma_f32_16x16x32_bf16 v[64:67], v[182:185], v[216:219], v[64:67]
	v_mfma_f32_16x16x32_bf16 v[108:111], v[178:181], v[196:199], v[108:111]
	v_mfma_f32_16x16x32_bf16 v[104:107], v[186:189], v[196:199], v[104:107]
	v_mfma_f32_16x16x32_bf16 v[100:103], v[178:181], v[204:207], v[100:103]
	v_mfma_f32_16x16x32_bf16 v[92:95], v[186:189], v[204:207], v[92:95]
	v_mfma_f32_16x16x32_bf16 v[84:87], v[178:181], v[212:215], v[84:87]
	v_mfma_f32_16x16x32_bf16 v[76:79], v[186:189], v[212:215], v[76:79]
	v_mfma_f32_16x16x32_bf16 v[68:71], v[178:181], v[220:223], v[68:71]
	v_mfma_f32_16x16x32_bf16 v[64:67], v[186:189], v[220:223], v[64:67]
	s_barrier
	s_add_i32 s66, s58, s50
	v_lshl_add_u64 v[224:225], s[46:47], 0, v[154:155]
	s_mov_b32 m0, s66
	ds_read_b128 v[190:193], v165 offset:16384
	ds_read_b128 v[196:199], v165 offset:17408
	ds_read_b128 v[200:203], v165 offset:18432
	ds_read_b128 v[204:207], v165 offset:19456
	ds_read_b128 v[208:211], v165 offset:20480
	ds_read_b128 v[212:215], v165 offset:21504
	ds_read_b128 v[216:219], v165 offset:22528
	ds_read_b128 v[220:223], v165 offset:23552
	global_load_lds_dwordx4 v[224:225], off
	s_add_i32 m0, s66, 0x2000
	s_add_u32 s66, s46, 0x40000
	v_lshl_add_u64 v[226:227], s[46:47], 0, v[158:159]
	s_addc_u32 s67, s47, 0
	s_add_i32 s68, s59, s50
	global_load_lds_dwordx4 v[226:227], off
	v_lshl_add_u64 v[228:229], s[66:67], 0, v[154:155]
	s_mov_b32 m0, s68
	v_lshl_add_u64 v[230:231], s[48:49], 0, v[156:157]
	global_load_lds_dwordx4 v[228:229], off
	v_lshl_add_u64 v[228:229], s[66:67], 0, v[158:159]
	s_add_i32 m0, s68, 0x2000
	s_nop 0
	global_load_lds_dwordx4 v[228:229], off
	v_lshl_add_u64 v[228:229], s[48:49], 0, v[152:153]
	s_mov_b32 m0, s43
	s_nop 0
	global_load_lds_dwordx4 v[228:229], off
	s_mov_b32 m0, s51
	s_nop 0
	global_load_lds_dwordx4 v[230:231], off
	s_waitcnt vmcnt(8)
	s_waitcnt lgkmcnt(0)
	s_barrier
; #define PG8_STAGE_T(bufoff, gbase, voff, AUX) do { _Pragma("unroll") for (int _i = 0; _i < 2; ++_i) \
;         __builtin_amdgcn_global_load_lds((const unsigned*)((const char*)(gbase) + (voff)[_i]), (PG8_LAS unsigned*)(lds + (bufoff) + ldsw + _i * 8192), 16, 0, AUX); } while (0)
; #define PG8_LDA(dst, b, h) do { _Pragma("unroll") for (int m = 0; m < 4; ++m) _Pragma("unroll") for (int k = 0; k < 2; ++k) dst[m][k] = *(const PG8_LAS bf16x8*)(lds + PG8_SA(b, h) + aoff + m * 2048 + k * 1024); } while (0)
; #define PG8_LDB(dst, b, h) do { _Pragma("unroll") for (int n = 0; n < 2; ++n) _Pragma("unroll") for (int k = 0; k < 2; ++k) dst[n][k] = *(const PG8_LAS bf16x8*)(lds + PG8_SB(b, h) + boff + n * 2048 + k * 1024); } while (0)
; #define PG8_MMA(ai, bj, At, Bt) do { __builtin_amdgcn_s_setprio(1); _Pragma("unroll") for (int m = 0; m < 4; ++m) _Pragma("unroll") for (int n = 0; n < 2; ++n) _Pragma("unroll") for (int k = 0; k < 2; ++k) \
;         acc[ai][bj][m][n] = __builtin_amdgcn_mfma_f32_16x16x32_bf16(Bt[n][k], At[m][k], acc[ai][bj][m][n], 0, 0, 0); __builtin_amdgcn_s_setprio(0); } while (0)
; #define PG8_WAIT_V(n) asm volatile("s_waitcnt vmcnt(" #n ")" ::: "memory")
; #define PG8_WAIT_L(n) asm volatile("s_waitcnt lgkmcnt(" #n ")" ::: "memory")
; #define PG8_BAR __builtin_amdgcn_s_barrier()
; #define PG8_SCHED __builtin_amdgcn_sched_barrier(0)
;     ...
;             if (!pe) { PG8_WAIT_V(8); } PG8_WAIT_L(0); PG8_BAR; PG8_MMA(1, 0, At, B0); PG8_MMA(1, 1, At, B1); PG8_BAR; PG8_SCHED;
;             PG8_LDB(B0, 1, 0); PG8_LDB(B1, 1, 1); PG8_SCHED; PG8_LDA(At, 1, 0); PG8_STAGE_T(PG8_SA(0, 1), a2 + hstep, voffA, AUX_A);
;             if (!pe) { PG8_WAIT_V(8); } PG8_WAIT_L(0); PG8_BAR; PG8_MMA(0, 0, At, B0); PG8_MMA(0, 1, At, B1); PG8_BAR; PG8_SCHED;
	s_waitcnt lgkmcnt(0)
	v_mfma_f32_16x16x32_bf16 v[60:63], v[136:139], v[190:193], v[60:63]
	v_mfma_f32_16x16x32_bf16 v[56:59], v[166:169], v[190:193], v[56:59]
	v_mfma_f32_16x16x32_bf16 v[48:51], v[136:139], v[200:203], v[48:51]
	v_mfma_f32_16x16x32_bf16 v[40:43], v[166:169], v[200:203], v[40:43]
	v_mfma_f32_16x16x32_bf16 v[32:35], v[136:139], v[208:211], v[32:35]
	v_mfma_f32_16x16x32_bf16 v[24:27], v[166:169], v[208:211], v[24:27]
	v_mfma_f32_16x16x32_bf16 v[16:19], v[136:139], v[216:219], v[16:19]
	v_mfma_f32_16x16x32_bf16 v[8:11], v[166:169], v[216:219], v[8:11]
	v_mfma_f32_16x16x32_bf16 v[60:63], v[140:143], v[196:199], v[60:63]
	v_mfma_f32_16x16x32_bf16 v[56:59], v[170:173], v[196:199], v[56:59]
	v_mfma_f32_16x16x32_bf16 v[48:51], v[140:143], v[204:207], v[48:51]
	v_mfma_f32_16x16x32_bf16 v[40:43], v[170:173], v[204:207], v[40:43]
	v_mfma_f32_16x16x32_bf16 v[32:35], v[140:143], v[212:215], v[32:35]
	v_mfma_f32_16x16x32_bf16 v[24:27], v[170:173], v[212:215], v[24:27]
	v_mfma_f32_16x16x32_bf16 v[16:19], v[140:143], v[220:223], v[16:19]
	v_mfma_f32_16x16x32_bf16 v[8:11], v[170:173], v[220:223], v[8:11]
	v_mfma_f32_16x16x32_bf16 v[52:55], v[174:177], v[190:193], v[52:55]
	v_mfma_f32_16x16x32_bf16 v[44:47], v[182:185], v[190:193], v[44:47]
	v_mfma_f32_16x16x32_bf16 v[36:39], v[174:177], v[200:203], v[36:39]
	v_mfma_f32_16x16x32_bf16 v[28:31], v[182:185], v[200:203], v[28:31]
	v_mfma_f32_16x16x32_bf16 v[20:23], v[174:177], v[208:211], v[20:23]
	v_mfma_f32_16x16x32_bf16 v[12:15], v[182:185], v[208:211], v[12:15]
	v_mfma_f32_16x16x32_bf16 v[4:7], v[174:177], v[216:219], v[4:7]
	v_mfma_f32_16x16x32_bf16 v[0:3], v[182:185], v[216:219], v[0:3]
	v_mfma_f32_16x16x32_bf16 v[52:55], v[178:181], v[196:199], v[52:55]
	v_mfma_f32_16x16x32_bf16 v[44:47], v[186:189], v[196:199], v[44:47]
	v_mfma_f32_16x16x32_bf16 v[36:39], v[178:181], v[204:207], v[36:39]
	v_mfma_f32_16x16x32_bf16 v[28:31], v[186:189], v[204:207], v[28:31]
	v_mfma_f32_16x16x32_bf16 v[20:23], v[178:181], v[212:215], v[20:23]
	v_mfma_f32_16x16x32_bf16 v[12:15], v[186:189], v[212:215], v[12:15]
	v_mfma_f32_16x16x32_bf16 v[4:7], v[178:181], v[220:223], v[4:7]
	v_mfma_f32_16x16x32_bf16 v[0:3], v[186:189], v[220:223], v[0:3]
	s_barrier
	s_add_i32 s66, 0, 0x18000
	s_add_i32 s67, 0, 0x1c000
	v_add_u32_e32 v170, s66, v161
	v_add_u32_e32 v186, s67, v161
	ds_read_b128 v[136:139], v170
	ds_read_b128 v[140:143], v170 offset:1024
	ds_read_b128 v[166:169], v170 offset:2048
	ds_read_b128 v[170:173], v170 offset:3072
	ds_read_b128 v[174:177], v186
	ds_read_b128 v[178:181], v186 offset:1024
	ds_read_b128 v[182:185], v186 offset:2048
	ds_read_b128 v[186:189], v186 offset:3072
	s_add_u32 s48, s48, 0x40000
	s_addc_u32 s49, s49, 0
	s_mov_b32 m0, s52
	v_lshl_add_u64 v[232:233], s[48:49], 0, v[152:153]
	ds_read_b128 v[190:193], v165 offset:32768
	ds_read_b128 v[196:199], v165 offset:33792
	ds_read_b128 v[200:203], v165 offset:34816
	ds_read_b128 v[204:207], v165 offset:35840
	ds_read_b128 v[208:211], v165 offset:36864
	ds_read_b128 v[212:215], v165 offset:37888
	ds_read_b128 v[216:219], v165 offset:38912
	ds_read_b128 v[220:223], v165 offset:39936
	global_load_lds_dwordx4 v[232:233], off
	v_lshl_add_u64 v[232:233], s[48:49], 0, v[156:157]
	s_mov_b32 m0, s53
	s_nop 0
	global_load_lds_dwordx4 v[232:233], off
	s_waitcnt vmcnt(8)
	s_waitcnt lgkmcnt(0)
	s_barrier
	s_waitcnt lgkmcnt(0)
	v_mfma_f32_16x16x32_bf16 v[124:127], v[136:139], v[190:193], v[124:127]
	v_mfma_f32_16x16x32_bf16 v[120:123], v[166:169], v[190:193], v[120:123]
	v_mfma_f32_16x16x32_bf16 v[116:119], v[136:139], v[200:203], v[116:119]
	v_mfma_f32_16x16x32_bf16 v[112:115], v[166:169], v[200:203], v[112:115]
	v_mfma_f32_16x16x32_bf16 v[96:99], v[136:139], v[208:211], v[96:99]
	v_mfma_f32_16x16x32_bf16 v[88:91], v[166:169], v[208:211], v[88:91]
	v_mfma_f32_16x16x32_bf16 v[80:83], v[136:139], v[216:219], v[80:83]
	v_mfma_f32_16x16x32_bf16 v[72:75], v[166:169], v[216:219], v[72:75]
	v_mfma_f32_16x16x32_bf16 v[124:127], v[140:143], v[196:199], v[124:127]
	v_mfma_f32_16x16x32_bf16 v[120:123], v[170:173], v[196:199], v[120:123]
	v_mfma_f32_16x16x32_bf16 v[116:119], v[140:143], v[204:207], v[116:119]
	v_mfma_f32_16x16x32_bf16 v[112:115], v[170:173], v[204:207], v[112:115]
	v_mfma_f32_16x16x32_bf16 v[96:99], v[140:143], v[212:215], v[96:99]
	v_mfma_f32_16x16x32_bf16 v[88:91], v[170:173], v[212:215], v[88:91]
	v_mfma_f32_16x16x32_bf16 v[80:83], v[140:143], v[220:223], v[80:83]
	v_mfma_f32_16x16x32_bf16 v[72:75], v[170:173], v[220:223], v[72:75]
	v_mfma_f32_16x16x32_bf16 v[108:111], v[174:177], v[190:193], v[108:111]
	v_mfma_f32_16x16x32_bf16 v[104:107], v[182:185], v[190:193], v[104:107]
	v_mfma_f32_16x16x32_bf16 v[100:103], v[174:177], v[200:203], v[100:103]
	v_mfma_f32_16x16x32_bf16 v[92:95], v[182:185], v[200:203], v[92:95]
	v_mfma_f32_16x16x32_bf16 v[84:87], v[174:177], v[208:211], v[84:87]
	v_mfma_f32_16x16x32_bf16 v[76:79], v[182:185], v[208:211], v[76:79]
	v_mfma_f32_16x16x32_bf16 v[68:71], v[174:177], v[216:219], v[68:71]
	v_mfma_f32_16x16x32_bf16 v[64:67], v[182:185], v[216:219], v[64:67]
	v_mfma_f32_16x16x32_bf16 v[108:111], v[178:181], v[196:199], v[108:111]
	v_mfma_f32_16x16x32_bf16 v[104:107], v[186:189], v[196:199], v[104:107]
	v_mfma_f32_16x16x32_bf16 v[100:103], v[178:181], v[204:207], v[100:103]
	v_mfma_f32_16x16x32_bf16 v[92:95], v[186:189], v[204:207], v[92:95]
	v_mfma_f32_16x16x32_bf16 v[84:87], v[178:181], v[212:215], v[84:87]
	v_mfma_f32_16x16x32_bf16 v[76:79], v[186:189], v[212:215], v[76:79]
	v_mfma_f32_16x16x32_bf16 v[68:71], v[178:181], v[220:223], v[68:71]
	v_mfma_f32_16x16x32_bf16 v[64:67], v[186:189], v[220:223], v[64:67]
	s_barrier
; #define PG8_STAGE_T(bufoff, gbase, voff, AUX) do { _Pragma("unroll") for (int _i = 0; _i < 2; ++_i) \
;         __builtin_amdgcn_global_load_lds((const unsigned*)((const char*)(gbase) + (voff)[_i]), (PG8_LAS unsigned*)(lds + (bufoff) + ldsw + _i * 8192), 16, 0, AUX); } while (0)
; #define PG8_LDA(dst, b, h) do { _Pragma("unroll") for (int m = 0; m < 4; ++m) _Pragma("unroll") for (int k = 0; k < 2; ++k) dst[m][k] = *(const PG8_LAS bf16x8*)(lds + PG8_SA(b, h) + aoff + m * 2048 + k * 1024); } while (0)
; #define PG8_MMA(ai, bj, At, Bt) do { __builtin_amdgcn_s_setprio(1); _Pragma("unroll") for (int m = 0; m < 4; ++m) _Pragma("unroll") for (int n = 0; n < 2; ++n) _Pragma("unroll") for (int k = 0; k < 2; ++k) \
;         acc[ai][bj][m][n] = __builtin_amdgcn_mfma_f32_16x16x32_bf16(Bt[n][k], At[m][k], acc[ai][bj][m][n], 0, 0, 0); __builtin_amdgcn_s_setprio(0); } while (0)
; #define PG8_WAIT_V(n) asm volatile("s_waitcnt vmcnt(" #n ")" ::: "memory")
; #define PG8_WAIT_L(n) asm volatile("s_waitcnt lgkmcnt(" #n ")" ::: "memory")
; #define PG8_BAR __builtin_amdgcn_s_barrier()
; #define PG8_SCHED __builtin_amdgcn_sched_barrier(0)
;     ...
;             PG8_LDA(At, 1, 1); PG8_STAGE_T(PG8_SB(1, 0), b3, voffB, AUX_B); PG8_STAGE_T(PG8_SB(1, 1), b3 + hstep, voffB, AUX_B); PG8_STAGE_T(PG8_SA(1, 0), a3, voffA, AUX_A);
;             PG8_WAIT_V(8); PG8_WAIT_L(0); PG8_BAR; PG8_MMA(1, 0, At, B0); PG8_MMA(1, 1, At, B1); PG8_BAR; PG8_SCHED;
	s_add_i32 s48, s66, s50
	v_lshl_add_u64 v[224:225], v[224:225], 0, s[10:11]
	s_mov_b32 m0, s48
	ds_read_b128 v[190:193], v165 offset:49152
	ds_read_b128 v[196:199], v165 offset:50176
	ds_read_b128 v[200:203], v165 offset:51200
	ds_read_b128 v[204:207], v165 offset:52224
	ds_read_b128 v[208:211], v165 offset:53248
	ds_read_b128 v[212:215], v165 offset:54272
	ds_read_b128 v[216:219], v165 offset:55296
	ds_read_b128 v[220:223], v165 offset:56320
	global_load_lds_dwordx4 v[224:225], off
	s_add_i32 m0, s48, 0x2000
	s_add_u32 s46, s46, 0x40080
	v_lshl_add_u64 v[224:225], v[226:227], 0, s[10:11]
	s_addc_u32 s47, s47, 0
	s_add_i32 s48, s67, s50
	global_load_lds_dwordx4 v[224:225], off
	v_lshl_add_u64 v[224:225], s[46:47], 0, v[154:155]
	s_mov_b32 m0, s48
	s_nop 0
	global_load_lds_dwordx4 v[224:225], off
	v_lshl_add_u64 v[224:225], s[46:47], 0, v[158:159]
	s_add_i32 m0, s48, 0x2000
	s_nop 0
	global_load_lds_dwordx4 v[224:225], off
	v_lshl_add_u64 v[224:225], v[228:229], 0, s[10:11]
	s_mov_b32 m0, s55
	s_nop 0
	global_load_lds_dwordx4 v[224:225], off
	v_lshl_add_u64 v[224:225], v[230:231], 0, s[10:11]
	s_mov_b32 m0, s56
	s_nop 0
	global_load_lds_dwordx4 v[224:225], off
	s_waitcnt vmcnt(8)
	s_waitcnt lgkmcnt(0)
	s_barrier
	s_waitcnt lgkmcnt(0)
	v_mfma_f32_16x16x32_bf16 v[60:63], v[136:139], v[190:193], v[60:63]
	v_mfma_f32_16x16x32_bf16 v[56:59], v[166:169], v[190:193], v[56:59]
	v_mfma_f32_16x16x32_bf16 v[48:51], v[136:139], v[200:203], v[48:51]
	v_mfma_f32_16x16x32_bf16 v[40:43], v[166:169], v[200:203], v[40:43]
	v_mfma_f32_16x16x32_bf16 v[32:35], v[136:139], v[208:211], v[32:35]
	v_mfma_f32_16x16x32_bf16 v[24:27], v[166:169], v[208:211], v[24:27]
	v_mfma_f32_16x16x32_bf16 v[16:19], v[136:139], v[216:219], v[16:19]
	v_mfma_f32_16x16x32_bf16 v[8:11], v[166:169], v[216:219], v[8:11]
	v_mfma_f32_16x16x32_bf16 v[60:63], v[140:143], v[196:199], v[60:63]
	v_mfma_f32_16x16x32_bf16 v[56:59], v[170:173], v[196:199], v[56:59]
	v_mfma_f32_16x16x32_bf16 v[48:51], v[140:143], v[204:207], v[48:51]
	v_mfma_f32_16x16x32_bf16 v[40:43], v[170:173], v[204:207], v[40:43]
	v_mfma_f32_16x16x32_bf16 v[32:35], v[140:143], v[212:215], v[32:35]
	v_mfma_f32_16x16x32_bf16 v[24:27], v[170:173], v[212:215], v[24:27]
	v_mfma_f32_16x16x32_bf16 v[16:19], v[140:143], v[220:223], v[16:19]
	v_mfma_f32_16x16x32_bf16 v[8:11], v[170:173], v[220:223], v[8:11]
	v_mfma_f32_16x16x32_bf16 v[52:55], v[174:177], v[190:193], v[52:55]
	v_mfma_f32_16x16x32_bf16 v[44:47], v[182:185], v[190:193], v[44:47]
	v_mfma_f32_16x16x32_bf16 v[36:39], v[174:177], v[200:203], v[36:39]
	v_mfma_f32_16x16x32_bf16 v[28:31], v[182:185], v[200:203], v[28:31]
	v_mfma_f32_16x16x32_bf16 v[20:23], v[174:177], v[208:211], v[20:23]
	v_mfma_f32_16x16x32_bf16 v[12:15], v[182:185], v[208:211], v[12:15]
	v_mfma_f32_16x16x32_bf16 v[4:7], v[174:177], v[216:219], v[4:7]
	v_mfma_f32_16x16x32_bf16 v[0:3], v[182:185], v[216:219], v[0:3]
	v_mfma_f32_16x16x32_bf16 v[52:55], v[178:181], v[196:199], v[52:55]
	v_mfma_f32_16x16x32_bf16 v[44:47], v[186:189], v[196:199], v[44:47]
	v_mfma_f32_16x16x32_bf16 v[36:39], v[178:181], v[204:207], v[36:39]
	v_mfma_f32_16x16x32_bf16 v[28:31], v[186:189], v[204:207], v[28:31]
	v_mfma_f32_16x16x32_bf16 v[20:23], v[178:181], v[212:215], v[20:23]
	v_mfma_f32_16x16x32_bf16 v[12:15], v[186:189], v[212:215], v[12:15]
	v_mfma_f32_16x16x32_bf16 v[4:7], v[178:181], v[220:223], v[4:7]
	v_mfma_f32_16x16x32_bf16 v[0:3], v[186:189], v[220:223], v[0:3]
	s_barrier
	s_add_i32 s65, s65, 2
	s_add_u32 s44, s44, 0x100
	s_addc_u32 s45, s45, 0
	s_add_u32 s63, s63, 0x100
	s_addc_u32 s64, s64, 0
	s_cmp_gt_u32 s65, 13
	s_cbranch_scc0 .LBB0_787
	s_and_b64 vcc, exec, s[12:13]
	s_cbranch_vccz .LBB0_790
	s_barrier

; #define PG8_STAGE_T(bufoff, gbase, voff, AUX) do { _Pragma("unroll") for (int _i = 0; _i < 2; ++_i) \
;         __builtin_amdgcn_global_load_lds((const unsigned*)((const char*)(gbase) + (voff)[_i]), (PG8_LAS unsigned*)(lds + (bufoff) + ldsw + _i * 8192), 16, 0, AUX); } while (0)
; #define PG8_LDA(dst, b, h) do { _Pragma("unroll") for (int m = 0; m < 4; ++m) _Pragma("unroll") for (int k = 0; k < 2; ++k) dst[m][k] = *(const PG8_LAS bf16x8*)(lds + PG8_SA(b, h) + aoff + m * 2048 + k * 1024); } while (0)
; #define PG8_LDB(dst, b, h) do { _Pragma("unroll") for (int n = 0; n < 2; ++n) _Pragma("unroll") for (int k = 0; k < 2; ++k) dst[n][k] = *(const PG8_LAS bf16x8*)(lds + PG8_SB(b, h) + boff + n * 2048 + k * 1024); } while (0)
; #define PG8_MMA(ai, bj, At, Bt) do { __builtin_amdgcn_s_setprio(1); _Pragma("unroll") for (int m = 0; m < 4; ++m) _Pragma("unroll") for (int n = 0; n < 2; ++n) _Pragma("unroll") for (int k = 0; k < 2; ++k) \
;         acc[ai][bj][m][n] = __builtin_amdgcn_mfma_f32_16x16x32_bf16(Bt[n][k], At[m][k], acc[ai][bj][m][n], 0, 0, 0); __builtin_amdgcn_s_setprio(0); } while (0)
; #define PG8_WAIT_V(n) asm volatile("s_waitcnt vmcnt(" #n ")" ::: "memory")
; #define PG8_WAIT_L(n) asm volatile("s_waitcnt lgkmcnt(" #n ")" ::: "memory")
; #define PG8_BAR __builtin_amdgcn_s_barrier()
; #define PG8_SCHED __builtin_amdgcn_sched_barrier(0)
;     ...
;             PG8_LDB(B0, 0, 0); PG8_LDB(B1, 0, 1); PG8_SCHED; PG8_LDA(At, 0, 0); if (!pe) { PG8_STAGE_T(PG8_SA(1, 1), a1 + hstep, voffA, AUX_A); }
;             if (!pe) { PG8_WAIT_V(8); } PG8_WAIT_L(0); PG8_BAR; PG8_MMA(0, 0, At, B0); PG8_MMA(0, 1, At, B1); PG8_BAR; PG8_SCHED;
;             PG8_LDA(At, 0, 1); PG8_STAGE_T(PG8_SB(0, 0), b2, voffB, AUX_B); PG8_STAGE_T(PG8_SB(0, 1), b2 + hstep, voffB, AUX_B); PG8_STAGE_T(PG8_SA(0, 0), a2, voffA, AUX_A);
;             if (!pe) { PG8_WAIT_V(8); } PG8_WAIT_L(0); PG8_BAR; PG8_MMA(1, 0, At, B0); PG8_MMA(1, 1, At, B1); PG8_BAR; PG8_SCHED;
.LBB0_811:
	ds_read_b128 v[128:131], v183
	ds_read_b128 v[132:135], v183 offset:1024
	ds_read_b128 v[136:139], v183 offset:2048
	ds_read_b128 v[140:143], v183 offset:3072
	ds_read_b128 v[144:147], v184
	ds_read_b128 v[148:151], v184 offset:1024
	ds_read_b128 v[168:171], v184 offset:2048
	ds_read_b128 v[172:175], v184 offset:3072
	s_add_u32 s48, s46, 0xfffc0080
	s_addc_u32 s49, s47, -1
	s_cmp_eq_u32 s67, 12
	s_cselect_b32 s51, s37, s49
	s_cselect_b32 s50, s63, s48
	s_cselect_b32 s49, s39, s66
	s_cselect_b32 s48, s64, s65
	v_lshl_add_u64 v[216:217], s[46:47], 0, v[160:161]
	s_add_i32 m0, s45, 0xc000
	ds_read_b128 v[176:179], v185
	ds_read_b128 v[186:189], v185 offset:1024
	ds_read_b128 v[190:193], v185 offset:2048
	ds_read_b128 v[196:199], v185 offset:3072
	ds_read_b128 v[200:203], v185 offset:4096
	ds_read_b128 v[204:207], v185 offset:5120
	ds_read_b128 v[208:211], v185 offset:6144
	ds_read_b128 v[212:215], v185 offset:7168
	global_load_lds_dwordx4 v[216:217], off
	v_lshl_add_u64 v[216:217], s[46:47], 0, v[162:163]
	s_add_i32 m0, s45, 0xe000
	s_nop 0
	global_load_lds_dwordx4 v[216:217], off
	s_waitcnt vmcnt(8)
	s_waitcnt lgkmcnt(0)
	s_barrier
	s_waitcnt lgkmcnt(0)
	v_mfma_f32_16x16x32_bf16 v[124:127], v[128:131], v[176:179], v[124:127]
	v_mfma_f32_16x16x32_bf16 v[120:123], v[136:139], v[176:179], v[120:123]
	v_mfma_f32_16x16x32_bf16 v[108:111], v[128:131], v[190:193], v[108:111]
	v_mfma_f32_16x16x32_bf16 v[104:107], v[136:139], v[190:193], v[104:107]
	v_mfma_f32_16x16x32_bf16 v[92:95], v[128:131], v[200:203], v[92:95]
	v_mfma_f32_16x16x32_bf16 v[88:91], v[136:139], v[200:203], v[88:91]
	v_mfma_f32_16x16x32_bf16 v[76:79], v[128:131], v[208:211], v[76:79]
	v_mfma_f32_16x16x32_bf16 v[72:75], v[136:139], v[208:211], v[72:75]
	v_mfma_f32_16x16x32_bf16 v[124:127], v[132:135], v[186:189], v[124:127]
	v_mfma_f32_16x16x32_bf16 v[120:123], v[140:143], v[186:189], v[120:123]
	v_mfma_f32_16x16x32_bf16 v[108:111], v[132:135], v[196:199], v[108:111]
	v_mfma_f32_16x16x32_bf16 v[104:107], v[140:143], v[196:199], v[104:107]
	v_mfma_f32_16x16x32_bf16 v[92:95], v[132:135], v[204:207], v[92:95]
	v_mfma_f32_16x16x32_bf16 v[88:91], v[140:143], v[204:207], v[88:91]
	v_mfma_f32_16x16x32_bf16 v[76:79], v[132:135], v[212:215], v[76:79]
	v_mfma_f32_16x16x32_bf16 v[72:75], v[140:143], v[212:215], v[72:75]
	v_mfma_f32_16x16x32_bf16 v[116:119], v[144:147], v[176:179], v[116:119]
	v_mfma_f32_16x16x32_bf16 v[112:115], v[168:171], v[176:179], v[112:115]
	v_mfma_f32_16x16x32_bf16 v[100:103], v[144:147], v[190:193], v[100:103]
	v_mfma_f32_16x16x32_bf16 v[96:99], v[168:171], v[190:193], v[96:99]
	v_mfma_f32_16x16x32_bf16 v[84:87], v[144:147], v[200:203], v[84:87]
	v_mfma_f32_16x16x32_bf16 v[80:83], v[168:171], v[200:203], v[80:83]
	v_mfma_f32_16x16x32_bf16 v[68:71], v[144:147], v[208:211], v[68:71]
	v_mfma_f32_16x16x32_bf16 v[64:67], v[168:171], v[208:211], v[64:67]
	v_mfma_f32_16x16x32_bf16 v[116:119], v[148:151], v[186:189], v[116:119]
	v_mfma_f32_16x16x32_bf16 v[112:115], v[172:175], v[186:189], v[112:115]
	v_mfma_f32_16x16x32_bf16 v[100:103], v[148:151], v[196:199], v[100:103]
	v_mfma_f32_16x16x32_bf16 v[96:99], v[172:175], v[196:199], v[96:99]
	v_mfma_f32_16x16x32_bf16 v[84:87], v[148:151], v[204:207], v[84:87]
	v_mfma_f32_16x16x32_bf16 v[80:83], v[172:175], v[204:207], v[80:83]
	v_mfma_f32_16x16x32_bf16 v[68:71], v[148:151], v[212:215], v[68:71]
	v_mfma_f32_16x16x32_bf16 v[64:67], v[172:175], v[212:215], v[64:67]
	s_barrier
	s_add_i32 s68, s60, s52
	v_lshl_add_u64 v[216:217], s[48:49], 0, v[154:155]
	s_mov_b32 m0, s68
	ds_read_b128 v[176:179], v185 offset:16384
	ds_read_b128 v[186:189], v185 offset:17408
	ds_read_b128 v[190:193], v185 offset:18432
	ds_read_b128 v[196:199], v185 offset:19456
	ds_read_b128 v[200:203], v185 offset:20480
	ds_read_b128 v[204:207], v185 offset:21504
	ds_read_b128 v[208:211], v185 offset:22528
	ds_read_b128 v[212:215], v185 offset:23552
	global_load_lds_dwordx4 v[216:217], off
	s_add_i32 m0, s68, 0x2000
	s_add_u32 s68, s48, 0x40000
	v_lshl_add_u64 v[218:219], s[48:49], 0, v[158:159]
	s_addc_u32 s69, s49, 0
	s_add_i32 s70, s61, s52
	global_load_lds_dwordx4 v[218:219], off
	v_lshl_add_u64 v[220:221], s[68:69], 0, v[154:155]
	s_mov_b32 m0, s70
	v_lshl_add_u64 v[222:223], s[50:51], 0, v[156:157]
	global_load_lds_dwordx4 v[220:221], off
	v_lshl_add_u64 v[220:221], s[68:69], 0, v[158:159]
	s_add_i32 m0, s70, 0x2000
	s_nop 0
	global_load_lds_dwordx4 v[220:221], off
	v_lshl_add_u64 v[220:221], s[50:51], 0, v[152:153]
	s_mov_b32 m0, s45
	s_nop 0
	global_load_lds_dwordx4 v[220:221], off
	s_mov_b32 m0, s53
	s_nop 0
	global_load_lds_dwordx4 v[222:223], off
	s_waitcnt vmcnt(8)
	s_waitcnt lgkmcnt(0)
	s_barrier
; #define PG8_STAGE_T(bufoff, gbase, voff, AUX) do { _Pragma("unroll") for (int _i = 0; _i < 2; ++_i) \
;         __builtin_amdgcn_global_load_lds((const unsigned*)((const char*)(gbase) + (voff)[_i]), (PG8_LAS unsigned*)(lds + (bufoff) + ldsw + _i * 8192), 16, 0, AUX); } while (0)
; #define PG8_LDA(dst, b, h) do { _Pragma("unroll") for (int m = 0; m < 4; ++m) _Pragma("unroll") for (int k = 0; k < 2; ++k) dst[m][k] = *(const PG8_LAS bf16x8*)(lds + PG8_SA(b, h) + aoff + m * 2048 + k * 1024); } while (0)
; #define PG8_LDB(dst, b, h) do { _Pragma("unroll") for (int n = 0; n < 2; ++n) _Pragma("unroll") for (int k = 0; k < 2; ++k) dst[n][k] = *(const PG8_LAS bf16x8*)(lds + PG8_SB(b, h) + boff + n * 2048 + k * 1024); } while (0)
; #define PG8_MMA(ai, bj, At, Bt) do { __builtin_amdgcn_s_setprio(1); _Pragma("unroll") for (int m = 0; m < 4; ++m) _Pragma("unroll") for (int n = 0; n < 2; ++n) _Pragma("unroll") for (int k = 0; k < 2; ++k) \
;         acc[ai][bj][m][n] = __builtin_amdgcn_mfma_f32_16x16x32_bf16(Bt[n][k], At[m][k], acc[ai][bj][m][n], 0, 0, 0); __builtin_amdgcn_s_setprio(0); } while (0)
; #define PG8_WAIT_V(n) asm volatile("s_waitcnt vmcnt(" #n ")" ::: "memory")
; #define PG8_WAIT_L(n) asm volatile("s_waitcnt lgkmcnt(" #n ")" ::: "memory")
; #define PG8_BAR __builtin_amdgcn_s_barrier()
; #define PG8_SCHED __builtin_amdgcn_sched_barrier(0)
;     ...
;             if (!pe) { PG8_WAIT_V(8); } PG8_WAIT_L(0); PG8_BAR; PG8_MMA(1, 0, At, B0); PG8_MMA(1, 1, At, B1); PG8_BAR; PG8_SCHED;
;             PG8_LDB(B0, 1, 0); PG8_LDB(B1, 1, 1); PG8_SCHED; PG8_LDA(At, 1, 0); PG8_STAGE_T(PG8_SA(0, 1), a2 + hstep, voffA, AUX_A);
;             if (!pe) { PG8_WAIT_V(8); } PG8_WAIT_L(0); PG8_BAR; PG8_MMA(0, 0, At, B0); PG8_MMA(0, 1, At, B1); PG8_BAR; PG8_SCHED;
	s_waitcnt lgkmcnt(0)
	v_mfma_f32_16x16x32_bf16 v[60:63], v[128:131], v[176:179], v[60:63]
	v_mfma_f32_16x16x32_bf16 v[56:59], v[136:139], v[176:179], v[56:59]
	v_mfma_f32_16x16x32_bf16 v[44:47], v[128:131], v[190:193], v[44:47]
	v_mfma_f32_16x16x32_bf16 v[40:43], v[136:139], v[190:193], v[40:43]
	v_mfma_f32_16x16x32_bf16 v[28:31], v[128:131], v[200:203], v[28:31]
	v_mfma_f32_16x16x32_bf16 v[24:27], v[136:139], v[200:203], v[24:27]
	v_mfma_f32_16x16x32_bf16 v[12:15], v[128:131], v[208:211], v[12:15]
	v_mfma_f32_16x16x32_bf16 v[8:11], v[136:139], v[208:211], v[8:11]
	v_mfma_f32_16x16x32_bf16 v[60:63], v[132:135], v[186:189], v[60:63]
	v_mfma_f32_16x16x32_bf16 v[56:59], v[140:143], v[186:189], v[56:59]
	v_mfma_f32_16x16x32_bf16 v[44:47], v[132:135], v[196:199], v[44:47]
	v_mfma_f32_16x16x32_bf16 v[40:43], v[140:143], v[196:199], v[40:43]
	v_mfma_f32_16x16x32_bf16 v[28:31], v[132:135], v[204:207], v[28:31]
	v_mfma_f32_16x16x32_bf16 v[24:27], v[140:143], v[204:207], v[24:27]
	v_mfma_f32_16x16x32_bf16 v[12:15], v[132:135], v[212:215], v[12:15]
	v_mfma_f32_16x16x32_bf16 v[8:11], v[140:143], v[212:215], v[8:11]
	v_mfma_f32_16x16x32_bf16 v[52:55], v[144:147], v[176:179], v[52:55]
	v_mfma_f32_16x16x32_bf16 v[48:51], v[168:171], v[176:179], v[48:51]
	v_mfma_f32_16x16x32_bf16 v[36:39], v[144:147], v[190:193], v[36:39]
	v_mfma_f32_16x16x32_bf16 v[32:35], v[168:171], v[190:193], v[32:35]
	v_mfma_f32_16x16x32_bf16 v[20:23], v[144:147], v[200:203], v[20:23]
	v_mfma_f32_16x16x32_bf16 v[16:19], v[168:171], v[200:203], v[16:19]
	v_mfma_f32_16x16x32_bf16 v[4:7], v[144:147], v[208:211], v[4:7]
	v_mfma_f32_16x16x32_bf16 v[0:3], v[168:171], v[208:211], v[0:3]
	v_mfma_f32_16x16x32_bf16 v[52:55], v[148:151], v[186:189], v[52:55]
	v_mfma_f32_16x16x32_bf16 v[48:51], v[172:175], v[186:189], v[48:51]
	v_mfma_f32_16x16x32_bf16 v[36:39], v[148:151], v[196:199], v[36:39]
	v_mfma_f32_16x16x32_bf16 v[32:35], v[172:175], v[196:199], v[32:35]
	v_mfma_f32_16x16x32_bf16 v[20:23], v[148:151], v[204:207], v[20:23]
	v_mfma_f32_16x16x32_bf16 v[16:19], v[172:175], v[204:207], v[16:19]
	v_mfma_f32_16x16x32_bf16 v[4:7], v[148:151], v[212:215], v[4:7]
	v_mfma_f32_16x16x32_bf16 v[0:3], v[172:175], v[212:215], v[0:3]
	s_barrier
	s_add_i32 s68, 0, 0x18000
	s_add_i32 s69, 0, 0x1c000
	v_add_u32_e32 v140, s68, v181
	v_add_u32_e32 v172, s69, v181
	ds_read_b128 v[128:131], v140
	ds_read_b128 v[132:135], v140 offset:1024
	ds_read_b128 v[136:139], v140 offset:2048
	ds_read_b128 v[140:143], v140 offset:3072
	ds_read_b128 v[144:147], v172
	ds_read_b128 v[148:151], v172 offset:1024
	ds_read_b128 v[168:171], v172 offset:2048
	ds_read_b128 v[172:175], v172 offset:3072
	s_add_u32 s50, s50, 0x40000
	s_addc_u32 s51, s51, 0
	s_mov_b32 m0, s54
	v_lshl_add_u64 v[224:225], s[50:51], 0, v[152:153]
	ds_read_b128 v[176:179], v185 offset:32768
	ds_read_b128 v[186:189], v185 offset:33792
	ds_read_b128 v[190:193], v185 offset:34816
	ds_read_b128 v[196:199], v185 offset:35840
	ds_read_b128 v[200:203], v185 offset:36864
	ds_read_b128 v[204:207], v185 offset:37888
	ds_read_b128 v[208:211], v185 offset:38912
	ds_read_b128 v[212:215], v185 offset:39936
	global_load_lds_dwordx4 v[224:225], off
	v_lshl_add_u64 v[224:225], s[50:51], 0, v[156:157]
	s_mov_b32 m0, s55
	s_nop 0
	global_load_lds_dwordx4 v[224:225], off
	s_waitcnt vmcnt(8)
	s_waitcnt lgkmcnt(0)
	s_barrier
	s_waitcnt lgkmcnt(0)
	v_mfma_f32_16x16x32_bf16 v[124:127], v[128:131], v[176:179], v[124:127]
	v_mfma_f32_16x16x32_bf16 v[120:123], v[136:139], v[176:179], v[120:123]
	v_mfma_f32_16x16x32_bf16 v[108:111], v[128:131], v[190:193], v[108:111]
	v_mfma_f32_16x16x32_bf16 v[104:107], v[136:139], v[190:193], v[104:107]
	v_mfma_f32_16x16x32_bf16 v[92:95], v[128:131], v[200:203], v[92:95]
	v_mfma_f32_16x16x32_bf16 v[88:91], v[136:139], v[200:203], v[88:91]
	v_mfma_f32_16x16x32_bf16 v[76:79], v[128:131], v[208:211], v[76:79]
	v_mfma_f32_16x16x32_bf16 v[72:75], v[136:139], v[208:211], v[72:75]
	v_mfma_f32_16x16x32_bf16 v[124:127], v[132:135], v[186:189], v[124:127]
	v_mfma_f32_16x16x32_bf16 v[120:123], v[140:143], v[186:189], v[120:123]
	v_mfma_f32_16x16x32_bf16 v[108:111], v[132:135], v[196:199], v[108:111]
	v_mfma_f32_16x16x32_bf16 v[104:107], v[140:143], v[196:199], v[104:107]
	v_mfma_f32_16x16x32_bf16 v[92:95], v[132:135], v[204:207], v[92:95]
	v_mfma_f32_16x16x32_bf16 v[88:91], v[140:143], v[204:207], v[88:91]
	v_mfma_f32_16x16x32_bf16 v[76:79], v[132:135], v[212:215], v[76:79]
	v_mfma_f32_16x16x32_bf16 v[72:75], v[140:143], v[212:215], v[72:75]
	v_mfma_f32_16x16x32_bf16 v[116:119], v[144:147], v[176:179], v[116:119]
	v_mfma_f32_16x16x32_bf16 v[112:115], v[168:171], v[176:179], v[112:115]
	v_mfma_f32_16x16x32_bf16 v[100:103], v[144:147], v[190:193], v[100:103]
	v_mfma_f32_16x16x32_bf16 v[96:99], v[168:171], v[190:193], v[96:99]
	v_mfma_f32_16x16x32_bf16 v[84:87], v[144:147], v[200:203], v[84:87]
	v_mfma_f32_16x16x32_bf16 v[80:83], v[168:171], v[200:203], v[80:83]
	v_mfma_f32_16x16x32_bf16 v[68:71], v[144:147], v[208:211], v[68:71]
	v_mfma_f32_16x16x32_bf16 v[64:67], v[168:171], v[208:211], v[64:67]
	v_mfma_f32_16x16x32_bf16 v[116:119], v[148:151], v[186:189], v[116:119]
	v_mfma_f32_16x16x32_bf16 v[112:115], v[172:175], v[186:189], v[112:115]
	v_mfma_f32_16x16x32_bf16 v[100:103], v[148:151], v[196:199], v[100:103]
	v_mfma_f32_16x16x32_bf16 v[96:99], v[172:175], v[196:199], v[96:99]
	v_mfma_f32_16x16x32_bf16 v[84:87], v[148:151], v[204:207], v[84:87]
	v_mfma_f32_16x16x32_bf16 v[80:83], v[172:175], v[204:207], v[80:83]
	v_mfma_f32_16x16x32_bf16 v[68:71], v[148:151], v[212:215], v[68:71]
	v_mfma_f32_16x16x32_bf16 v[64:67], v[172:175], v[212:215], v[64:67]
	s_barrier
; #define PG8_STAGE_T(bufoff, gbase, voff, AUX) do { _Pragma("unroll") for (int _i = 0; _i < 2; ++_i) \
;         __builtin_amdgcn_global_load_lds((const unsigned*)((const char*)(gbase) + (voff)[_i]), (PG8_LAS unsigned*)(lds + (bufoff) + ldsw + _i * 8192), 16, 0, AUX); } while (0)
; #define PG8_LDA(dst, b, h) do { _Pragma("unroll") for (int m = 0; m < 4; ++m) _Pragma("unroll") for (int k = 0; k < 2; ++k) dst[m][k] = *(const PG8_LAS bf16x8*)(lds + PG8_SA(b, h) + aoff + m * 2048 + k * 1024); } while (0)
; #define PG8_MMA(ai, bj, At, Bt) do { __builtin_amdgcn_s_setprio(1); _Pragma("unroll") for (int m = 0; m < 4; ++m) _Pragma("unroll") for (int n = 0; n < 2; ++n) _Pragma("unroll") for (int k = 0; k < 2; ++k) \
;         acc[ai][bj][m][n] = __builtin_amdgcn_mfma_f32_16x16x32_bf16(Bt[n][k], At[m][k], acc[ai][bj][m][n], 0, 0, 0); __builtin_amdgcn_s_setprio(0); } while (0)
; #define PG8_WAIT_V(n) asm volatile("s_waitcnt vmcnt(" #n ")" ::: "memory")
; #define PG8_WAIT_L(n) asm volatile("s_waitcnt lgkmcnt(" #n ")" ::: "memory")
; #define PG8_BAR __builtin_amdgcn_s_barrier()
; #define PG8_SCHED __builtin_amdgcn_sched_barrier(0)
;     ...
;             PG8_LDA(At, 1, 1); PG8_STAGE_T(PG8_SB(1, 0), b3, voffB, AUX_B); PG8_STAGE_T(PG8_SB(1, 1), b3 + hstep, voffB, AUX_B); PG8_STAGE_T(PG8_SA(1, 0), a3, voffA, AUX_A);
;             PG8_WAIT_V(8); PG8_WAIT_L(0); PG8_BAR; PG8_MMA(1, 0, At, B0); PG8_MMA(1, 1, At, B1); PG8_BAR; PG8_SCHED;
	s_add_i32 s50, s68, s52
	v_lshl_add_u64 v[216:217], v[216:217], 0, s[10:11]
	s_mov_b32 m0, s50
	ds_read_b128 v[176:179], v185 offset:49152
	ds_read_b128 v[186:189], v185 offset:50176
	ds_read_b128 v[190:193], v185 offset:51200
	ds_read_b128 v[196:199], v185 offset:52224
	ds_read_b128 v[200:203], v185 offset:53248
	ds_read_b128 v[204:207], v185 offset:54272
	ds_read_b128 v[208:211], v185 offset:55296
	ds_read_b128 v[212:215], v185 offset:56320
	global_load_lds_dwordx4 v[216:217], off
	s_add_i32 m0, s50, 0x2000
	s_add_u32 s48, s48, 0x40080
	v_lshl_add_u64 v[216:217], v[218:219], 0, s[10:11]
	s_addc_u32 s49, s49, 0
	s_add_i32 s50, s69, s52
	global_load_lds_dwordx4 v[216:217], off
	v_lshl_add_u64 v[216:217], s[48:49], 0, v[154:155]
	s_mov_b32 m0, s50
	s_nop 0
	global_load_lds_dwordx4 v[216:217], off
	v_lshl_add_u64 v[216:217], s[48:49], 0, v[158:159]
	s_add_i32 m0, s50, 0x2000
	s_nop 0
	global_load_lds_dwordx4 v[216:217], off
	v_lshl_add_u64 v[216:217], v[220:221], 0, s[10:11]
	s_mov_b32 m0, s57
	s_nop 0
	global_load_lds_dwordx4 v[216:217], off
	v_lshl_add_u64 v[216:217], v[222:223], 0, s[10:11]
	s_mov_b32 m0, s58
	s_nop 0
	global_load_lds_dwordx4 v[216:217], off
	s_waitcnt vmcnt(8)
	s_waitcnt lgkmcnt(0)
	s_barrier
	s_waitcnt lgkmcnt(0)
	v_mfma_f32_16x16x32_bf16 v[60:63], v[128:131], v[176:179], v[60:63]
	v_mfma_f32_16x16x32_bf16 v[56:59], v[136:139], v[176:179], v[56:59]
	v_mfma_f32_16x16x32_bf16 v[44:47], v[128:131], v[190:193], v[44:47]
	v_mfma_f32_16x16x32_bf16 v[40:43], v[136:139], v[190:193], v[40:43]
	v_mfma_f32_16x16x32_bf16 v[28:31], v[128:131], v[200:203], v[28:31]
	v_mfma_f32_16x16x32_bf16 v[24:27], v[136:139], v[200:203], v[24:27]
	v_mfma_f32_16x16x32_bf16 v[12:15], v[128:131], v[208:211], v[12:15]
	v_mfma_f32_16x16x32_bf16 v[8:11], v[136:139], v[208:211], v[8:11]
	v_mfma_f32_16x16x32_bf16 v[60:63], v[132:135], v[186:189], v[60:63]
	v_mfma_f32_16x16x32_bf16 v[56:59], v[140:143], v[186:189], v[56:59]
	v_mfma_f32_16x16x32_bf16 v[44:47], v[132:135], v[196:199], v[44:47]
	v_mfma_f32_16x16x32_bf16 v[40:43], v[140:143], v[196:199], v[40:43]
	v_mfma_f32_16x16x32_bf16 v[28:31], v[132:135], v[204:207], v[28:31]
	v_mfma_f32_16x16x32_bf16 v[24:27], v[140:143], v[204:207], v[24:27]
	v_mfma_f32_16x16x32_bf16 v[12:15], v[132:135], v[212:215], v[12:15]
	v_mfma_f32_16x16x32_bf16 v[8:11], v[140:143], v[212:215], v[8:11]
	v_mfma_f32_16x16x32_bf16 v[52:55], v[144:147], v[176:179], v[52:55]
	v_mfma_f32_16x16x32_bf16 v[48:51], v[168:171], v[176:179], v[48:51]
	v_mfma_f32_16x16x32_bf16 v[36:39], v[144:147], v[190:193], v[36:39]
	v_mfma_f32_16x16x32_bf16 v[32:35], v[168:171], v[190:193], v[32:35]
	v_mfma_f32_16x16x32_bf16 v[20:23], v[144:147], v[200:203], v[20:23]
	v_mfma_f32_16x16x32_bf16 v[16:19], v[168:171], v[200:203], v[16:19]
	v_mfma_f32_16x16x32_bf16 v[4:7], v[144:147], v[208:211], v[4:7]
	v_mfma_f32_16x16x32_bf16 v[0:3], v[168:171], v[208:211], v[0:3]
	v_mfma_f32_16x16x32_bf16 v[52:55], v[148:151], v[186:189], v[52:55]
	v_mfma_f32_16x16x32_bf16 v[48:51], v[172:175], v[186:189], v[48:51]
	v_mfma_f32_16x16x32_bf16 v[36:39], v[148:151], v[196:199], v[36:39]
	v_mfma_f32_16x16x32_bf16 v[32:35], v[172:175], v[196:199], v[32:35]
	v_mfma_f32_16x16x32_bf16 v[20:23], v[148:151], v[204:207], v[20:23]
	v_mfma_f32_16x16x32_bf16 v[16:19], v[172:175], v[204:207], v[16:19]
	v_mfma_f32_16x16x32_bf16 v[4:7], v[148:151], v[212:215], v[4:7]
	v_mfma_f32_16x16x32_bf16 v[0:3], v[172:175], v[212:215], v[0:3]
	s_barrier
	s_add_i32 s67, s67, 2
	s_add_u32 s46, s46, 0x100
	s_addc_u32 s47, s47, 0
	s_add_u32 s65, s65, 0x100
	s_addc_u32 s66, s66, 0
	s_cmp_gt_u32 s67, 13
	s_cbranch_scc0 .LBB0_811
	s_and_b64 vcc, exec, s[12:13]
	s_cbranch_vccz .LBB0_814
	s_barrier

; #define PG8_STAGE_T(bufoff, gbase, voff, AUX) do { _Pragma("unroll") for (int _i = 0; _i < 2; ++_i) \
;         __builtin_amdgcn_global_load_lds((const unsigned*)((const char*)(gbase) + (voff)[_i]), (PG8_LAS unsigned*)(lds + (bufoff) + ldsw + _i * 8192), 16, 0, AUX); } while (0)
; #define PG8_LDA(dst, b, h) do { _Pragma("unroll") for (int m = 0; m < 4; ++m) _Pragma("unroll") for (int k = 0; k < 2; ++k) dst[m][k] = *(const PG8_LAS bf16x8*)(lds + PG8_SA(b, h) + aoff + m * 2048 + k * 1024); } while (0)
; #define PG8_LDB(dst, b, h) do { _Pragma("unroll") for (int n = 0; n < 2; ++n) _Pragma("unroll") for (int k = 0; k < 2; ++k) dst[n][k] = *(const PG8_LAS bf16x8*)(lds + PG8_SB(b, h) + boff + n * 2048 + k * 1024); } while (0)
; #define PG8_MMA(ai, bj, At, Bt) do { __builtin_amdgcn_s_setprio(1); _Pragma("unroll") for (int m = 0; m < 4; ++m) _Pragma("unroll") for (int n = 0; n < 2; ++n) _Pragma("unroll") for (int k = 0; k < 2; ++k) \
;         acc[ai][bj][m][n] = __builtin_amdgcn_mfma_f32_16x16x32_bf16(Bt[n][k], At[m][k], acc[ai][bj][m][n], 0, 0, 0); __builtin_amdgcn_s_setprio(0); } while (0)
; #define PG8_WAIT_V(n) asm volatile("s_waitcnt vmcnt(" #n ")" ::: "memory")
; #define PG8_WAIT_L(n) asm volatile("s_waitcnt lgkmcnt(" #n ")" ::: "memory")
; #define PG8_BAR __builtin_amdgcn_s_barrier()
; #define PG8_SCHED __builtin_amdgcn_sched_barrier(0)
;     ...
;             PG8_LDB(B0, 0, 0); PG8_LDB(B1, 0, 1); PG8_SCHED; PG8_LDA(At, 0, 0); if (!pe) { PG8_STAGE_T(PG8_SA(1, 1), a1 + hstep, voffA, AUX_A); }
;             if (!pe) { PG8_WAIT_V(8); } PG8_WAIT_L(0); PG8_BAR; PG8_MMA(0, 0, At, B0); PG8_MMA(0, 1, At, B1); PG8_BAR; PG8_SCHED;
;             PG8_LDA(At, 0, 1); PG8_STAGE_T(PG8_SB(0, 0), b2, voffB, AUX_B); PG8_STAGE_T(PG8_SB(0, 1), b2 + hstep, voffB, AUX_B); PG8_STAGE_T(PG8_SA(0, 0), a2, voffA, AUX_A);
;             if (!pe) { PG8_WAIT_V(8); } PG8_WAIT_L(0); PG8_BAR; PG8_MMA(1, 0, At, B0); PG8_MMA(1, 1, At, B1); PG8_BAR; PG8_SCHED;
.LBB0_886:
	ds_read_b128 v[154:157], v149
	s_waitcnt lgkmcnt(0)
	ds_read_b128 v[158:161], v149 offset:1024
	ds_read_b128 v[162:165], v149 offset:2048
	ds_read_b128 v[166:169], v149 offset:3072
	ds_read_b128 v[170:173], v150
	ds_read_b128 v[174:177], v150 offset:1024
	ds_read_b128 v[178:181], v150 offset:2048
	ds_read_b128 v[182:185], v150 offset:3072
	s_add_u32 s44, s42, 0xfffc0080
	s_addc_u32 s45, s43, -1
	s_cmp_eq_u32 s63, 12
	s_cselect_b32 s47, s15, s45
	s_cselect_b32 s46, s59, s44
	s_cselect_b32 s45, s25, s62
	s_cselect_b32 s44, s60, s61
	v_lshl_add_u64 v[144:145], s[42:43], 0, v[136:137]
	s_add_i32 m0, s49, 0xc000
	ds_read_b128 v[186:189], v151
	ds_read_b128 v[190:193], v151 offset:1024
	ds_read_b128 v[196:199], v151 offset:2048
	ds_read_b128 v[200:203], v151 offset:3072
	ds_read_b128 v[204:207], v151 offset:4096
	ds_read_b128 v[208:211], v151 offset:5120
	ds_read_b128 v[212:215], v151 offset:6144
	ds_read_b128 v[216:219], v151 offset:7168
	global_load_lds_dwordx4 v[144:145], off
	v_lshl_add_u64 v[144:145], s[42:43], 0, v[138:139]
	s_add_i32 m0, s49, 0xe000
	s_nop 0
	global_load_lds_dwordx4 v[144:145], off
	s_waitcnt vmcnt(8)
	s_waitcnt lgkmcnt(0)
	s_barrier
	s_waitcnt lgkmcnt(0)
	v_mfma_f32_16x16x32_bf16 v[124:127], v[154:157], v[186:189], v[124:127]
	v_mfma_f32_16x16x32_bf16 v[120:123], v[162:165], v[186:189], v[120:123]
	v_mfma_f32_16x16x32_bf16 v[108:111], v[154:157], v[196:199], v[108:111]
	v_mfma_f32_16x16x32_bf16 v[104:107], v[162:165], v[196:199], v[104:107]
	v_mfma_f32_16x16x32_bf16 v[92:95], v[154:157], v[204:207], v[92:95]
	v_mfma_f32_16x16x32_bf16 v[88:91], v[162:165], v[204:207], v[88:91]
	v_mfma_f32_16x16x32_bf16 v[76:79], v[154:157], v[212:215], v[76:79]
	v_mfma_f32_16x16x32_bf16 v[72:75], v[162:165], v[212:215], v[72:75]
	v_mfma_f32_16x16x32_bf16 v[124:127], v[158:161], v[190:193], v[124:127]
	v_mfma_f32_16x16x32_bf16 v[120:123], v[166:169], v[190:193], v[120:123]
	v_mfma_f32_16x16x32_bf16 v[108:111], v[158:161], v[200:203], v[108:111]
	v_mfma_f32_16x16x32_bf16 v[104:107], v[166:169], v[200:203], v[104:107]
	v_mfma_f32_16x16x32_bf16 v[92:95], v[158:161], v[208:211], v[92:95]
	v_mfma_f32_16x16x32_bf16 v[88:91], v[166:169], v[208:211], v[88:91]
	v_mfma_f32_16x16x32_bf16 v[76:79], v[158:161], v[216:219], v[76:79]
	v_mfma_f32_16x16x32_bf16 v[72:75], v[166:169], v[216:219], v[72:75]
	v_mfma_f32_16x16x32_bf16 v[116:119], v[170:173], v[186:189], v[116:119]
	v_mfma_f32_16x16x32_bf16 v[112:115], v[178:181], v[186:189], v[112:115]
	v_mfma_f32_16x16x32_bf16 v[100:103], v[170:173], v[196:199], v[100:103]
	v_mfma_f32_16x16x32_bf16 v[96:99], v[178:181], v[196:199], v[96:99]
	v_mfma_f32_16x16x32_bf16 v[84:87], v[170:173], v[204:207], v[84:87]
	v_mfma_f32_16x16x32_bf16 v[80:83], v[178:181], v[204:207], v[80:83]
	v_mfma_f32_16x16x32_bf16 v[68:71], v[170:173], v[212:215], v[68:71]
	v_mfma_f32_16x16x32_bf16 v[64:67], v[178:181], v[212:215], v[64:67]
	v_mfma_f32_16x16x32_bf16 v[116:119], v[174:177], v[190:193], v[116:119]
	v_mfma_f32_16x16x32_bf16 v[112:115], v[182:185], v[190:193], v[112:115]
	v_mfma_f32_16x16x32_bf16 v[100:103], v[174:177], v[200:203], v[100:103]
	v_mfma_f32_16x16x32_bf16 v[96:99], v[182:185], v[200:203], v[96:99]
	v_mfma_f32_16x16x32_bf16 v[84:87], v[174:177], v[208:211], v[84:87]
	v_mfma_f32_16x16x32_bf16 v[80:83], v[182:185], v[208:211], v[80:83]
	v_mfma_f32_16x16x32_bf16 v[68:71], v[174:177], v[216:219], v[68:71]
	v_mfma_f32_16x16x32_bf16 v[64:67], v[182:185], v[216:219], v[64:67]
	s_barrier
	s_add_i32 s64, s56, s48
	v_lshl_add_u64 v[144:145], s[44:45], 0, v[130:131]
	s_mov_b32 m0, s64
	ds_read_b128 v[186:189], v151 offset:16384
	ds_read_b128 v[190:193], v151 offset:17408
	ds_read_b128 v[196:199], v151 offset:18432
	ds_read_b128 v[200:203], v151 offset:19456
	ds_read_b128 v[204:207], v151 offset:20480
	ds_read_b128 v[208:211], v151 offset:21504
	ds_read_b128 v[212:215], v151 offset:22528
	ds_read_b128 v[216:219], v151 offset:23552
	global_load_lds_dwordx4 v[144:145], off
	s_add_i32 m0, s64, 0x2000
	s_add_u32 s64, s44, 0x40000
	v_lshl_add_u64 v[220:221], s[44:45], 0, v[134:135]
	s_addc_u32 s65, s45, 0
	s_add_i32 s66, s57, s48
	global_load_lds_dwordx4 v[220:221], off
	v_lshl_add_u64 v[222:223], s[64:65], 0, v[130:131]
	s_mov_b32 m0, s66
	v_lshl_add_u64 v[224:225], s[46:47], 0, v[132:133]
	global_load_lds_dwordx4 v[222:223], off
	v_lshl_add_u64 v[222:223], s[64:65], 0, v[134:135]
	s_add_i32 m0, s66, 0x2000
	s_nop 0
	global_load_lds_dwordx4 v[222:223], off
	v_lshl_add_u64 v[222:223], s[46:47], 0, v[128:129]
	s_mov_b32 m0, s49
	s_nop 0
	global_load_lds_dwordx4 v[222:223], off
	s_mov_b32 m0, s50
	s_nop 0
	global_load_lds_dwordx4 v[224:225], off
	s_waitcnt vmcnt(8)
	s_waitcnt lgkmcnt(0)
	s_barrier
; #define PG8_STAGE_T(bufoff, gbase, voff, AUX) do { _Pragma("unroll") for (int _i = 0; _i < 2; ++_i) \
;         __builtin_amdgcn_global_load_lds((const unsigned*)((const char*)(gbase) + (voff)[_i]), (PG8_LAS unsigned*)(lds + (bufoff) + ldsw + _i * 8192), 16, 0, AUX); } while (0)
; #define PG8_LDA(dst, b, h) do { _Pragma("unroll") for (int m = 0; m < 4; ++m) _Pragma("unroll") for (int k = 0; k < 2; ++k) dst[m][k] = *(const PG8_LAS bf16x8*)(lds + PG8_SA(b, h) + aoff + m * 2048 + k * 1024); } while (0)
; #define PG8_LDB(dst, b, h) do { _Pragma("unroll") for (int n = 0; n < 2; ++n) _Pragma("unroll") for (int k = 0; k < 2; ++k) dst[n][k] = *(const PG8_LAS bf16x8*)(lds + PG8_SB(b, h) + boff + n * 2048 + k * 1024); } while (0)
; #define PG8_MMA(ai, bj, At, Bt) do { __builtin_amdgcn_s_setprio(1); _Pragma("unroll") for (int m = 0; m < 4; ++m) _Pragma("unroll") for (int n = 0; n < 2; ++n) _Pragma("unroll") for (int k = 0; k < 2; ++k) \
;         acc[ai][bj][m][n] = __builtin_amdgcn_mfma_f32_16x16x32_bf16(Bt[n][k], At[m][k], acc[ai][bj][m][n], 0, 0, 0); __builtin_amdgcn_s_setprio(0); } while (0)
; #define PG8_WAIT_V(n) asm volatile("s_waitcnt vmcnt(" #n ")" ::: "memory")
; #define PG8_WAIT_L(n) asm volatile("s_waitcnt lgkmcnt(" #n ")" ::: "memory")
; #define PG8_BAR __builtin_amdgcn_s_barrier()
; #define PG8_SCHED __builtin_amdgcn_sched_barrier(0)
;     ...
;             if (!pe) { PG8_WAIT_V(8); } PG8_WAIT_L(0); PG8_BAR; PG8_MMA(1, 0, At, B0); PG8_MMA(1, 1, At, B1); PG8_BAR; PG8_SCHED;
;             PG8_LDB(B0, 1, 0); PG8_LDB(B1, 1, 1); PG8_SCHED; PG8_LDA(At, 1, 0); PG8_STAGE_T(PG8_SA(0, 1), a2 + hstep, voffA, AUX_A);
;             if (!pe) { PG8_WAIT_V(8); } PG8_WAIT_L(0); PG8_BAR; PG8_MMA(0, 0, At, B0); PG8_MMA(0, 1, At, B1); PG8_BAR; PG8_SCHED;
	s_waitcnt lgkmcnt(0)
	v_mfma_f32_16x16x32_bf16 v[60:63], v[154:157], v[186:189], v[60:63]
	v_mfma_f32_16x16x32_bf16 v[56:59], v[162:165], v[186:189], v[56:59]
	v_mfma_f32_16x16x32_bf16 v[44:47], v[154:157], v[196:199], v[44:47]
	v_mfma_f32_16x16x32_bf16 v[40:43], v[162:165], v[196:199], v[40:43]
	v_mfma_f32_16x16x32_bf16 v[28:31], v[154:157], v[204:207], v[28:31]
	v_mfma_f32_16x16x32_bf16 v[24:27], v[162:165], v[204:207], v[24:27]
	v_mfma_f32_16x16x32_bf16 v[12:15], v[154:157], v[212:215], v[12:15]
	v_mfma_f32_16x16x32_bf16 v[8:11], v[162:165], v[212:215], v[8:11]
	v_mfma_f32_16x16x32_bf16 v[60:63], v[158:161], v[190:193], v[60:63]
	v_mfma_f32_16x16x32_bf16 v[56:59], v[166:169], v[190:193], v[56:59]
	v_mfma_f32_16x16x32_bf16 v[44:47], v[158:161], v[200:203], v[44:47]
	v_mfma_f32_16x16x32_bf16 v[40:43], v[166:169], v[200:203], v[40:43]
	v_mfma_f32_16x16x32_bf16 v[28:31], v[158:161], v[208:211], v[28:31]
	v_mfma_f32_16x16x32_bf16 v[24:27], v[166:169], v[208:211], v[24:27]
	v_mfma_f32_16x16x32_bf16 v[12:15], v[158:161], v[216:219], v[12:15]
	v_mfma_f32_16x16x32_bf16 v[8:11], v[166:169], v[216:219], v[8:11]
	v_mfma_f32_16x16x32_bf16 v[52:55], v[170:173], v[186:189], v[52:55]
	v_mfma_f32_16x16x32_bf16 v[48:51], v[178:181], v[186:189], v[48:51]
	v_mfma_f32_16x16x32_bf16 v[36:39], v[170:173], v[196:199], v[36:39]
	v_mfma_f32_16x16x32_bf16 v[32:35], v[178:181], v[196:199], v[32:35]
	v_mfma_f32_16x16x32_bf16 v[20:23], v[170:173], v[204:207], v[20:23]
	v_mfma_f32_16x16x32_bf16 v[16:19], v[178:181], v[204:207], v[16:19]
	v_mfma_f32_16x16x32_bf16 v[4:7], v[170:173], v[212:215], v[4:7]
	v_mfma_f32_16x16x32_bf16 v[0:3], v[178:181], v[212:215], v[0:3]
	v_mfma_f32_16x16x32_bf16 v[52:55], v[174:177], v[190:193], v[52:55]
	v_mfma_f32_16x16x32_bf16 v[48:51], v[182:185], v[190:193], v[48:51]
	v_mfma_f32_16x16x32_bf16 v[36:39], v[174:177], v[200:203], v[36:39]
	v_mfma_f32_16x16x32_bf16 v[32:35], v[182:185], v[200:203], v[32:35]
	v_mfma_f32_16x16x32_bf16 v[20:23], v[174:177], v[208:211], v[20:23]
	v_mfma_f32_16x16x32_bf16 v[16:19], v[182:185], v[208:211], v[16:19]
	v_mfma_f32_16x16x32_bf16 v[4:7], v[174:177], v[216:219], v[4:7]
	v_mfma_f32_16x16x32_bf16 v[0:3], v[182:185], v[216:219], v[0:3]
	s_barrier
	s_add_i32 s64, 0, 0x18000
	v_add_u32_e32 v153, s64, v147
	s_add_i32 s65, 0, 0x1c000
	ds_read_b128 v[154:157], v153
	ds_read_b128 v[158:161], v153 offset:1024
	ds_read_b128 v[162:165], v153 offset:2048
	ds_read_b128 v[166:169], v153 offset:3072
	v_add_u32_e32 v153, s65, v147
	ds_read_b128 v[170:173], v153
	ds_read_b128 v[174:177], v153 offset:1024
	ds_read_b128 v[178:181], v153 offset:2048
	ds_read_b128 v[182:185], v153 offset:3072
	s_add_u32 s46, s46, 0x40000
	s_addc_u32 s47, s47, 0
	s_mov_b32 m0, s51
	v_lshl_add_u64 v[226:227], s[46:47], 0, v[128:129]
	ds_read_b128 v[186:189], v151 offset:32768
	ds_read_b128 v[190:193], v151 offset:33792
	ds_read_b128 v[196:199], v151 offset:34816
	ds_read_b128 v[200:203], v151 offset:35840
	ds_read_b128 v[204:207], v151 offset:36864
	ds_read_b128 v[208:211], v151 offset:37888
	ds_read_b128 v[212:215], v151 offset:38912
	ds_read_b128 v[216:219], v151 offset:39936
	global_load_lds_dwordx4 v[226:227], off
	v_lshl_add_u64 v[226:227], s[46:47], 0, v[132:133]
	s_mov_b32 m0, s52
	s_nop 0
	global_load_lds_dwordx4 v[226:227], off
	s_waitcnt vmcnt(8)
	s_waitcnt lgkmcnt(0)
	s_barrier
	s_waitcnt lgkmcnt(0)
	v_mfma_f32_16x16x32_bf16 v[124:127], v[154:157], v[186:189], v[124:127]
	v_mfma_f32_16x16x32_bf16 v[120:123], v[162:165], v[186:189], v[120:123]
	v_mfma_f32_16x16x32_bf16 v[108:111], v[154:157], v[196:199], v[108:111]
	v_mfma_f32_16x16x32_bf16 v[104:107], v[162:165], v[196:199], v[104:107]
	v_mfma_f32_16x16x32_bf16 v[92:95], v[154:157], v[204:207], v[92:95]
	v_mfma_f32_16x16x32_bf16 v[88:91], v[162:165], v[204:207], v[88:91]
	v_mfma_f32_16x16x32_bf16 v[76:79], v[154:157], v[212:215], v[76:79]
	v_mfma_f32_16x16x32_bf16 v[72:75], v[162:165], v[212:215], v[72:75]
	v_mfma_f32_16x16x32_bf16 v[124:127], v[158:161], v[190:193], v[124:127]
	v_mfma_f32_16x16x32_bf16 v[120:123], v[166:169], v[190:193], v[120:123]
	v_mfma_f32_16x16x32_bf16 v[108:111], v[158:161], v[200:203], v[108:111]
	v_mfma_f32_16x16x32_bf16 v[104:107], v[166:169], v[200:203], v[104:107]
	v_mfma_f32_16x16x32_bf16 v[92:95], v[158:161], v[208:211], v[92:95]
	v_mfma_f32_16x16x32_bf16 v[88:91], v[166:169], v[208:211], v[88:91]
	v_mfma_f32_16x16x32_bf16 v[76:79], v[158:161], v[216:219], v[76:79]
	v_mfma_f32_16x16x32_bf16 v[72:75], v[166:169], v[216:219], v[72:75]
	v_mfma_f32_16x16x32_bf16 v[116:119], v[170:173], v[186:189], v[116:119]
	v_mfma_f32_16x16x32_bf16 v[112:115], v[178:181], v[186:189], v[112:115]
	v_mfma_f32_16x16x32_bf16 v[100:103], v[170:173], v[196:199], v[100:103]
	v_mfma_f32_16x16x32_bf16 v[96:99], v[178:181], v[196:199], v[96:99]
	v_mfma_f32_16x16x32_bf16 v[84:87], v[170:173], v[204:207], v[84:87]
	v_mfma_f32_16x16x32_bf16 v[80:83], v[178:181], v[204:207], v[80:83]
	v_mfma_f32_16x16x32_bf16 v[68:71], v[170:173], v[212:215], v[68:71]
	v_mfma_f32_16x16x32_bf16 v[64:67], v[178:181], v[212:215], v[64:67]
	v_mfma_f32_16x16x32_bf16 v[116:119], v[174:177], v[190:193], v[116:119]
	v_mfma_f32_16x16x32_bf16 v[112:115], v[182:185], v[190:193], v[112:115]
	v_mfma_f32_16x16x32_bf16 v[100:103], v[174:177], v[200:203], v[100:103]
	v_mfma_f32_16x16x32_bf16 v[96:99], v[182:185], v[200:203], v[96:99]
	v_mfma_f32_16x16x32_bf16 v[84:87], v[174:177], v[208:211], v[84:87]
	v_mfma_f32_16x16x32_bf16 v[80:83], v[182:185], v[208:211], v[80:83]
	v_mfma_f32_16x16x32_bf16 v[68:71], v[174:177], v[216:219], v[68:71]
	v_mfma_f32_16x16x32_bf16 v[64:67], v[182:185], v[216:219], v[64:67]
	s_barrier
; #define PG8_STAGE_T(bufoff, gbase, voff, AUX) do { _Pragma("unroll") for (int _i = 0; _i < 2; ++_i) \
;         __builtin_amdgcn_global_load_lds((const unsigned*)((const char*)(gbase) + (voff)[_i]), (PG8_LAS unsigned*)(lds + (bufoff) + ldsw + _i * 8192), 16, 0, AUX); } while (0)
; #define PG8_LDA(dst, b, h) do { _Pragma("unroll") for (int m = 0; m < 4; ++m) _Pragma("unroll") for (int k = 0; k < 2; ++k) dst[m][k] = *(const PG8_LAS bf16x8*)(lds + PG8_SA(b, h) + aoff + m * 2048 + k * 1024); } while (0)
; #define PG8_MMA(ai, bj, At, Bt) do { __builtin_amdgcn_s_setprio(1); _Pragma("unroll") for (int m = 0; m < 4; ++m) _Pragma("unroll") for (int n = 0; n < 2; ++n) _Pragma("unroll") for (int k = 0; k < 2; ++k) \
;         acc[ai][bj][m][n] = __builtin_amdgcn_mfma_f32_16x16x32_bf16(Bt[n][k], At[m][k], acc[ai][bj][m][n], 0, 0, 0); __builtin_amdgcn_s_setprio(0); } while (0)
; #define PG8_WAIT_V(n) asm volatile("s_waitcnt vmcnt(" #n ")" ::: "memory")
; #define PG8_WAIT_L(n) asm volatile("s_waitcnt lgkmcnt(" #n ")" ::: "memory")
; #define PG8_BAR __builtin_amdgcn_s_barrier()
; #define PG8_SCHED __builtin_amdgcn_sched_barrier(0)
;     ...
;             PG8_LDA(At, 1, 1); PG8_STAGE_T(PG8_SB(1, 0), b3, voffB, AUX_B); PG8_STAGE_T(PG8_SB(1, 1), b3 + hstep, voffB, AUX_B); PG8_STAGE_T(PG8_SA(1, 0), a3, voffA, AUX_A);
;             PG8_WAIT_V(8); PG8_WAIT_L(0); PG8_BAR; PG8_MMA(1, 0, At, B0); PG8_MMA(1, 1, At, B1); PG8_BAR; PG8_SCHED;
	s_add_i32 s46, s64, s48
	v_lshl_add_u64 v[144:145], v[144:145], 0, s[10:11]
	s_mov_b32 m0, s46
	ds_read_b128 v[186:189], v151 offset:49152
	ds_read_b128 v[190:193], v151 offset:50176
	ds_read_b128 v[196:199], v151 offset:51200
	ds_read_b128 v[200:203], v151 offset:52224
	ds_read_b128 v[204:207], v151 offset:53248
	ds_read_b128 v[208:211], v151 offset:54272
	ds_read_b128 v[212:215], v151 offset:55296
	ds_read_b128 v[216:219], v151 offset:56320
	global_load_lds_dwordx4 v[144:145], off
	s_add_i32 m0, s46, 0x2000
	s_add_u32 s44, s44, 0x40080
	v_lshl_add_u64 v[144:145], v[220:221], 0, s[10:11]
	s_addc_u32 s45, s45, 0
	s_add_i32 s46, s65, s48
	global_load_lds_dwordx4 v[144:145], off
	v_lshl_add_u64 v[144:145], s[44:45], 0, v[130:131]
	s_mov_b32 m0, s46
	s_nop 0
	global_load_lds_dwordx4 v[144:145], off
	v_lshl_add_u64 v[144:145], s[44:45], 0, v[134:135]
	s_add_i32 m0, s46, 0x2000
	s_nop 0
	global_load_lds_dwordx4 v[144:145], off
	v_lshl_add_u64 v[144:145], v[222:223], 0, s[10:11]
	s_mov_b32 m0, s53
	s_nop 0
	global_load_lds_dwordx4 v[144:145], off
	v_lshl_add_u64 v[144:145], v[224:225], 0, s[10:11]
	s_mov_b32 m0, s54
	s_nop 0
	global_load_lds_dwordx4 v[144:145], off
	s_waitcnt vmcnt(8)
	s_waitcnt lgkmcnt(0)
	s_barrier
	s_waitcnt lgkmcnt(0)
	v_mfma_f32_16x16x32_bf16 v[60:63], v[154:157], v[186:189], v[60:63]
	v_mfma_f32_16x16x32_bf16 v[56:59], v[162:165], v[186:189], v[56:59]
	v_mfma_f32_16x16x32_bf16 v[44:47], v[154:157], v[196:199], v[44:47]
	v_mfma_f32_16x16x32_bf16 v[40:43], v[162:165], v[196:199], v[40:43]
	v_mfma_f32_16x16x32_bf16 v[28:31], v[154:157], v[204:207], v[28:31]
	v_mfma_f32_16x16x32_bf16 v[24:27], v[162:165], v[204:207], v[24:27]
	v_mfma_f32_16x16x32_bf16 v[12:15], v[154:157], v[212:215], v[12:15]
	v_mfma_f32_16x16x32_bf16 v[8:11], v[162:165], v[212:215], v[8:11]
	v_mfma_f32_16x16x32_bf16 v[60:63], v[158:161], v[190:193], v[60:63]
	v_mfma_f32_16x16x32_bf16 v[56:59], v[166:169], v[190:193], v[56:59]
	v_mfma_f32_16x16x32_bf16 v[44:47], v[158:161], v[200:203], v[44:47]
	v_mfma_f32_16x16x32_bf16 v[40:43], v[166:169], v[200:203], v[40:43]
	v_mfma_f32_16x16x32_bf16 v[28:31], v[158:161], v[208:211], v[28:31]
	v_mfma_f32_16x16x32_bf16 v[24:27], v[166:169], v[208:211], v[24:27]
	v_mfma_f32_16x16x32_bf16 v[12:15], v[158:161], v[216:219], v[12:15]
	v_mfma_f32_16x16x32_bf16 v[8:11], v[166:169], v[216:219], v[8:11]
	v_mfma_f32_16x16x32_bf16 v[52:55], v[170:173], v[186:189], v[52:55]
	v_mfma_f32_16x16x32_bf16 v[48:51], v[178:181], v[186:189], v[48:51]
	v_mfma_f32_16x16x32_bf16 v[36:39], v[170:173], v[196:199], v[36:39]
	v_mfma_f32_16x16x32_bf16 v[32:35], v[178:181], v[196:199], v[32:35]
	v_mfma_f32_16x16x32_bf16 v[20:23], v[170:173], v[204:207], v[20:23]
	v_mfma_f32_16x16x32_bf16 v[16:19], v[178:181], v[204:207], v[16:19]
	v_mfma_f32_16x16x32_bf16 v[4:7], v[170:173], v[212:215], v[4:7]
	v_mfma_f32_16x16x32_bf16 v[0:3], v[178:181], v[212:215], v[0:3]
	v_mfma_f32_16x16x32_bf16 v[52:55], v[174:177], v[190:193], v[52:55]
	v_mfma_f32_16x16x32_bf16 v[48:51], v[182:185], v[190:193], v[48:51]
	v_mfma_f32_16x16x32_bf16 v[36:39], v[174:177], v[200:203], v[36:39]
	v_mfma_f32_16x16x32_bf16 v[32:35], v[182:185], v[200:203], v[32:35]
	v_mfma_f32_16x16x32_bf16 v[20:23], v[174:177], v[208:211], v[20:23]
	v_mfma_f32_16x16x32_bf16 v[16:19], v[182:185], v[208:211], v[16:19]
	v_mfma_f32_16x16x32_bf16 v[4:7], v[174:177], v[216:219], v[4:7]
	v_mfma_f32_16x16x32_bf16 v[0:3], v[182:185], v[216:219], v[0:3]
	s_barrier
	s_add_i32 s63, s63, 2
	s_add_u32 s42, s42, 0x100
	s_addc_u32 s43, s43, 0
	s_add_u32 s61, s61, 0x100
	s_addc_u32 s62, s62, 0
	s_cmp_gt_u32 s63, 13
	s_cbranch_scc0 .LBB0_886
	s_and_b64 vcc, exec, s[12:13]
	s_cbranch_vccz .LBB0_889
	s_barrier

; #define PG8_STAGE_T(bufoff, gbase, voff, AUX) do { _Pragma("unroll") for (int _i = 0; _i < 2; ++_i) \
;         __builtin_amdgcn_global_load_lds((const unsigned*)((const char*)(gbase) + (voff)[_i]), (PG8_LAS unsigned*)(lds + (bufoff) + ldsw + _i * 8192), 16, 0, AUX); } while (0)
; #define PG8_LDA(dst, b, h) do { _Pragma("unroll") for (int m = 0; m < 4; ++m) _Pragma("unroll") for (int k = 0; k < 2; ++k) dst[m][k] = *(const PG8_LAS bf16x8*)(lds + PG8_SA(b, h) + aoff + m * 2048 + k * 1024); } while (0)
; #define PG8_LDB(dst, b, h) do { _Pragma("unroll") for (int n = 0; n < 2; ++n) _Pragma("unroll") for (int k = 0; k < 2; ++k) dst[n][k] = *(const PG8_LAS bf16x8*)(lds + PG8_SB(b, h) + boff + n * 2048 + k * 1024); } while (0)
; #define PG8_MMA(ai, bj, At, Bt) do { __builtin_amdgcn_s_setprio(1); _Pragma("unroll") for (int m = 0; m < 4; ++m) _Pragma("unroll") for (int n = 0; n < 2; ++n) _Pragma("unroll") for (int k = 0; k < 2; ++k) \
;         acc[ai][bj][m][n] = __builtin_amdgcn_mfma_f32_16x16x32_bf16(Bt[n][k], At[m][k], acc[ai][bj][m][n], 0, 0, 0); __builtin_amdgcn_s_setprio(0); } while (0)
; #define PG8_WAIT_V(n) asm volatile("s_waitcnt vmcnt(" #n ")" ::: "memory")
; #define PG8_WAIT_L(n) asm volatile("s_waitcnt lgkmcnt(" #n ")" ::: "memory")
; #define PG8_BAR __builtin_amdgcn_s_barrier()
; #define PG8_SCHED __builtin_amdgcn_sched_barrier(0)
;     ...
;             PG8_LDB(B0, 0, 0); PG8_LDB(B1, 0, 1); PG8_SCHED; PG8_LDA(At, 0, 0); if (!pe) { PG8_STAGE_T(PG8_SA(1, 1), a1 + hstep, voffA, AUX_A); }
;             if (!pe) { PG8_WAIT_V(8); } PG8_WAIT_L(0); PG8_BAR; PG8_MMA(0, 0, At, B0); PG8_MMA(0, 1, At, B1); PG8_BAR; PG8_SCHED;
;             PG8_LDA(At, 0, 1); PG8_STAGE_T(PG8_SB(0, 0), b2, voffB, AUX_B); PG8_STAGE_T(PG8_SB(0, 1), b2 + hstep, voffB, AUX_B); PG8_STAGE_T(PG8_SA(0, 0), a2, voffA, AUX_A);
;             if (!pe) { PG8_WAIT_V(8); } PG8_WAIT_L(0); PG8_BAR; PG8_MMA(1, 0, At, B0); PG8_MMA(1, 1, At, B1); PG8_BAR; PG8_SCHED;
.LBB0_1071:
	ds_read_b128 v[146:149], v166
	ds_read_b128 v[162:165], v166 offset:1024
	ds_read_b128 v[170:173], v166 offset:2048
	ds_read_b128 v[174:177], v166 offset:3072
	ds_read_b128 v[178:181], v167
	ds_read_b128 v[182:185], v167 offset:1024
	ds_read_b128 v[186:189], v167 offset:2048
	ds_read_b128 v[190:193], v167 offset:3072
	s_add_u32 s38, s36, 0xfffc0080
	s_addc_u32 s39, s37, -1
	s_cmp_eq_u32 s62, 12
	s_cselect_b32 s41, s13, s39
	s_cselect_b32 s40, s27, s38
	s_cselect_b32 s39, s15, s61
	s_cselect_b32 s38, s59, s60
	v_lshl_add_u64 v[150:151], s[36:37], 0, v[136:137]
	s_add_i32 m0, s45, 0xc000
	ds_read_b128 v[196:199], v168
	ds_read_b128 v[200:203], v168 offset:1024
	ds_read_b128 v[204:207], v168 offset:2048
	ds_read_b128 v[208:211], v168 offset:3072
	ds_read_b128 v[212:215], v168 offset:4096
	ds_read_b128 v[216:219], v168 offset:5120
	ds_read_b128 v[220:223], v168 offset:6144
	ds_read_b128 v[224:227], v168 offset:7168
	global_load_lds_dwordx4 v[150:151], off
	v_lshl_add_u64 v[150:151], s[36:37], 0, v[138:139]
	s_add_i32 m0, s45, 0xe000
	s_nop 0
	global_load_lds_dwordx4 v[150:151], off
	s_waitcnt vmcnt(8)
	s_waitcnt lgkmcnt(0)
	s_barrier
	s_waitcnt lgkmcnt(0)
	v_mfma_f32_16x16x32_bf16 v[124:127], v[146:149], v[196:199], v[124:127]
	v_mfma_f32_16x16x32_bf16 v[120:123], v[170:173], v[196:199], v[120:123]
	v_mfma_f32_16x16x32_bf16 v[108:111], v[146:149], v[204:207], v[108:111]
	v_mfma_f32_16x16x32_bf16 v[104:107], v[170:173], v[204:207], v[104:107]
	v_mfma_f32_16x16x32_bf16 v[92:95], v[146:149], v[212:215], v[92:95]
	v_mfma_f32_16x16x32_bf16 v[88:91], v[170:173], v[212:215], v[88:91]
	v_mfma_f32_16x16x32_bf16 v[76:79], v[146:149], v[220:223], v[76:79]
	v_mfma_f32_16x16x32_bf16 v[72:75], v[170:173], v[220:223], v[72:75]
	v_mfma_f32_16x16x32_bf16 v[124:127], v[162:165], v[200:203], v[124:127]
	v_mfma_f32_16x16x32_bf16 v[120:123], v[174:177], v[200:203], v[120:123]
	v_mfma_f32_16x16x32_bf16 v[108:111], v[162:165], v[208:211], v[108:111]
	v_mfma_f32_16x16x32_bf16 v[104:107], v[174:177], v[208:211], v[104:107]
	v_mfma_f32_16x16x32_bf16 v[92:95], v[162:165], v[216:219], v[92:95]
	v_mfma_f32_16x16x32_bf16 v[88:91], v[174:177], v[216:219], v[88:91]
	v_mfma_f32_16x16x32_bf16 v[76:79], v[162:165], v[224:227], v[76:79]
	v_mfma_f32_16x16x32_bf16 v[72:75], v[174:177], v[224:227], v[72:75]
	v_mfma_f32_16x16x32_bf16 v[116:119], v[178:181], v[196:199], v[116:119]
	v_mfma_f32_16x16x32_bf16 v[112:115], v[186:189], v[196:199], v[112:115]
	v_mfma_f32_16x16x32_bf16 v[100:103], v[178:181], v[204:207], v[100:103]
	v_mfma_f32_16x16x32_bf16 v[96:99], v[186:189], v[204:207], v[96:99]
	v_mfma_f32_16x16x32_bf16 v[84:87], v[178:181], v[212:215], v[84:87]
	v_mfma_f32_16x16x32_bf16 v[80:83], v[186:189], v[212:215], v[80:83]
	v_mfma_f32_16x16x32_bf16 v[68:71], v[178:181], v[220:223], v[68:71]
	v_mfma_f32_16x16x32_bf16 v[64:67], v[186:189], v[220:223], v[64:67]
	v_mfma_f32_16x16x32_bf16 v[116:119], v[182:185], v[200:203], v[116:119]
	v_mfma_f32_16x16x32_bf16 v[112:115], v[190:193], v[200:203], v[112:115]
	v_mfma_f32_16x16x32_bf16 v[100:103], v[182:185], v[208:211], v[100:103]
	v_mfma_f32_16x16x32_bf16 v[96:99], v[190:193], v[208:211], v[96:99]
	v_mfma_f32_16x16x32_bf16 v[84:87], v[182:185], v[216:219], v[84:87]
	v_mfma_f32_16x16x32_bf16 v[80:83], v[190:193], v[216:219], v[80:83]
	v_mfma_f32_16x16x32_bf16 v[68:71], v[182:185], v[224:227], v[68:71]
	v_mfma_f32_16x16x32_bf16 v[64:67], v[190:193], v[224:227], v[64:67]
	s_barrier
	s_add_i32 s63, s52, s43
	v_lshl_add_u64 v[150:151], s[38:39], 0, v[132:133]
	s_mov_b32 m0, s63
	ds_read_b128 v[196:199], v168 offset:16384
	ds_read_b128 v[200:203], v168 offset:17408
	ds_read_b128 v[204:207], v168 offset:18432
	ds_read_b128 v[208:211], v168 offset:19456
	ds_read_b128 v[212:215], v168 offset:20480
	ds_read_b128 v[216:219], v168 offset:21504
	ds_read_b128 v[220:223], v168 offset:22528
	ds_read_b128 v[224:227], v168 offset:23552
	global_load_lds_dwordx4 v[150:151], off
	s_add_i32 m0, s63, 0x2000
	s_add_u32 s64, s38, 0x40000
	v_lshl_add_u64 v[154:155], s[38:39], 0, v[128:129]
	s_addc_u32 s65, s39, 0
	s_add_i32 s63, s53, s43
	global_load_lds_dwordx4 v[154:155], off
	v_lshl_add_u64 v[158:159], s[64:65], 0, v[132:133]
	s_mov_b32 m0, s63
	v_lshl_add_u64 v[228:229], s[40:41], 0, v[130:131]
	global_load_lds_dwordx4 v[158:159], off
	v_lshl_add_u64 v[158:159], s[64:65], 0, v[128:129]
	s_add_i32 m0, s63, 0x2000
	s_nop 0
	global_load_lds_dwordx4 v[158:159], off
	v_lshl_add_u64 v[158:159], s[40:41], 0, v[134:135]
	s_mov_b32 m0, s45
	s_nop 0
	global_load_lds_dwordx4 v[158:159], off
	s_mov_b32 m0, s46
	s_nop 0
	global_load_lds_dwordx4 v[228:229], off
	s_waitcnt vmcnt(8)
	s_waitcnt lgkmcnt(0)
	s_barrier
; #define PG8_STAGE_T(bufoff, gbase, voff, AUX) do { _Pragma("unroll") for (int _i = 0; _i < 2; ++_i) \
;         __builtin_amdgcn_global_load_lds((const unsigned*)((const char*)(gbase) + (voff)[_i]), (PG8_LAS unsigned*)(lds + (bufoff) + ldsw + _i * 8192), 16, 0, AUX); } while (0)
; #define PG8_LDA(dst, b, h) do { _Pragma("unroll") for (int m = 0; m < 4; ++m) _Pragma("unroll") for (int k = 0; k < 2; ++k) dst[m][k] = *(const PG8_LAS bf16x8*)(lds + PG8_SA(b, h) + aoff + m * 2048 + k * 1024); } while (0)
; #define PG8_LDB(dst, b, h) do { _Pragma("unroll") for (int n = 0; n < 2; ++n) _Pragma("unroll") for (int k = 0; k < 2; ++k) dst[n][k] = *(const PG8_LAS bf16x8*)(lds + PG8_SB(b, h) + boff + n * 2048 + k * 1024); } while (0)
; #define PG8_MMA(ai, bj, At, Bt) do { __builtin_amdgcn_s_setprio(1); _Pragma("unroll") for (int m = 0; m < 4; ++m) _Pragma("unroll") for (int n = 0; n < 2; ++n) _Pragma("unroll") for (int k = 0; k < 2; ++k) \
;         acc[ai][bj][m][n] = __builtin_amdgcn_mfma_f32_16x16x32_bf16(Bt[n][k], At[m][k], acc[ai][bj][m][n], 0, 0, 0); __builtin_amdgcn_s_setprio(0); } while (0)
; #define PG8_WAIT_V(n) asm volatile("s_waitcnt vmcnt(" #n ")" ::: "memory")
; #define PG8_WAIT_L(n) asm volatile("s_waitcnt lgkmcnt(" #n ")" ::: "memory")
; #define PG8_BAR __builtin_amdgcn_s_barrier()
; #define PG8_SCHED __builtin_amdgcn_sched_barrier(0)
;     ...
;             if (!pe) { PG8_WAIT_V(8); } PG8_WAIT_L(0); PG8_BAR; PG8_MMA(1, 0, At, B0); PG8_MMA(1, 1, At, B1); PG8_BAR; PG8_SCHED;
;             PG8_LDB(B0, 1, 0); PG8_LDB(B1, 1, 1); PG8_SCHED; PG8_LDA(At, 1, 0); PG8_STAGE_T(PG8_SA(0, 1), a2 + hstep, voffA, AUX_A);
;             if (!pe) { PG8_WAIT_V(8); } PG8_WAIT_L(0); PG8_BAR; PG8_MMA(0, 0, At, B0); PG8_MMA(0, 1, At, B1); PG8_BAR; PG8_SCHED;
	s_waitcnt lgkmcnt(0)
	v_mfma_f32_16x16x32_bf16 v[60:63], v[146:149], v[196:199], v[60:63]
	v_mfma_f32_16x16x32_bf16 v[56:59], v[170:173], v[196:199], v[56:59]
	v_mfma_f32_16x16x32_bf16 v[44:47], v[146:149], v[204:207], v[44:47]
	v_mfma_f32_16x16x32_bf16 v[40:43], v[170:173], v[204:207], v[40:43]
	v_mfma_f32_16x16x32_bf16 v[28:31], v[146:149], v[212:215], v[28:31]
	v_mfma_f32_16x16x32_bf16 v[24:27], v[170:173], v[212:215], v[24:27]
	v_mfma_f32_16x16x32_bf16 v[12:15], v[146:149], v[220:223], v[12:15]
	v_mfma_f32_16x16x32_bf16 v[8:11], v[170:173], v[220:223], v[8:11]
	v_mfma_f32_16x16x32_bf16 v[60:63], v[162:165], v[200:203], v[60:63]
	v_mfma_f32_16x16x32_bf16 v[56:59], v[174:177], v[200:203], v[56:59]
	v_mfma_f32_16x16x32_bf16 v[44:47], v[162:165], v[208:211], v[44:47]
	v_mfma_f32_16x16x32_bf16 v[40:43], v[174:177], v[208:211], v[40:43]
	v_mfma_f32_16x16x32_bf16 v[28:31], v[162:165], v[216:219], v[28:31]
	v_mfma_f32_16x16x32_bf16 v[24:27], v[174:177], v[216:219], v[24:27]
	v_mfma_f32_16x16x32_bf16 v[12:15], v[162:165], v[224:227], v[12:15]
	v_mfma_f32_16x16x32_bf16 v[8:11], v[174:177], v[224:227], v[8:11]
	v_mfma_f32_16x16x32_bf16 v[52:55], v[178:181], v[196:199], v[52:55]
	v_mfma_f32_16x16x32_bf16 v[48:51], v[186:189], v[196:199], v[48:51]
	v_mfma_f32_16x16x32_bf16 v[36:39], v[178:181], v[204:207], v[36:39]
	v_mfma_f32_16x16x32_bf16 v[32:35], v[186:189], v[204:207], v[32:35]
	v_mfma_f32_16x16x32_bf16 v[20:23], v[178:181], v[212:215], v[20:23]
	v_mfma_f32_16x16x32_bf16 v[16:19], v[186:189], v[212:215], v[16:19]
	v_mfma_f32_16x16x32_bf16 v[4:7], v[178:181], v[220:223], v[4:7]
	v_mfma_f32_16x16x32_bf16 v[0:3], v[186:189], v[220:223], v[0:3]
	v_mfma_f32_16x16x32_bf16 v[52:55], v[182:185], v[200:203], v[52:55]
	v_mfma_f32_16x16x32_bf16 v[48:51], v[190:193], v[200:203], v[48:51]
	v_mfma_f32_16x16x32_bf16 v[36:39], v[182:185], v[208:211], v[36:39]
	v_mfma_f32_16x16x32_bf16 v[32:35], v[190:193], v[208:211], v[32:35]
	v_mfma_f32_16x16x32_bf16 v[20:23], v[182:185], v[216:219], v[20:23]
	v_mfma_f32_16x16x32_bf16 v[16:19], v[190:193], v[216:219], v[16:19]
	v_mfma_f32_16x16x32_bf16 v[4:7], v[182:185], v[224:227], v[4:7]
	v_mfma_f32_16x16x32_bf16 v[0:3], v[190:193], v[224:227], v[0:3]
	s_barrier
	s_add_i32 s63, 0, 0x18000
	v_add_u32_e32 v144, s63, v153
	s_add_i32 s64, 0, 0x1c000
	ds_read_b128 v[146:149], v144
	ds_read_b128 v[162:165], v144 offset:1024
	ds_read_b128 v[170:173], v144 offset:2048
	ds_read_b128 v[174:177], v144 offset:3072
	v_add_u32_e32 v144, s64, v153
	ds_read_b128 v[178:181], v144
	ds_read_b128 v[182:185], v144 offset:1024
	ds_read_b128 v[186:189], v144 offset:2048
	ds_read_b128 v[190:193], v144 offset:3072
	s_add_u32 s40, s40, 0x40000
	s_addc_u32 s41, s41, 0
	s_mov_b32 m0, s47
	v_lshl_add_u64 v[230:231], s[40:41], 0, v[134:135]
	ds_read_b128 v[196:199], v168 offset:32768
	ds_read_b128 v[200:203], v168 offset:33792
	ds_read_b128 v[204:207], v168 offset:34816
	ds_read_b128 v[208:211], v168 offset:35840
	ds_read_b128 v[212:215], v168 offset:36864
	ds_read_b128 v[216:219], v168 offset:37888
	ds_read_b128 v[220:223], v168 offset:38912
	ds_read_b128 v[224:227], v168 offset:39936
	global_load_lds_dwordx4 v[230:231], off
	v_lshl_add_u64 v[230:231], s[40:41], 0, v[130:131]
	s_mov_b32 m0, s48
	s_nop 0
	global_load_lds_dwordx4 v[230:231], off
	s_waitcnt vmcnt(8)
	s_waitcnt lgkmcnt(0)
	s_barrier
	s_waitcnt lgkmcnt(0)
	v_mfma_f32_16x16x32_bf16 v[124:127], v[146:149], v[196:199], v[124:127]
	v_mfma_f32_16x16x32_bf16 v[120:123], v[170:173], v[196:199], v[120:123]
	v_mfma_f32_16x16x32_bf16 v[108:111], v[146:149], v[204:207], v[108:111]
	v_mfma_f32_16x16x32_bf16 v[104:107], v[170:173], v[204:207], v[104:107]
	v_mfma_f32_16x16x32_bf16 v[92:95], v[146:149], v[212:215], v[92:95]
	v_mfma_f32_16x16x32_bf16 v[88:91], v[170:173], v[212:215], v[88:91]
	v_mfma_f32_16x16x32_bf16 v[76:79], v[146:149], v[220:223], v[76:79]
	v_mfma_f32_16x16x32_bf16 v[72:75], v[170:173], v[220:223], v[72:75]
	v_mfma_f32_16x16x32_bf16 v[124:127], v[162:165], v[200:203], v[124:127]
	v_mfma_f32_16x16x32_bf16 v[120:123], v[174:177], v[200:203], v[120:123]
	v_mfma_f32_16x16x32_bf16 v[108:111], v[162:165], v[208:211], v[108:111]
	v_mfma_f32_16x16x32_bf16 v[104:107], v[174:177], v[208:211], v[104:107]
	v_mfma_f32_16x16x32_bf16 v[92:95], v[162:165], v[216:219], v[92:95]
	v_mfma_f32_16x16x32_bf16 v[88:91], v[174:177], v[216:219], v[88:91]
	v_mfma_f32_16x16x32_bf16 v[76:79], v[162:165], v[224:227], v[76:79]
	v_mfma_f32_16x16x32_bf16 v[72:75], v[174:177], v[224:227], v[72:75]
	v_mfma_f32_16x16x32_bf16 v[116:119], v[178:181], v[196:199], v[116:119]
	v_mfma_f32_16x16x32_bf16 v[112:115], v[186:189], v[196:199], v[112:115]
	v_mfma_f32_16x16x32_bf16 v[100:103], v[178:181], v[204:207], v[100:103]
	v_mfma_f32_16x16x32_bf16 v[96:99], v[186:189], v[204:207], v[96:99]
	v_mfma_f32_16x16x32_bf16 v[84:87], v[178:181], v[212:215], v[84:87]
	v_mfma_f32_16x16x32_bf16 v[80:83], v[186:189], v[212:215], v[80:83]
	v_mfma_f32_16x16x32_bf16 v[68:71], v[178:181], v[220:223], v[68:71]
	v_mfma_f32_16x16x32_bf16 v[64:67], v[186:189], v[220:223], v[64:67]
	v_mfma_f32_16x16x32_bf16 v[116:119], v[182:185], v[200:203], v[116:119]
	v_mfma_f32_16x16x32_bf16 v[112:115], v[190:193], v[200:203], v[112:115]
	v_mfma_f32_16x16x32_bf16 v[100:103], v[182:185], v[208:211], v[100:103]
	v_mfma_f32_16x16x32_bf16 v[96:99], v[190:193], v[208:211], v[96:99]
	v_mfma_f32_16x16x32_bf16 v[84:87], v[182:185], v[216:219], v[84:87]
	v_mfma_f32_16x16x32_bf16 v[80:83], v[190:193], v[216:219], v[80:83]
	v_mfma_f32_16x16x32_bf16 v[68:71], v[182:185], v[224:227], v[68:71]
	v_mfma_f32_16x16x32_bf16 v[64:67], v[190:193], v[224:227], v[64:67]
	s_barrier
; #define PG8_STAGE_T(bufoff, gbase, voff, AUX) do { _Pragma("unroll") for (int _i = 0; _i < 2; ++_i) \
;         __builtin_amdgcn_global_load_lds((const unsigned*)((const char*)(gbase) + (voff)[_i]), (PG8_LAS unsigned*)(lds + (bufoff) + ldsw + _i * 8192), 16, 0, AUX); } while (0)
; #define PG8_LDA(dst, b, h) do { _Pragma("unroll") for (int m = 0; m < 4; ++m) _Pragma("unroll") for (int k = 0; k < 2; ++k) dst[m][k] = *(const PG8_LAS bf16x8*)(lds + PG8_SA(b, h) + aoff + m * 2048 + k * 1024); } while (0)
; #define PG8_MMA(ai, bj, At, Bt) do { __builtin_amdgcn_s_setprio(1); _Pragma("unroll") for (int m = 0; m < 4; ++m) _Pragma("unroll") for (int n = 0; n < 2; ++n) _Pragma("unroll") for (int k = 0; k < 2; ++k) \
;         acc[ai][bj][m][n] = __builtin_amdgcn_mfma_f32_16x16x32_bf16(Bt[n][k], At[m][k], acc[ai][bj][m][n], 0, 0, 0); __builtin_amdgcn_s_setprio(0); } while (0)
; #define PG8_WAIT_V(n) asm volatile("s_waitcnt vmcnt(" #n ")" ::: "memory")
; #define PG8_WAIT_L(n) asm volatile("s_waitcnt lgkmcnt(" #n ")" ::: "memory")
; #define PG8_BAR __builtin_amdgcn_s_barrier()
; #define PG8_SCHED __builtin_amdgcn_sched_barrier(0)
;     ...
;             PG8_LDA(At, 1, 1); PG8_STAGE_T(PG8_SB(1, 0), b3, voffB, AUX_B); PG8_STAGE_T(PG8_SB(1, 1), b3 + hstep, voffB, AUX_B); PG8_STAGE_T(PG8_SA(1, 0), a3, voffA, AUX_A);
;             PG8_WAIT_V(8); PG8_WAIT_L(0); PG8_BAR; PG8_MMA(1, 0, At, B0); PG8_MMA(1, 1, At, B1); PG8_BAR; PG8_SCHED;
	s_add_i32 s40, s63, s43
	v_lshl_add_u64 v[150:151], v[150:151], 0, s[8:9]
	s_mov_b32 m0, s40
	ds_read_b128 v[196:199], v168 offset:49152
	ds_read_b128 v[200:203], v168 offset:50176
	ds_read_b128 v[204:207], v168 offset:51200
	ds_read_b128 v[208:211], v168 offset:52224
	ds_read_b128 v[212:215], v168 offset:53248
	ds_read_b128 v[216:219], v168 offset:54272
	ds_read_b128 v[220:223], v168 offset:55296
	ds_read_b128 v[224:227], v168 offset:56320
	global_load_lds_dwordx4 v[150:151], off
	s_add_i32 m0, s40, 0x2000
	s_add_u32 s38, s38, 0x40080
	v_lshl_add_u64 v[150:151], v[154:155], 0, s[8:9]
	s_addc_u32 s39, s39, 0
	s_add_i32 s40, s64, s43
	global_load_lds_dwordx4 v[150:151], off
	v_lshl_add_u64 v[150:151], s[38:39], 0, v[132:133]
	s_mov_b32 m0, s40
	s_nop 0
	global_load_lds_dwordx4 v[150:151], off
	v_lshl_add_u64 v[150:151], s[38:39], 0, v[128:129]
	s_add_i32 m0, s40, 0x2000
	s_nop 0
	global_load_lds_dwordx4 v[150:151], off
	v_lshl_add_u64 v[150:151], v[158:159], 0, s[8:9]
	s_mov_b32 m0, s50
	s_nop 0
	global_load_lds_dwordx4 v[150:151], off
	v_lshl_add_u64 v[150:151], v[228:229], 0, s[8:9]
	s_mov_b32 m0, s51
	s_nop 0
	global_load_lds_dwordx4 v[150:151], off
	s_waitcnt vmcnt(8)
	s_waitcnt lgkmcnt(0)
	s_barrier
	s_waitcnt lgkmcnt(0)
	v_mfma_f32_16x16x32_bf16 v[60:63], v[146:149], v[196:199], v[60:63]
	v_mfma_f32_16x16x32_bf16 v[56:59], v[170:173], v[196:199], v[56:59]
	v_mfma_f32_16x16x32_bf16 v[44:47], v[146:149], v[204:207], v[44:47]
	v_mfma_f32_16x16x32_bf16 v[40:43], v[170:173], v[204:207], v[40:43]
	v_mfma_f32_16x16x32_bf16 v[28:31], v[146:149], v[212:215], v[28:31]
	v_mfma_f32_16x16x32_bf16 v[24:27], v[170:173], v[212:215], v[24:27]
	v_mfma_f32_16x16x32_bf16 v[12:15], v[146:149], v[220:223], v[12:15]
	v_mfma_f32_16x16x32_bf16 v[8:11], v[170:173], v[220:223], v[8:11]
	v_mfma_f32_16x16x32_bf16 v[60:63], v[162:165], v[200:203], v[60:63]
	v_mfma_f32_16x16x32_bf16 v[56:59], v[174:177], v[200:203], v[56:59]
	v_mfma_f32_16x16x32_bf16 v[44:47], v[162:165], v[208:211], v[44:47]
	v_mfma_f32_16x16x32_bf16 v[40:43], v[174:177], v[208:211], v[40:43]
	v_mfma_f32_16x16x32_bf16 v[28:31], v[162:165], v[216:219], v[28:31]
	v_mfma_f32_16x16x32_bf16 v[24:27], v[174:177], v[216:219], v[24:27]
	v_mfma_f32_16x16x32_bf16 v[12:15], v[162:165], v[224:227], v[12:15]
	v_mfma_f32_16x16x32_bf16 v[8:11], v[174:177], v[224:227], v[8:11]
	v_mfma_f32_16x16x32_bf16 v[52:55], v[178:181], v[196:199], v[52:55]
	v_mfma_f32_16x16x32_bf16 v[48:51], v[186:189], v[196:199], v[48:51]
	v_mfma_f32_16x16x32_bf16 v[36:39], v[178:181], v[204:207], v[36:39]
	v_mfma_f32_16x16x32_bf16 v[32:35], v[186:189], v[204:207], v[32:35]
	v_mfma_f32_16x16x32_bf16 v[20:23], v[178:181], v[212:215], v[20:23]
	v_mfma_f32_16x16x32_bf16 v[16:19], v[186:189], v[212:215], v[16:19]
	v_mfma_f32_16x16x32_bf16 v[4:7], v[178:181], v[220:223], v[4:7]
	v_mfma_f32_16x16x32_bf16 v[0:3], v[186:189], v[220:223], v[0:3]
	v_mfma_f32_16x16x32_bf16 v[52:55], v[182:185], v[200:203], v[52:55]
	v_mfma_f32_16x16x32_bf16 v[48:51], v[190:193], v[200:203], v[48:51]
	v_mfma_f32_16x16x32_bf16 v[36:39], v[182:185], v[208:211], v[36:39]
	v_mfma_f32_16x16x32_bf16 v[32:35], v[190:193], v[208:211], v[32:35]
	v_mfma_f32_16x16x32_bf16 v[20:23], v[182:185], v[216:219], v[20:23]
	v_mfma_f32_16x16x32_bf16 v[16:19], v[190:193], v[216:219], v[16:19]
	v_mfma_f32_16x16x32_bf16 v[4:7], v[182:185], v[224:227], v[4:7]
	v_mfma_f32_16x16x32_bf16 v[0:3], v[190:193], v[224:227], v[0:3]
	s_barrier
	s_add_i32 s62, s62, 2
	s_add_u32 s36, s36, 0x100
	s_addc_u32 s37, s37, 0
	s_add_u32 s60, s60, 0x100
	s_addc_u32 s61, s61, 0
	s_cmp_gt_u32 s62, 13
	s_cbranch_scc0 .LBB0_1071
	s_and_b64 vcc, exec, s[10:11]
	s_cbranch_vccz .LBB0_1074
	s_barrier

; #define PG8_STAGE_T(bufoff, gbase, voff, AUX) do { _Pragma("unroll") for (int _i = 0; _i < 2; ++_i) \
;         __builtin_amdgcn_global_load_lds((const unsigned*)((const char*)(gbase) + (voff)[_i]), (PG8_LAS unsigned*)(lds + (bufoff) + ldsw + _i * 8192), 16, 0, AUX); } while (0)
; #define PG8_LDA(dst, b, h) do { _Pragma("unroll") for (int m = 0; m < 4; ++m) _Pragma("unroll") for (int k = 0; k < 2; ++k) dst[m][k] = *(const PG8_LAS bf16x8*)(lds + PG8_SA(b, h) + aoff + m * 2048 + k * 1024); } while (0)
; #define PG8_LDB(dst, b, h) do { _Pragma("unroll") for (int n = 0; n < 2; ++n) _Pragma("unroll") for (int k = 0; k < 2; ++k) dst[n][k] = *(const PG8_LAS bf16x8*)(lds + PG8_SB(b, h) + boff + n * 2048 + k * 1024); } while (0)
; #define PG8_MMA(ai, bj, At, Bt) do { __builtin_amdgcn_s_setprio(1); _Pragma("unroll") for (int m = 0; m < 4; ++m) _Pragma("unroll") for (int n = 0; n < 2; ++n) _Pragma("unroll") for (int k = 0; k < 2; ++k) \
;         acc[ai][bj][m][n] = __builtin_amdgcn_mfma_f32_16x16x32_bf16(Bt[n][k], At[m][k], acc[ai][bj][m][n], 0, 0, 0); __builtin_amdgcn_s_setprio(0); } while (0)
; #define PG8_WAIT_V(n) asm volatile("s_waitcnt vmcnt(" #n ")" ::: "memory")
; #define PG8_WAIT_L(n) asm volatile("s_waitcnt lgkmcnt(" #n ")" ::: "memory")
; #define PG8_BAR __builtin_amdgcn_s_barrier()
; #define PG8_SCHED __builtin_amdgcn_sched_barrier(0)
;     ...
;             PG8_LDB(B0, 0, 0); PG8_LDB(B1, 0, 1); PG8_SCHED; PG8_LDA(At, 0, 0); if (!pe) { PG8_STAGE_T(PG8_SA(1, 1), a1 + hstep, voffA, AUX_A); }
;             if (!pe) { PG8_WAIT_V(8); } PG8_WAIT_L(0); PG8_BAR; PG8_MMA(0, 0, At, B0); PG8_MMA(0, 1, At, B1); PG8_BAR; PG8_SCHED;
;             PG8_LDA(At, 0, 1); PG8_STAGE_T(PG8_SB(0, 0), b2, voffB, AUX_B); PG8_STAGE_T(PG8_SB(0, 1), b2 + hstep, voffB, AUX_B); PG8_STAGE_T(PG8_SA(0, 0), a2, voffA, AUX_A);
;             if (!pe) { PG8_WAIT_V(8); } PG8_WAIT_L(0); PG8_BAR; PG8_MMA(1, 0, At, B0); PG8_MMA(1, 1, At, B1); PG8_BAR; PG8_SCHED;
.LBB0_1156:
	ds_read_b128 v[154:157], v149
	s_waitcnt lgkmcnt(0)
	ds_read_b128 v[158:161], v149 offset:1024
	ds_read_b128 v[162:165], v149 offset:2048
	ds_read_b128 v[166:169], v149 offset:3072
	ds_read_b128 v[170:173], v150
	ds_read_b128 v[174:177], v150 offset:1024
	ds_read_b128 v[178:181], v150 offset:2048
	ds_read_b128 v[182:185], v150 offset:3072
	s_add_u32 s26, s24, 0xfff50080
	s_addc_u32 s27, s25, -1
	s_cmp_eq_u32 s55, 40
	s_cselect_b32 s37, s5, s27
	s_cselect_b32 s36, s4, s26
	s_cselect_b32 s27, s23, s54
	s_cselect_b32 s26, s22, s53
	v_lshl_add_u64 v[144:145], s[24:25], 0, v[136:137]
	s_add_i32 m0, s39, 0xc000
	ds_read_b128 v[186:189], v151
	ds_read_b128 v[190:193], v151 offset:1024
	ds_read_b128 v[196:199], v151 offset:2048
	ds_read_b128 v[200:203], v151 offset:3072
	ds_read_b128 v[204:207], v151 offset:4096
	ds_read_b128 v[208:211], v151 offset:5120
	ds_read_b128 v[212:215], v151 offset:6144
	ds_read_b128 v[216:219], v151 offset:7168
	global_load_lds_dwordx4 v[144:145], off
	v_lshl_add_u64 v[144:145], s[24:25], 0, v[138:139]
	s_add_i32 m0, s39, 0xe000
	s_nop 0
	global_load_lds_dwordx4 v[144:145], off
	s_waitcnt vmcnt(8)
	s_waitcnt lgkmcnt(0)
	s_barrier
	s_waitcnt lgkmcnt(0)
	v_mfma_f32_16x16x32_bf16 v[124:127], v[154:157], v[186:189], v[124:127]
	v_mfma_f32_16x16x32_bf16 v[120:123], v[162:165], v[186:189], v[120:123]
	v_mfma_f32_16x16x32_bf16 v[108:111], v[154:157], v[196:199], v[108:111]
	v_mfma_f32_16x16x32_bf16 v[104:107], v[162:165], v[196:199], v[104:107]
	v_mfma_f32_16x16x32_bf16 v[92:95], v[154:157], v[204:207], v[92:95]
	v_mfma_f32_16x16x32_bf16 v[88:91], v[162:165], v[204:207], v[88:91]
	v_mfma_f32_16x16x32_bf16 v[76:79], v[154:157], v[212:215], v[76:79]
	v_mfma_f32_16x16x32_bf16 v[72:75], v[162:165], v[212:215], v[72:75]
	v_mfma_f32_16x16x32_bf16 v[124:127], v[158:161], v[190:193], v[124:127]
	v_mfma_f32_16x16x32_bf16 v[120:123], v[166:169], v[190:193], v[120:123]
	v_mfma_f32_16x16x32_bf16 v[108:111], v[158:161], v[200:203], v[108:111]
	v_mfma_f32_16x16x32_bf16 v[104:107], v[166:169], v[200:203], v[104:107]
	v_mfma_f32_16x16x32_bf16 v[92:95], v[158:161], v[208:211], v[92:95]
	v_mfma_f32_16x16x32_bf16 v[88:91], v[166:169], v[208:211], v[88:91]
	v_mfma_f32_16x16x32_bf16 v[76:79], v[158:161], v[216:219], v[76:79]
	v_mfma_f32_16x16x32_bf16 v[72:75], v[166:169], v[216:219], v[72:75]
	v_mfma_f32_16x16x32_bf16 v[116:119], v[170:173], v[186:189], v[116:119]
	v_mfma_f32_16x16x32_bf16 v[112:115], v[178:181], v[186:189], v[112:115]
	v_mfma_f32_16x16x32_bf16 v[100:103], v[170:173], v[196:199], v[100:103]
	v_mfma_f32_16x16x32_bf16 v[96:99], v[178:181], v[196:199], v[96:99]
	v_mfma_f32_16x16x32_bf16 v[84:87], v[170:173], v[204:207], v[84:87]
	v_mfma_f32_16x16x32_bf16 v[80:83], v[178:181], v[204:207], v[80:83]
	v_mfma_f32_16x16x32_bf16 v[68:71], v[170:173], v[212:215], v[68:71]
	v_mfma_f32_16x16x32_bf16 v[64:67], v[178:181], v[212:215], v[64:67]
	v_mfma_f32_16x16x32_bf16 v[116:119], v[174:177], v[190:193], v[116:119]
	v_mfma_f32_16x16x32_bf16 v[112:115], v[182:185], v[190:193], v[112:115]
	v_mfma_f32_16x16x32_bf16 v[100:103], v[174:177], v[200:203], v[100:103]
	v_mfma_f32_16x16x32_bf16 v[96:99], v[182:185], v[200:203], v[96:99]
	v_mfma_f32_16x16x32_bf16 v[84:87], v[174:177], v[208:211], v[84:87]
	v_mfma_f32_16x16x32_bf16 v[80:83], v[182:185], v[208:211], v[80:83]
	v_mfma_f32_16x16x32_bf16 v[68:71], v[174:177], v[216:219], v[68:71]
	v_mfma_f32_16x16x32_bf16 v[64:67], v[182:185], v[216:219], v[64:67]
	s_barrier
	s_add_i32 s56, s46, s38
	v_lshl_add_u64 v[144:145], s[26:27], 0, v[130:131]
	s_mov_b32 m0, s56
	ds_read_b128 v[186:189], v151 offset:16384
	ds_read_b128 v[190:193], v151 offset:17408
	ds_read_b128 v[196:199], v151 offset:18432
	ds_read_b128 v[200:203], v151 offset:19456
	ds_read_b128 v[204:207], v151 offset:20480
	ds_read_b128 v[208:211], v151 offset:21504
	ds_read_b128 v[212:215], v151 offset:22528
	ds_read_b128 v[216:219], v151 offset:23552
	global_load_lds_dwordx4 v[144:145], off
	s_add_i32 m0, s56, 0x2000
	s_add_u32 s56, s26, 0xb0000
	v_lshl_add_u64 v[220:221], s[26:27], 0, v[134:135]
	s_addc_u32 s57, s27, 0
	s_add_i32 s58, s47, s38
	global_load_lds_dwordx4 v[220:221], off
	v_lshl_add_u64 v[222:223], s[56:57], 0, v[130:131]
	s_mov_b32 m0, s58
	v_lshl_add_u64 v[224:225], s[36:37], 0, v[132:133]
	global_load_lds_dwordx4 v[222:223], off
	v_lshl_add_u64 v[222:223], s[56:57], 0, v[134:135]
	s_add_i32 m0, s58, 0x2000
	s_nop 0
	global_load_lds_dwordx4 v[222:223], off
	v_lshl_add_u64 v[222:223], s[36:37], 0, v[128:129]
	s_mov_b32 m0, s39
	s_nop 0
	global_load_lds_dwordx4 v[222:223], off
	s_mov_b32 m0, s40
	s_nop 0
	global_load_lds_dwordx4 v[224:225], off
	s_waitcnt vmcnt(8)
	s_waitcnt lgkmcnt(0)
	s_barrier
; #define PG8_STAGE_T(bufoff, gbase, voff, AUX) do { _Pragma("unroll") for (int _i = 0; _i < 2; ++_i) \
;         __builtin_amdgcn_global_load_lds((const unsigned*)((const char*)(gbase) + (voff)[_i]), (PG8_LAS unsigned*)(lds + (bufoff) + ldsw + _i * 8192), 16, 0, AUX); } while (0)
; #define PG8_LDA(dst, b, h) do { _Pragma("unroll") for (int m = 0; m < 4; ++m) _Pragma("unroll") for (int k = 0; k < 2; ++k) dst[m][k] = *(const PG8_LAS bf16x8*)(lds + PG8_SA(b, h) + aoff + m * 2048 + k * 1024); } while (0)
; #define PG8_LDB(dst, b, h) do { _Pragma("unroll") for (int n = 0; n < 2; ++n) _Pragma("unroll") for (int k = 0; k < 2; ++k) dst[n][k] = *(const PG8_LAS bf16x8*)(lds + PG8_SB(b, h) + boff + n * 2048 + k * 1024); } while (0)
; #define PG8_MMA(ai, bj, At, Bt) do { __builtin_amdgcn_s_setprio(1); _Pragma("unroll") for (int m = 0; m < 4; ++m) _Pragma("unroll") for (int n = 0; n < 2; ++n) _Pragma("unroll") for (int k = 0; k < 2; ++k) \
;         acc[ai][bj][m][n] = __builtin_amdgcn_mfma_f32_16x16x32_bf16(Bt[n][k], At[m][k], acc[ai][bj][m][n], 0, 0, 0); __builtin_amdgcn_s_setprio(0); } while (0)
; #define PG8_WAIT_V(n) asm volatile("s_waitcnt vmcnt(" #n ")" ::: "memory")
; #define PG8_WAIT_L(n) asm volatile("s_waitcnt lgkmcnt(" #n ")" ::: "memory")
; #define PG8_BAR __builtin_amdgcn_s_barrier()
; #define PG8_SCHED __builtin_amdgcn_sched_barrier(0)
;     ...
;             if (!pe) { PG8_WAIT_V(8); } PG8_WAIT_L(0); PG8_BAR; PG8_MMA(1, 0, At, B0); PG8_MMA(1, 1, At, B1); PG8_BAR; PG8_SCHED;
;             PG8_LDB(B0, 1, 0); PG8_LDB(B1, 1, 1); PG8_SCHED; PG8_LDA(At, 1, 0); PG8_STAGE_T(PG8_SA(0, 1), a2 + hstep, voffA, AUX_A);
;             if (!pe) { PG8_WAIT_V(8); } PG8_WAIT_L(0); PG8_BAR; PG8_MMA(0, 0, At, B0); PG8_MMA(0, 1, At, B1); PG8_BAR; PG8_SCHED;
	s_waitcnt lgkmcnt(0)
	v_mfma_f32_16x16x32_bf16 v[60:63], v[154:157], v[186:189], v[60:63]
	v_mfma_f32_16x16x32_bf16 v[56:59], v[162:165], v[186:189], v[56:59]
	v_mfma_f32_16x16x32_bf16 v[44:47], v[154:157], v[196:199], v[44:47]
	v_mfma_f32_16x16x32_bf16 v[40:43], v[162:165], v[196:199], v[40:43]
	v_mfma_f32_16x16x32_bf16 v[28:31], v[154:157], v[204:207], v[28:31]
	v_mfma_f32_16x16x32_bf16 v[24:27], v[162:165], v[204:207], v[24:27]
	v_mfma_f32_16x16x32_bf16 v[12:15], v[154:157], v[212:215], v[12:15]
	v_mfma_f32_16x16x32_bf16 v[8:11], v[162:165], v[212:215], v[8:11]
	v_mfma_f32_16x16x32_bf16 v[60:63], v[158:161], v[190:193], v[60:63]
	v_mfma_f32_16x16x32_bf16 v[56:59], v[166:169], v[190:193], v[56:59]
	v_mfma_f32_16x16x32_bf16 v[44:47], v[158:161], v[200:203], v[44:47]
	v_mfma_f32_16x16x32_bf16 v[40:43], v[166:169], v[200:203], v[40:43]
	v_mfma_f32_16x16x32_bf16 v[28:31], v[158:161], v[208:211], v[28:31]
	v_mfma_f32_16x16x32_bf16 v[24:27], v[166:169], v[208:211], v[24:27]
	v_mfma_f32_16x16x32_bf16 v[12:15], v[158:161], v[216:219], v[12:15]
	v_mfma_f32_16x16x32_bf16 v[8:11], v[166:169], v[216:219], v[8:11]
	v_mfma_f32_16x16x32_bf16 v[52:55], v[170:173], v[186:189], v[52:55]
	v_mfma_f32_16x16x32_bf16 v[48:51], v[178:181], v[186:189], v[48:51]
	v_mfma_f32_16x16x32_bf16 v[36:39], v[170:173], v[196:199], v[36:39]
	v_mfma_f32_16x16x32_bf16 v[32:35], v[178:181], v[196:199], v[32:35]
	v_mfma_f32_16x16x32_bf16 v[20:23], v[170:173], v[204:207], v[20:23]
	v_mfma_f32_16x16x32_bf16 v[16:19], v[178:181], v[204:207], v[16:19]
	v_mfma_f32_16x16x32_bf16 v[4:7], v[170:173], v[212:215], v[4:7]
	v_mfma_f32_16x16x32_bf16 v[0:3], v[178:181], v[212:215], v[0:3]
	v_mfma_f32_16x16x32_bf16 v[52:55], v[174:177], v[190:193], v[52:55]
	v_mfma_f32_16x16x32_bf16 v[48:51], v[182:185], v[190:193], v[48:51]
	v_mfma_f32_16x16x32_bf16 v[36:39], v[174:177], v[200:203], v[36:39]
	v_mfma_f32_16x16x32_bf16 v[32:35], v[182:185], v[200:203], v[32:35]
	v_mfma_f32_16x16x32_bf16 v[20:23], v[174:177], v[208:211], v[20:23]
	v_mfma_f32_16x16x32_bf16 v[16:19], v[182:185], v[208:211], v[16:19]
	v_mfma_f32_16x16x32_bf16 v[4:7], v[174:177], v[216:219], v[4:7]
	v_mfma_f32_16x16x32_bf16 v[0:3], v[182:185], v[216:219], v[0:3]
	s_barrier
	s_add_i32 s56, 0, 0x18000
	v_add_u32_e32 v153, s56, v147
	s_add_i32 s57, 0, 0x1c000
	ds_read_b128 v[154:157], v153
	ds_read_b128 v[158:161], v153 offset:1024
	ds_read_b128 v[162:165], v153 offset:2048
	ds_read_b128 v[166:169], v153 offset:3072
	v_add_u32_e32 v153, s57, v147
	ds_read_b128 v[170:173], v153
	ds_read_b128 v[174:177], v153 offset:1024
	ds_read_b128 v[178:181], v153 offset:2048
	ds_read_b128 v[182:185], v153 offset:3072
	s_add_u32 s36, s36, 0xb0000
	s_addc_u32 s37, s37, 0
	s_mov_b32 m0, s41
	v_lshl_add_u64 v[226:227], s[36:37], 0, v[128:129]
	ds_read_b128 v[186:189], v151 offset:32768
	ds_read_b128 v[190:193], v151 offset:33792
	ds_read_b128 v[196:199], v151 offset:34816
	ds_read_b128 v[200:203], v151 offset:35840
	ds_read_b128 v[204:207], v151 offset:36864
	ds_read_b128 v[208:211], v151 offset:37888
	ds_read_b128 v[212:215], v151 offset:38912
	ds_read_b128 v[216:219], v151 offset:39936
	global_load_lds_dwordx4 v[226:227], off
	v_lshl_add_u64 v[226:227], s[36:37], 0, v[132:133]
	s_mov_b32 m0, s42
	s_nop 0
	global_load_lds_dwordx4 v[226:227], off
	s_waitcnt vmcnt(8)
	s_waitcnt lgkmcnt(0)
	s_barrier
	s_waitcnt lgkmcnt(0)
	v_mfma_f32_16x16x32_bf16 v[124:127], v[154:157], v[186:189], v[124:127]
	v_mfma_f32_16x16x32_bf16 v[120:123], v[162:165], v[186:189], v[120:123]
	v_mfma_f32_16x16x32_bf16 v[108:111], v[154:157], v[196:199], v[108:111]
	v_mfma_f32_16x16x32_bf16 v[104:107], v[162:165], v[196:199], v[104:107]
	v_mfma_f32_16x16x32_bf16 v[92:95], v[154:157], v[204:207], v[92:95]
	v_mfma_f32_16x16x32_bf16 v[88:91], v[162:165], v[204:207], v[88:91]
	v_mfma_f32_16x16x32_bf16 v[76:79], v[154:157], v[212:215], v[76:79]
	v_mfma_f32_16x16x32_bf16 v[72:75], v[162:165], v[212:215], v[72:75]
	v_mfma_f32_16x16x32_bf16 v[124:127], v[158:161], v[190:193], v[124:127]
	v_mfma_f32_16x16x32_bf16 v[120:123], v[166:169], v[190:193], v[120:123]
	v_mfma_f32_16x16x32_bf16 v[108:111], v[158:161], v[200:203], v[108:111]
	v_mfma_f32_16x16x32_bf16 v[104:107], v[166:169], v[200:203], v[104:107]
	v_mfma_f32_16x16x32_bf16 v[92:95], v[158:161], v[208:211], v[92:95]
	v_mfma_f32_16x16x32_bf16 v[88:91], v[166:169], v[208:211], v[88:91]
	v_mfma_f32_16x16x32_bf16 v[76:79], v[158:161], v[216:219], v[76:79]
	v_mfma_f32_16x16x32_bf16 v[72:75], v[166:169], v[216:219], v[72:75]
	v_mfma_f32_16x16x32_bf16 v[116:119], v[170:173], v[186:189], v[116:119]
	v_mfma_f32_16x16x32_bf16 v[112:115], v[178:181], v[186:189], v[112:115]
	v_mfma_f32_16x16x32_bf16 v[100:103], v[170:173], v[196:199], v[100:103]
	v_mfma_f32_16x16x32_bf16 v[96:99], v[178:181], v[196:199], v[96:99]
	v_mfma_f32_16x16x32_bf16 v[84:87], v[170:173], v[204:207], v[84:87]
	v_mfma_f32_16x16x32_bf16 v[80:83], v[178:181], v[204:207], v[80:83]
	v_mfma_f32_16x16x32_bf16 v[68:71], v[170:173], v[212:215], v[68:71]
	v_mfma_f32_16x16x32_bf16 v[64:67], v[178:181], v[212:215], v[64:67]
	v_mfma_f32_16x16x32_bf16 v[116:119], v[174:177], v[190:193], v[116:119]
	v_mfma_f32_16x16x32_bf16 v[112:115], v[182:185], v[190:193], v[112:115]
	v_mfma_f32_16x16x32_bf16 v[100:103], v[174:177], v[200:203], v[100:103]
	v_mfma_f32_16x16x32_bf16 v[96:99], v[182:185], v[200:203], v[96:99]
	v_mfma_f32_16x16x32_bf16 v[84:87], v[174:177], v[208:211], v[84:87]
	v_mfma_f32_16x16x32_bf16 v[80:83], v[182:185], v[208:211], v[80:83]
	v_mfma_f32_16x16x32_bf16 v[68:71], v[174:177], v[216:219], v[68:71]
	v_mfma_f32_16x16x32_bf16 v[64:67], v[182:185], v[216:219], v[64:67]
	s_barrier
; #define PG8_STAGE_T(bufoff, gbase, voff, AUX) do { _Pragma("unroll") for (int _i = 0; _i < 2; ++_i) \
;         __builtin_amdgcn_global_load_lds((const unsigned*)((const char*)(gbase) + (voff)[_i]), (PG8_LAS unsigned*)(lds + (bufoff) + ldsw + _i * 8192), 16, 0, AUX); } while (0)
; #define PG8_LDA(dst, b, h) do { _Pragma("unroll") for (int m = 0; m < 4; ++m) _Pragma("unroll") for (int k = 0; k < 2; ++k) dst[m][k] = *(const PG8_LAS bf16x8*)(lds + PG8_SA(b, h) + aoff + m * 2048 + k * 1024); } while (0)
; #define PG8_MMA(ai, bj, At, Bt) do { __builtin_amdgcn_s_setprio(1); _Pragma("unroll") for (int m = 0; m < 4; ++m) _Pragma("unroll") for (int n = 0; n < 2; ++n) _Pragma("unroll") for (int k = 0; k < 2; ++k) \
;         acc[ai][bj][m][n] = __builtin_amdgcn_mfma_f32_16x16x32_bf16(Bt[n][k], At[m][k], acc[ai][bj][m][n], 0, 0, 0); __builtin_amdgcn_s_setprio(0); } while (0)
; #define PG8_WAIT_V(n) asm volatile("s_waitcnt vmcnt(" #n ")" ::: "memory")
; #define PG8_WAIT_L(n) asm volatile("s_waitcnt lgkmcnt(" #n ")" ::: "memory")
; #define PG8_BAR __builtin_amdgcn_s_barrier()
; #define PG8_SCHED __builtin_amdgcn_sched_barrier(0)
;     ...
;             PG8_LDA(At, 1, 1); PG8_STAGE_T(PG8_SB(1, 0), b3, voffB, AUX_B); PG8_STAGE_T(PG8_SB(1, 1), b3 + hstep, voffB, AUX_B); PG8_STAGE_T(PG8_SA(1, 0), a3, voffA, AUX_A);
;             PG8_WAIT_V(8); PG8_WAIT_L(0); PG8_BAR; PG8_MMA(1, 0, At, B0); PG8_MMA(1, 1, At, B1); PG8_BAR; PG8_SCHED;
	s_add_i32 s36, s56, s38
	v_lshl_add_u64 v[144:145], v[144:145], 0, s[12:13]
	s_mov_b32 m0, s36
	ds_read_b128 v[186:189], v151 offset:49152
	ds_read_b128 v[190:193], v151 offset:50176
	ds_read_b128 v[196:199], v151 offset:51200
	ds_read_b128 v[200:203], v151 offset:52224
	ds_read_b128 v[204:207], v151 offset:53248
	ds_read_b128 v[208:211], v151 offset:54272
	ds_read_b128 v[212:215], v151 offset:55296
	ds_read_b128 v[216:219], v151 offset:56320
	global_load_lds_dwordx4 v[144:145], off
	s_add_i32 m0, s36, 0x2000
	s_add_u32 s26, s26, 0xb0080
	v_lshl_add_u64 v[144:145], v[220:221], 0, s[12:13]
	s_addc_u32 s27, s27, 0
	s_add_i32 s36, s57, s38
	global_load_lds_dwordx4 v[144:145], off
	v_lshl_add_u64 v[144:145], s[26:27], 0, v[130:131]
	s_mov_b32 m0, s36
	s_nop 0
	global_load_lds_dwordx4 v[144:145], off
	v_lshl_add_u64 v[144:145], s[26:27], 0, v[134:135]
	s_add_i32 m0, s36, 0x2000
	s_nop 0
	global_load_lds_dwordx4 v[144:145], off
	v_lshl_add_u64 v[144:145], v[222:223], 0, s[12:13]
	s_mov_b32 m0, s43
	s_nop 0
	global_load_lds_dwordx4 v[144:145], off
	v_lshl_add_u64 v[144:145], v[224:225], 0, s[12:13]
	s_mov_b32 m0, s44
	s_nop 0
	global_load_lds_dwordx4 v[144:145], off
	s_waitcnt vmcnt(8)
	s_waitcnt lgkmcnt(0)
	s_barrier
	s_waitcnt lgkmcnt(0)
	v_mfma_f32_16x16x32_bf16 v[60:63], v[154:157], v[186:189], v[60:63]
	v_mfma_f32_16x16x32_bf16 v[56:59], v[162:165], v[186:189], v[56:59]
	v_mfma_f32_16x16x32_bf16 v[44:47], v[154:157], v[196:199], v[44:47]
	v_mfma_f32_16x16x32_bf16 v[40:43], v[162:165], v[196:199], v[40:43]
	v_mfma_f32_16x16x32_bf16 v[28:31], v[154:157], v[204:207], v[28:31]
	v_mfma_f32_16x16x32_bf16 v[24:27], v[162:165], v[204:207], v[24:27]
	v_mfma_f32_16x16x32_bf16 v[12:15], v[154:157], v[212:215], v[12:15]
	v_mfma_f32_16x16x32_bf16 v[8:11], v[162:165], v[212:215], v[8:11]
	v_mfma_f32_16x16x32_bf16 v[60:63], v[158:161], v[190:193], v[60:63]
	v_mfma_f32_16x16x32_bf16 v[56:59], v[166:169], v[190:193], v[56:59]
	v_mfma_f32_16x16x32_bf16 v[44:47], v[158:161], v[200:203], v[44:47]
	v_mfma_f32_16x16x32_bf16 v[40:43], v[166:169], v[200:203], v[40:43]
	v_mfma_f32_16x16x32_bf16 v[28:31], v[158:161], v[208:211], v[28:31]
	v_mfma_f32_16x16x32_bf16 v[24:27], v[166:169], v[208:211], v[24:27]
	v_mfma_f32_16x16x32_bf16 v[12:15], v[158:161], v[216:219], v[12:15]
	v_mfma_f32_16x16x32_bf16 v[8:11], v[166:169], v[216:219], v[8:11]
	v_mfma_f32_16x16x32_bf16 v[52:55], v[170:173], v[186:189], v[52:55]
	v_mfma_f32_16x16x32_bf16 v[48:51], v[178:181], v[186:189], v[48:51]
	v_mfma_f32_16x16x32_bf16 v[36:39], v[170:173], v[196:199], v[36:39]
	v_mfma_f32_16x16x32_bf16 v[32:35], v[178:181], v[196:199], v[32:35]
	v_mfma_f32_16x16x32_bf16 v[20:23], v[170:173], v[204:207], v[20:23]
	v_mfma_f32_16x16x32_bf16 v[16:19], v[178:181], v[204:207], v[16:19]
	v_mfma_f32_16x16x32_bf16 v[4:7], v[170:173], v[212:215], v[4:7]
	v_mfma_f32_16x16x32_bf16 v[0:3], v[178:181], v[212:215], v[0:3]
	v_mfma_f32_16x16x32_bf16 v[52:55], v[174:177], v[190:193], v[52:55]
	v_mfma_f32_16x16x32_bf16 v[48:51], v[182:185], v[190:193], v[48:51]
	v_mfma_f32_16x16x32_bf16 v[36:39], v[174:177], v[200:203], v[36:39]
	v_mfma_f32_16x16x32_bf16 v[32:35], v[182:185], v[200:203], v[32:35]
	v_mfma_f32_16x16x32_bf16 v[20:23], v[174:177], v[208:211], v[20:23]
	v_mfma_f32_16x16x32_bf16 v[16:19], v[182:185], v[208:211], v[16:19]
	v_mfma_f32_16x16x32_bf16 v[4:7], v[174:177], v[216:219], v[4:7]
	v_mfma_f32_16x16x32_bf16 v[0:3], v[182:185], v[216:219], v[0:3]
	s_barrier
	s_add_i32 s55, s55, 2
	s_add_u32 s24, s24, 0x100
	s_addc_u32 s25, s25, 0
	s_add_u32 s53, s53, 0x100
	s_addc_u32 s54, s54, 0
	s_cmp_gt_u32 s55, 41
	s_cbranch_scc0 .LBB0_1156
	s_and_b64 vcc, exec, s[14:15]
	s_cbranch_vccz .LBB0_1159
	s_barrier

; #define PG8_STAGE_T(bufoff, gbase, voff, AUX) do { _Pragma("unroll") for (int _i = 0; _i < 2; ++_i) \
;         __builtin_amdgcn_global_load_lds((const unsigned*)((const char*)(gbase) + (voff)[_i]), (PG8_LAS unsigned*)(lds + (bufoff) + ldsw + _i * 8192), 16, 0, AUX); } while (0)
; #define PG8_LDA(dst, b, h) do { _Pragma("unroll") for (int m = 0; m < 4; ++m) _Pragma("unroll") for (int k = 0; k < 2; ++k) dst[m][k] = *(const PG8_LAS bf16x8*)(lds + PG8_SA(b, h) + aoff + m * 2048 + k * 1024); } while (0)
; #define PG8_LDB(dst, b, h) do { _Pragma("unroll") for (int n = 0; n < 2; ++n) _Pragma("unroll") for (int k = 0; k < 2; ++k) dst[n][k] = *(const PG8_LAS bf16x8*)(lds + PG8_SB(b, h) + boff + n * 2048 + k * 1024); } while (0)
; #define PG8_MMA(ai, bj, At, Bt) do { __builtin_amdgcn_s_setprio(1); _Pragma("unroll") for (int m = 0; m < 4; ++m) _Pragma("unroll") for (int n = 0; n < 2; ++n) _Pragma("unroll") for (int k = 0; k < 2; ++k) \
;         acc[ai][bj][m][n] = __builtin_amdgcn_mfma_f32_16x16x32_bf16(Bt[n][k], At[m][k], acc[ai][bj][m][n], 0, 0, 0); __builtin_amdgcn_s_setprio(0); } while (0)
; #define PG8_WAIT_V(n) asm volatile("s_waitcnt vmcnt(" #n ")" ::: "memory")
; #define PG8_WAIT_L(n) asm volatile("s_waitcnt lgkmcnt(" #n ")" ::: "memory")
; #define PG8_BAR __builtin_amdgcn_s_barrier()
; #define PG8_SCHED __builtin_amdgcn_sched_barrier(0)
;     ...
;             PG8_LDB(B0, 0, 0); PG8_LDB(B1, 0, 1); PG8_SCHED; PG8_LDA(At, 0, 0); if (!pe) { PG8_STAGE_T(PG8_SA(1, 1), a1 + hstep, voffA, AUX_A); }
;             if (!pe) { PG8_WAIT_V(8); } PG8_WAIT_L(0); PG8_BAR; PG8_MMA(0, 0, At, B0); PG8_MMA(0, 1, At, B1); PG8_BAR; PG8_SCHED;
;             PG8_LDA(At, 0, 1); PG8_STAGE_T(PG8_SB(0, 0), b2, voffB, AUX_B); PG8_STAGE_T(PG8_SB(0, 1), b2 + hstep, voffB, AUX_B); PG8_STAGE_T(PG8_SA(0, 0), a2, voffA, AUX_A);
;             if (!pe) { PG8_WAIT_V(8); } PG8_WAIT_L(0); PG8_BAR; PG8_MMA(1, 0, At, B0); PG8_MMA(1, 1, At, B1); PG8_BAR; PG8_SCHED;
.LBB0_1353:
	ds_read_b128 v[144:147], v162
	ds_read_b128 v[148:151], v162 offset:1024
	ds_read_b128 v[152:155], v162 offset:2048
	ds_read_b128 v[166:169], v162 offset:3072
	ds_read_b128 v[170:173], v163
	ds_read_b128 v[174:177], v163 offset:1024
	ds_read_b128 v[178:181], v163 offset:2048
	ds_read_b128 v[182:185], v163 offset:3072
	s_add_u32 s44, s42, 0xfffc0080
	s_addc_u32 s45, s43, -1
	s_cmp_eq_u32 s70, 12
	s_cselect_b32 s47, s25, s45
	s_cselect_b32 s46, s41, s44
	s_cselect_b32 s45, s27, s69
	s_cselect_b32 s44, s67, s68
	v_lshl_add_u64 v[156:157], s[42:43], 0, v[136:137]
	s_add_i32 m0, s50, 0xc000
	ds_read_b128 v[186:189], v164
	ds_read_b128 v[190:193], v164 offset:1024
	ds_read_b128 v[196:199], v164 offset:2048
	ds_read_b128 v[200:203], v164 offset:3072
	ds_read_b128 v[204:207], v164 offset:4096
	ds_read_b128 v[208:211], v164 offset:5120
	ds_read_b128 v[212:215], v164 offset:6144
	ds_read_b128 v[216:219], v164 offset:7168
	global_load_lds_dwordx4 v[156:157], off
	v_lshl_add_u64 v[156:157], s[42:43], 0, v[138:139]
	s_add_i32 m0, s50, 0xe000
	s_nop 0
	global_load_lds_dwordx4 v[156:157], off
	s_waitcnt vmcnt(8)
	s_waitcnt lgkmcnt(0)
	s_barrier
	s_waitcnt lgkmcnt(0)
	v_mfma_f32_16x16x32_bf16 v[124:127], v[144:147], v[186:189], v[124:127]
	v_mfma_f32_16x16x32_bf16 v[120:123], v[152:155], v[186:189], v[120:123]
	v_mfma_f32_16x16x32_bf16 v[108:111], v[144:147], v[196:199], v[108:111]
	v_mfma_f32_16x16x32_bf16 v[104:107], v[152:155], v[196:199], v[104:107]
	v_mfma_f32_16x16x32_bf16 v[92:95], v[144:147], v[204:207], v[92:95]
	v_mfma_f32_16x16x32_bf16 v[88:91], v[152:155], v[204:207], v[88:91]
	v_mfma_f32_16x16x32_bf16 v[76:79], v[144:147], v[212:215], v[76:79]
	v_mfma_f32_16x16x32_bf16 v[72:75], v[152:155], v[212:215], v[72:75]
	v_mfma_f32_16x16x32_bf16 v[124:127], v[148:151], v[190:193], v[124:127]
	v_mfma_f32_16x16x32_bf16 v[120:123], v[166:169], v[190:193], v[120:123]
	v_mfma_f32_16x16x32_bf16 v[108:111], v[148:151], v[200:203], v[108:111]
	v_mfma_f32_16x16x32_bf16 v[104:107], v[166:169], v[200:203], v[104:107]
	v_mfma_f32_16x16x32_bf16 v[92:95], v[148:151], v[208:211], v[92:95]
	v_mfma_f32_16x16x32_bf16 v[88:91], v[166:169], v[208:211], v[88:91]
	v_mfma_f32_16x16x32_bf16 v[76:79], v[148:151], v[216:219], v[76:79]
	v_mfma_f32_16x16x32_bf16 v[72:75], v[166:169], v[216:219], v[72:75]
	v_mfma_f32_16x16x32_bf16 v[116:119], v[170:173], v[186:189], v[116:119]
	v_mfma_f32_16x16x32_bf16 v[112:115], v[178:181], v[186:189], v[112:115]
	v_mfma_f32_16x16x32_bf16 v[100:103], v[170:173], v[196:199], v[100:103]
	v_mfma_f32_16x16x32_bf16 v[96:99], v[178:181], v[196:199], v[96:99]
	v_mfma_f32_16x16x32_bf16 v[84:87], v[170:173], v[204:207], v[84:87]
	v_mfma_f32_16x16x32_bf16 v[80:83], v[178:181], v[204:207], v[80:83]
	v_mfma_f32_16x16x32_bf16 v[68:71], v[170:173], v[212:215], v[68:71]
	v_mfma_f32_16x16x32_bf16 v[64:67], v[178:181], v[212:215], v[64:67]
	v_mfma_f32_16x16x32_bf16 v[116:119], v[174:177], v[190:193], v[116:119]
	v_mfma_f32_16x16x32_bf16 v[112:115], v[182:185], v[190:193], v[112:115]
	v_mfma_f32_16x16x32_bf16 v[100:103], v[174:177], v[200:203], v[100:103]
	v_mfma_f32_16x16x32_bf16 v[96:99], v[182:185], v[200:203], v[96:99]
	v_mfma_f32_16x16x32_bf16 v[84:87], v[174:177], v[208:211], v[84:87]
	v_mfma_f32_16x16x32_bf16 v[80:83], v[182:185], v[208:211], v[80:83]
	v_mfma_f32_16x16x32_bf16 v[68:71], v[174:177], v[216:219], v[68:71]
	v_mfma_f32_16x16x32_bf16 v[64:67], v[182:185], v[216:219], v[64:67]
	s_barrier
	s_add_i32 s71, s57, s49
	v_lshl_add_u64 v[156:157], s[44:45], 0, v[130:131]
	s_mov_b32 m0, s71
	ds_read_b128 v[186:189], v164 offset:16384
	ds_read_b128 v[190:193], v164 offset:17408
	ds_read_b128 v[196:199], v164 offset:18432
	ds_read_b128 v[200:203], v164 offset:19456
	ds_read_b128 v[204:207], v164 offset:20480
	ds_read_b128 v[208:211], v164 offset:21504
	ds_read_b128 v[212:215], v164 offset:22528
	ds_read_b128 v[216:219], v164 offset:23552
	global_load_lds_dwordx4 v[156:157], off
	s_add_i32 m0, s71, 0x2000
	s_add_u32 s76, s44, 0x40000
	v_lshl_add_u64 v[220:221], s[44:45], 0, v[134:135]
	s_addc_u32 s77, s45, 0
	s_add_i32 s71, s58, s49
	global_load_lds_dwordx4 v[220:221], off
	v_lshl_add_u64 v[222:223], s[76:77], 0, v[130:131]
	s_mov_b32 m0, s71
	v_lshl_add_u64 v[224:225], s[46:47], 0, v[132:133]
	global_load_lds_dwordx4 v[222:223], off
	v_lshl_add_u64 v[222:223], s[76:77], 0, v[134:135]
	s_add_i32 m0, s71, 0x2000
	s_nop 0
	global_load_lds_dwordx4 v[222:223], off
	v_lshl_add_u64 v[222:223], s[46:47], 0, v[128:129]
	s_mov_b32 m0, s50
	s_nop 0
	global_load_lds_dwordx4 v[222:223], off
	s_mov_b32 m0, s51
	s_nop 0
	global_load_lds_dwordx4 v[224:225], off
	s_waitcnt vmcnt(8)
	s_waitcnt lgkmcnt(0)
	s_barrier
; #define PG8_STAGE_T(bufoff, gbase, voff, AUX) do { _Pragma("unroll") for (int _i = 0; _i < 2; ++_i) \
;         __builtin_amdgcn_global_load_lds((const unsigned*)((const char*)(gbase) + (voff)[_i]), (PG8_LAS unsigned*)(lds + (bufoff) + ldsw + _i * 8192), 16, 0, AUX); } while (0)
; #define PG8_LDA(dst, b, h) do { _Pragma("unroll") for (int m = 0; m < 4; ++m) _Pragma("unroll") for (int k = 0; k < 2; ++k) dst[m][k] = *(const PG8_LAS bf16x8*)(lds + PG8_SA(b, h) + aoff + m * 2048 + k * 1024); } while (0)
; #define PG8_LDB(dst, b, h) do { _Pragma("unroll") for (int n = 0; n < 2; ++n) _Pragma("unroll") for (int k = 0; k < 2; ++k) dst[n][k] = *(const PG8_LAS bf16x8*)(lds + PG8_SB(b, h) + boff + n * 2048 + k * 1024); } while (0)
; #define PG8_MMA(ai, bj, At, Bt) do { __builtin_amdgcn_s_setprio(1); _Pragma("unroll") for (int m = 0; m < 4; ++m) _Pragma("unroll") for (int n = 0; n < 2; ++n) _Pragma("unroll") for (int k = 0; k < 2; ++k) \
;         acc[ai][bj][m][n] = __builtin_amdgcn_mfma_f32_16x16x32_bf16(Bt[n][k], At[m][k], acc[ai][bj][m][n], 0, 0, 0); __builtin_amdgcn_s_setprio(0); } while (0)
; #define PG8_WAIT_V(n) asm volatile("s_waitcnt vmcnt(" #n ")" ::: "memory")
; #define PG8_WAIT_L(n) asm volatile("s_waitcnt lgkmcnt(" #n ")" ::: "memory")
; #define PG8_BAR __builtin_amdgcn_s_barrier()
; #define PG8_SCHED __builtin_amdgcn_sched_barrier(0)
;     ...
;             if (!pe) { PG8_WAIT_V(8); } PG8_WAIT_L(0); PG8_BAR; PG8_MMA(1, 0, At, B0); PG8_MMA(1, 1, At, B1); PG8_BAR; PG8_SCHED;
;             PG8_LDB(B0, 1, 0); PG8_LDB(B1, 1, 1); PG8_SCHED; PG8_LDA(At, 1, 0); PG8_STAGE_T(PG8_SA(0, 1), a2 + hstep, voffA, AUX_A);
;             if (!pe) { PG8_WAIT_V(8); } PG8_WAIT_L(0); PG8_BAR; PG8_MMA(0, 0, At, B0); PG8_MMA(0, 1, At, B1); PG8_BAR; PG8_SCHED;
	s_waitcnt lgkmcnt(0)
	v_mfma_f32_16x16x32_bf16 v[60:63], v[144:147], v[186:189], v[60:63]
	v_mfma_f32_16x16x32_bf16 v[56:59], v[152:155], v[186:189], v[56:59]
	v_mfma_f32_16x16x32_bf16 v[44:47], v[144:147], v[196:199], v[44:47]
	v_mfma_f32_16x16x32_bf16 v[40:43], v[152:155], v[196:199], v[40:43]
	v_mfma_f32_16x16x32_bf16 v[28:31], v[144:147], v[204:207], v[28:31]
	v_mfma_f32_16x16x32_bf16 v[24:27], v[152:155], v[204:207], v[24:27]
	v_mfma_f32_16x16x32_bf16 v[12:15], v[144:147], v[212:215], v[12:15]
	v_mfma_f32_16x16x32_bf16 v[8:11], v[152:155], v[212:215], v[8:11]
	v_mfma_f32_16x16x32_bf16 v[60:63], v[148:151], v[190:193], v[60:63]
	v_mfma_f32_16x16x32_bf16 v[56:59], v[166:169], v[190:193], v[56:59]
	v_mfma_f32_16x16x32_bf16 v[44:47], v[148:151], v[200:203], v[44:47]
	v_mfma_f32_16x16x32_bf16 v[40:43], v[166:169], v[200:203], v[40:43]
	v_mfma_f32_16x16x32_bf16 v[28:31], v[148:151], v[208:211], v[28:31]
	v_mfma_f32_16x16x32_bf16 v[24:27], v[166:169], v[208:211], v[24:27]
	v_mfma_f32_16x16x32_bf16 v[12:15], v[148:151], v[216:219], v[12:15]
	v_mfma_f32_16x16x32_bf16 v[8:11], v[166:169], v[216:219], v[8:11]
	v_mfma_f32_16x16x32_bf16 v[52:55], v[170:173], v[186:189], v[52:55]
	v_mfma_f32_16x16x32_bf16 v[48:51], v[178:181], v[186:189], v[48:51]
	v_mfma_f32_16x16x32_bf16 v[36:39], v[170:173], v[196:199], v[36:39]
	v_mfma_f32_16x16x32_bf16 v[32:35], v[178:181], v[196:199], v[32:35]
	v_mfma_f32_16x16x32_bf16 v[20:23], v[170:173], v[204:207], v[20:23]
	v_mfma_f32_16x16x32_bf16 v[16:19], v[178:181], v[204:207], v[16:19]
	v_mfma_f32_16x16x32_bf16 v[4:7], v[170:173], v[212:215], v[4:7]
	v_mfma_f32_16x16x32_bf16 v[0:3], v[178:181], v[212:215], v[0:3]
	v_mfma_f32_16x16x32_bf16 v[52:55], v[174:177], v[190:193], v[52:55]
	v_mfma_f32_16x16x32_bf16 v[48:51], v[182:185], v[190:193], v[48:51]
	v_mfma_f32_16x16x32_bf16 v[36:39], v[174:177], v[200:203], v[36:39]
	v_mfma_f32_16x16x32_bf16 v[32:35], v[182:185], v[200:203], v[32:35]
	v_mfma_f32_16x16x32_bf16 v[20:23], v[174:177], v[208:211], v[20:23]
	v_mfma_f32_16x16x32_bf16 v[16:19], v[182:185], v[208:211], v[16:19]
	v_mfma_f32_16x16x32_bf16 v[4:7], v[174:177], v[216:219], v[4:7]
	v_mfma_f32_16x16x32_bf16 v[0:3], v[182:185], v[216:219], v[0:3]
	s_barrier
	s_add_i32 s71, 0, 0x18000
	v_add_u32_e32 v165, s71, v159
	s_add_i32 s76, 0, 0x1c000
	ds_read_b128 v[144:147], v165
	ds_read_b128 v[148:151], v165 offset:1024
	ds_read_b128 v[152:155], v165 offset:2048
	ds_read_b128 v[166:169], v165 offset:3072
	v_add_u32_e32 v165, s76, v159
	ds_read_b128 v[170:173], v165
	ds_read_b128 v[174:177], v165 offset:1024
	ds_read_b128 v[178:181], v165 offset:2048
	ds_read_b128 v[182:185], v165 offset:3072
	s_add_u32 s46, s46, 0x40000
	s_addc_u32 s47, s47, 0
	s_mov_b32 m0, s52
	v_lshl_add_u64 v[226:227], s[46:47], 0, v[128:129]
	ds_read_b128 v[186:189], v164 offset:32768
	ds_read_b128 v[190:193], v164 offset:33792
	ds_read_b128 v[196:199], v164 offset:34816
	ds_read_b128 v[200:203], v164 offset:35840
	ds_read_b128 v[204:207], v164 offset:36864
	ds_read_b128 v[208:211], v164 offset:37888
	ds_read_b128 v[212:215], v164 offset:38912
	ds_read_b128 v[216:219], v164 offset:39936
	global_load_lds_dwordx4 v[226:227], off
	v_lshl_add_u64 v[226:227], s[46:47], 0, v[132:133]
	s_mov_b32 m0, s53
	s_nop 0
	global_load_lds_dwordx4 v[226:227], off
	s_waitcnt vmcnt(8)
	s_waitcnt lgkmcnt(0)
	s_barrier
	s_waitcnt lgkmcnt(0)
	v_mfma_f32_16x16x32_bf16 v[124:127], v[144:147], v[186:189], v[124:127]
	v_mfma_f32_16x16x32_bf16 v[120:123], v[152:155], v[186:189], v[120:123]
	v_mfma_f32_16x16x32_bf16 v[108:111], v[144:147], v[196:199], v[108:111]
	v_mfma_f32_16x16x32_bf16 v[104:107], v[152:155], v[196:199], v[104:107]
	v_mfma_f32_16x16x32_bf16 v[92:95], v[144:147], v[204:207], v[92:95]
	v_mfma_f32_16x16x32_bf16 v[88:91], v[152:155], v[204:207], v[88:91]
	v_mfma_f32_16x16x32_bf16 v[76:79], v[144:147], v[212:215], v[76:79]
	v_mfma_f32_16x16x32_bf16 v[72:75], v[152:155], v[212:215], v[72:75]
	v_mfma_f32_16x16x32_bf16 v[124:127], v[148:151], v[190:193], v[124:127]
	v_mfma_f32_16x16x32_bf16 v[120:123], v[166:169], v[190:193], v[120:123]
	v_mfma_f32_16x16x32_bf16 v[108:111], v[148:151], v[200:203], v[108:111]
	v_mfma_f32_16x16x32_bf16 v[104:107], v[166:169], v[200:203], v[104:107]
	v_mfma_f32_16x16x32_bf16 v[92:95], v[148:151], v[208:211], v[92:95]
	v_mfma_f32_16x16x32_bf16 v[88:91], v[166:169], v[208:211], v[88:91]
	v_mfma_f32_16x16x32_bf16 v[76:79], v[148:151], v[216:219], v[76:79]
	v_mfma_f32_16x16x32_bf16 v[72:75], v[166:169], v[216:219], v[72:75]
	v_mfma_f32_16x16x32_bf16 v[116:119], v[170:173], v[186:189], v[116:119]
	v_mfma_f32_16x16x32_bf16 v[112:115], v[178:181], v[186:189], v[112:115]
	v_mfma_f32_16x16x32_bf16 v[100:103], v[170:173], v[196:199], v[100:103]
	v_mfma_f32_16x16x32_bf16 v[96:99], v[178:181], v[196:199], v[96:99]
	v_mfma_f32_16x16x32_bf16 v[84:87], v[170:173], v[204:207], v[84:87]
	v_mfma_f32_16x16x32_bf16 v[80:83], v[178:181], v[204:207], v[80:83]
	v_mfma_f32_16x16x32_bf16 v[68:71], v[170:173], v[212:215], v[68:71]
	v_mfma_f32_16x16x32_bf16 v[64:67], v[178:181], v[212:215], v[64:67]
	v_mfma_f32_16x16x32_bf16 v[116:119], v[174:177], v[190:193], v[116:119]
	v_mfma_f32_16x16x32_bf16 v[112:115], v[182:185], v[190:193], v[112:115]
	v_mfma_f32_16x16x32_bf16 v[100:103], v[174:177], v[200:203], v[100:103]
	v_mfma_f32_16x16x32_bf16 v[96:99], v[182:185], v[200:203], v[96:99]
	v_mfma_f32_16x16x32_bf16 v[84:87], v[174:177], v[208:211], v[84:87]
	v_mfma_f32_16x16x32_bf16 v[80:83], v[182:185], v[208:211], v[80:83]
	v_mfma_f32_16x16x32_bf16 v[68:71], v[174:177], v[216:219], v[68:71]
	v_mfma_f32_16x16x32_bf16 v[64:67], v[182:185], v[216:219], v[64:67]
	s_barrier
; #define PG8_STAGE_T(bufoff, gbase, voff, AUX) do { _Pragma("unroll") for (int _i = 0; _i < 2; ++_i) \
;         __builtin_amdgcn_global_load_lds((const unsigned*)((const char*)(gbase) + (voff)[_i]), (PG8_LAS unsigned*)(lds + (bufoff) + ldsw + _i * 8192), 16, 0, AUX); } while (0)
; #define PG8_LDA(dst, b, h) do { _Pragma("unroll") for (int m = 0; m < 4; ++m) _Pragma("unroll") for (int k = 0; k < 2; ++k) dst[m][k] = *(const PG8_LAS bf16x8*)(lds + PG8_SA(b, h) + aoff + m * 2048 + k * 1024); } while (0)
; #define PG8_MMA(ai, bj, At, Bt) do { __builtin_amdgcn_s_setprio(1); _Pragma("unroll") for (int m = 0; m < 4; ++m) _Pragma("unroll") for (int n = 0; n < 2; ++n) _Pragma("unroll") for (int k = 0; k < 2; ++k) \
;         acc[ai][bj][m][n] = __builtin_amdgcn_mfma_f32_16x16x32_bf16(Bt[n][k], At[m][k], acc[ai][bj][m][n], 0, 0, 0); __builtin_amdgcn_s_setprio(0); } while (0)
; #define PG8_WAIT_V(n) asm volatile("s_waitcnt vmcnt(" #n ")" ::: "memory")
; #define PG8_WAIT_L(n) asm volatile("s_waitcnt lgkmcnt(" #n ")" ::: "memory")
; #define PG8_BAR __builtin_amdgcn_s_barrier()
; #define PG8_SCHED __builtin_amdgcn_sched_barrier(0)
;     ...
;         for (int t = 0; t < nt; t += 2) {
;             const bool last = (t == nt - 2);
;     ...
;             PG8_LDA(At, 1, 1); PG8_STAGE_T(PG8_SB(1, 0), b3, voffB, AUX_B); PG8_STAGE_T(PG8_SB(1, 1), b3 + hstep, voffB, AUX_B); PG8_STAGE_T(PG8_SA(1, 0), a3, voffA, AUX_A);
;             PG8_WAIT_V(8); PG8_WAIT_L(0); PG8_BAR; PG8_MMA(1, 0, At, B0); PG8_MMA(1, 1, At, B1); PG8_BAR; PG8_SCHED;
	s_add_i32 s46, s71, s49
	v_lshl_add_u64 v[156:157], v[156:157], 0, s[8:9]
	s_mov_b32 m0, s46
	ds_read_b128 v[186:189], v164 offset:49152
	ds_read_b128 v[190:193], v164 offset:50176
	ds_read_b128 v[196:199], v164 offset:51200
	ds_read_b128 v[200:203], v164 offset:52224
	ds_read_b128 v[204:207], v164 offset:53248
	ds_read_b128 v[208:211], v164 offset:54272
	ds_read_b128 v[212:215], v164 offset:55296
	ds_read_b128 v[216:219], v164 offset:56320
	global_load_lds_dwordx4 v[156:157], off
	s_add_i32 m0, s46, 0x2000
	s_add_u32 s44, s44, 0x40080
	v_lshl_add_u64 v[156:157], v[220:221], 0, s[8:9]
	s_addc_u32 s45, s45, 0
	s_add_i32 s46, s76, s49
	global_load_lds_dwordx4 v[156:157], off
	v_lshl_add_u64 v[156:157], s[44:45], 0, v[130:131]
	s_mov_b32 m0, s46
	s_nop 0
	global_load_lds_dwordx4 v[156:157], off
	v_lshl_add_u64 v[156:157], s[44:45], 0, v[134:135]
	s_add_i32 m0, s46, 0x2000
	s_nop 0
	global_load_lds_dwordx4 v[156:157], off
	v_lshl_add_u64 v[156:157], v[222:223], 0, s[8:9]
	s_mov_b32 m0, s55
	s_nop 0
	global_load_lds_dwordx4 v[156:157], off
	v_lshl_add_u64 v[156:157], v[224:225], 0, s[8:9]
	s_mov_b32 m0, s56
	s_nop 0
	global_load_lds_dwordx4 v[156:157], off
	s_waitcnt vmcnt(8)
	s_waitcnt lgkmcnt(0)
	s_barrier
	s_waitcnt lgkmcnt(0)
	v_mfma_f32_16x16x32_bf16 v[60:63], v[144:147], v[186:189], v[60:63]
	v_mfma_f32_16x16x32_bf16 v[56:59], v[152:155], v[186:189], v[56:59]
	v_mfma_f32_16x16x32_bf16 v[44:47], v[144:147], v[196:199], v[44:47]
	v_mfma_f32_16x16x32_bf16 v[40:43], v[152:155], v[196:199], v[40:43]
	v_mfma_f32_16x16x32_bf16 v[28:31], v[144:147], v[204:207], v[28:31]
	v_mfma_f32_16x16x32_bf16 v[24:27], v[152:155], v[204:207], v[24:27]
	v_mfma_f32_16x16x32_bf16 v[12:15], v[144:147], v[212:215], v[12:15]
	v_mfma_f32_16x16x32_bf16 v[8:11], v[152:155], v[212:215], v[8:11]
	v_mfma_f32_16x16x32_bf16 v[60:63], v[148:151], v[190:193], v[60:63]
	v_mfma_f32_16x16x32_bf16 v[56:59], v[166:169], v[190:193], v[56:59]
	v_mfma_f32_16x16x32_bf16 v[44:47], v[148:151], v[200:203], v[44:47]
	v_mfma_f32_16x16x32_bf16 v[40:43], v[166:169], v[200:203], v[40:43]
	v_mfma_f32_16x16x32_bf16 v[28:31], v[148:151], v[208:211], v[28:31]
	v_mfma_f32_16x16x32_bf16 v[24:27], v[166:169], v[208:211], v[24:27]
	v_mfma_f32_16x16x32_bf16 v[12:15], v[148:151], v[216:219], v[12:15]
	v_mfma_f32_16x16x32_bf16 v[8:11], v[166:169], v[216:219], v[8:11]
	v_mfma_f32_16x16x32_bf16 v[52:55], v[170:173], v[186:189], v[52:55]
	v_mfma_f32_16x16x32_bf16 v[48:51], v[178:181], v[186:189], v[48:51]
	v_mfma_f32_16x16x32_bf16 v[36:39], v[170:173], v[196:199], v[36:39]
	v_mfma_f32_16x16x32_bf16 v[32:35], v[178:181], v[196:199], v[32:35]
	v_mfma_f32_16x16x32_bf16 v[20:23], v[170:173], v[204:207], v[20:23]
	v_mfma_f32_16x16x32_bf16 v[16:19], v[178:181], v[204:207], v[16:19]
	v_mfma_f32_16x16x32_bf16 v[4:7], v[170:173], v[212:215], v[4:7]
	v_mfma_f32_16x16x32_bf16 v[0:3], v[178:181], v[212:215], v[0:3]
	v_mfma_f32_16x16x32_bf16 v[52:55], v[174:177], v[190:193], v[52:55]
	v_mfma_f32_16x16x32_bf16 v[48:51], v[182:185], v[190:193], v[48:51]
	v_mfma_f32_16x16x32_bf16 v[36:39], v[174:177], v[200:203], v[36:39]
	v_mfma_f32_16x16x32_bf16 v[32:35], v[182:185], v[200:203], v[32:35]
	v_mfma_f32_16x16x32_bf16 v[20:23], v[174:177], v[208:211], v[20:23]
	v_mfma_f32_16x16x32_bf16 v[16:19], v[182:185], v[208:211], v[16:19]
	v_mfma_f32_16x16x32_bf16 v[4:7], v[174:177], v[216:219], v[4:7]
	v_mfma_f32_16x16x32_bf16 v[0:3], v[182:185], v[216:219], v[0:3]
	s_barrier
	s_add_i32 s70, s70, 2
	s_add_u32 s42, s42, 0x100
	s_addc_u32 s43, s43, 0
	s_add_u32 s68, s68, 0x100
	s_addc_u32 s69, s69, 0
	s_cmp_gt_u32 s70, 13
	s_cbranch_scc0 .LBB0_1353
	s_and_b64 vcc, exec, s[10:11]
	s_cbranch_vccz .LBB0_1356
	s_barrier

; #define PG8_STAGE_T(bufoff, gbase, voff, AUX) do { _Pragma("unroll") for (int _i = 0; _i < 2; ++_i) \
;         __builtin_amdgcn_global_load_lds((const unsigned*)((const char*)(gbase) + (voff)[_i]), (PG8_LAS unsigned*)(lds + (bufoff) + ldsw + _i * 8192), 16, 0, AUX); } while (0)
; #define PG8_LDA(dst, b, h) do { _Pragma("unroll") for (int m = 0; m < 4; ++m) _Pragma("unroll") for (int k = 0; k < 2; ++k) dst[m][k] = *(const PG8_LAS bf16x8*)(lds + PG8_SA(b, h) + aoff + m * 2048 + k * 1024); } while (0)
; #define PG8_LDB(dst, b, h) do { _Pragma("unroll") for (int n = 0; n < 2; ++n) _Pragma("unroll") for (int k = 0; k < 2; ++k) dst[n][k] = *(const PG8_LAS bf16x8*)(lds + PG8_SB(b, h) + boff + n * 2048 + k * 1024); } while (0)
; #define PG8_MMA(ai, bj, At, Bt) do { __builtin_amdgcn_s_setprio(1); _Pragma("unroll") for (int m = 0; m < 4; ++m) _Pragma("unroll") for (int n = 0; n < 2; ++n) _Pragma("unroll") for (int k = 0; k < 2; ++k) \
;         acc[ai][bj][m][n] = __builtin_amdgcn_mfma_f32_16x16x32_bf16(Bt[n][k], At[m][k], acc[ai][bj][m][n], 0, 0, 0); __builtin_amdgcn_s_setprio(0); } while (0)
; #define PG8_WAIT_V(n) asm volatile("s_waitcnt vmcnt(" #n ")" ::: "memory")
; #define PG8_WAIT_L(n) asm volatile("s_waitcnt lgkmcnt(" #n ")" ::: "memory")
; #define PG8_BAR __builtin_amdgcn_s_barrier()
;     ...
;             const bool last = (t == nt - 2);
;             const char* a1 = cA + (ptrdiff_t)(t + 1) * ck;
;             const char* a2 = last ? nA : cA + (ptrdiff_t)(t + 2) * ck; const char* b2 = last ? nB : cB + (ptrdiff_t)(t + 2) * ck;
;             const ptrdiff_t k3 = last ? nk : ck;
;             const char* a3 = a2 + k3; const char* b3 = b2 + k3;
;             if (last && has_next) S.a_ready(nxt);
;             if constexpr (SP2) {
;             int pei = 0; if constexpr (PEEL) { pei = __builtin_amdgcn_readfirstlane((t == 0 && ui > 0) ? 1 : 0); asm volatile("" : "+s"(pei)); }
;             const bool pe = pei != 0;
;             PG8_LDB(B0, 0, 0); PG8_LDB(B1, 0, 1); PG8_SCHED; PG8_LDA(At, 0, 0); if (!pe) { PG8_STAGE_T(PG8_SA(1, 1), a1 + hstep, voffA, AUX_A); }
;             if (!pe) { PG8_WAIT_V(8); } PG8_WAIT_L(0); PG8_BAR; PG8_MMA(0, 0, At, B0); PG8_MMA(0, 1, At, B1); PG8_BAR; PG8_SCHED;
;             PG8_LDA(At, 0, 1); PG8_STAGE_T(PG8_SB(0, 0), b2, voffB, AUX_B); PG8_STAGE_T(PG8_SB(0, 1), b2 + hstep, voffB, AUX_B); PG8_STAGE_T(PG8_SA(0, 0), a2, voffA, AUX_A);
.LBB0_1389:
	ds_read_b128 v[128:131], v173
	ds_read_b128 v[132:135], v173 offset:1024
	ds_read_b128 v[152:155], v173 offset:2048
	ds_read_b128 v[156:159], v173 offset:3072
	s_waitcnt lgkmcnt(0)
	ds_read_b128 v[160:163], v174
	ds_read_b128 v[164:167], v174 offset:1024
	ds_read_b128 v[178:181], v174 offset:2048
	ds_read_b128 v[182:185], v174 offset:3072
	s_add_i32 s61, s40, 2
	s_add_u32 s62, s38, 0x80
	s_addc_u32 s41, s39, 0
	s_cmp_eq_u32 s50, s40
	s_cselect_b32 s40, s6, s62
	s_cselect_b32 s41, s7, s41
	s_cselect_b32 s63, s37, s60
	s_cselect_b32 s62, s36, s59
	v_lshl_add_u64 v[168:169], s[38:39], 0, v[144:145]
	s_add_i32 m0, s43, 0xc000
	ds_read_b128 v[186:189], v175
	ds_read_b128 v[190:193], v175 offset:1024
	ds_read_b128 v[196:199], v175 offset:2048
	ds_read_b128 v[200:203], v175 offset:3072
	ds_read_b128 v[204:207], v175 offset:4096
	ds_read_b128 v[208:211], v175 offset:5120
	ds_read_b128 v[212:215], v175 offset:6144
	ds_read_b128 v[216:219], v175 offset:7168
	global_load_lds_dwordx4 v[168:169], off
	v_lshl_add_u64 v[168:169], s[38:39], 0, v[146:147]
	s_add_i32 m0, s43, 0xe000
	s_nop 0
	global_load_lds_dwordx4 v[168:169], off
	s_waitcnt vmcnt(8)
	s_waitcnt lgkmcnt(0)
	s_barrier
	s_waitcnt lgkmcnt(0)
	v_mfma_f32_16x16x32_bf16 v[124:127], v[128:131], v[186:189], v[124:127]
	v_mfma_f32_16x16x32_bf16 v[120:123], v[152:155], v[186:189], v[120:123]
	v_mfma_f32_16x16x32_bf16 v[108:111], v[128:131], v[196:199], v[108:111]
	v_mfma_f32_16x16x32_bf16 v[104:107], v[152:155], v[196:199], v[104:107]
	v_mfma_f32_16x16x32_bf16 v[92:95], v[128:131], v[204:207], v[92:95]
	v_mfma_f32_16x16x32_bf16 v[88:91], v[152:155], v[204:207], v[88:91]
	v_mfma_f32_16x16x32_bf16 v[76:79], v[128:131], v[212:215], v[76:79]
	v_mfma_f32_16x16x32_bf16 v[72:75], v[152:155], v[212:215], v[72:75]
	v_mfma_f32_16x16x32_bf16 v[124:127], v[132:135], v[190:193], v[124:127]
	v_mfma_f32_16x16x32_bf16 v[120:123], v[156:159], v[190:193], v[120:123]
	v_mfma_f32_16x16x32_bf16 v[108:111], v[132:135], v[200:203], v[108:111]
	v_mfma_f32_16x16x32_bf16 v[104:107], v[156:159], v[200:203], v[104:107]
	v_mfma_f32_16x16x32_bf16 v[92:95], v[132:135], v[208:211], v[92:95]
	v_mfma_f32_16x16x32_bf16 v[88:91], v[156:159], v[208:211], v[88:91]
	v_mfma_f32_16x16x32_bf16 v[76:79], v[132:135], v[216:219], v[76:79]
	v_mfma_f32_16x16x32_bf16 v[72:75], v[156:159], v[216:219], v[72:75]
	v_mfma_f32_16x16x32_bf16 v[116:119], v[160:163], v[186:189], v[116:119]
	v_mfma_f32_16x16x32_bf16 v[112:115], v[178:181], v[186:189], v[112:115]
	v_mfma_f32_16x16x32_bf16 v[100:103], v[160:163], v[196:199], v[100:103]
	v_mfma_f32_16x16x32_bf16 v[96:99], v[178:181], v[196:199], v[96:99]
	v_mfma_f32_16x16x32_bf16 v[84:87], v[160:163], v[204:207], v[84:87]
	v_mfma_f32_16x16x32_bf16 v[80:83], v[178:181], v[204:207], v[80:83]
	v_mfma_f32_16x16x32_bf16 v[68:71], v[160:163], v[212:215], v[68:71]
	v_mfma_f32_16x16x32_bf16 v[64:67], v[178:181], v[212:215], v[64:67]
	v_mfma_f32_16x16x32_bf16 v[116:119], v[164:167], v[190:193], v[116:119]
	v_mfma_f32_16x16x32_bf16 v[112:115], v[182:185], v[190:193], v[112:115]
	v_mfma_f32_16x16x32_bf16 v[100:103], v[164:167], v[200:203], v[100:103]
	v_mfma_f32_16x16x32_bf16 v[96:99], v[182:185], v[200:203], v[96:99]
	v_mfma_f32_16x16x32_bf16 v[84:87], v[164:167], v[208:211], v[84:87]
	v_mfma_f32_16x16x32_bf16 v[80:83], v[182:185], v[208:211], v[80:83]
	v_mfma_f32_16x16x32_bf16 v[68:71], v[164:167], v[216:219], v[68:71]
	v_mfma_f32_16x16x32_bf16 v[64:67], v[182:185], v[216:219], v[64:67]
	s_barrier
	s_add_i32 s64, s52, s42
	v_lshl_add_u64 v[168:169], s[62:63], 0, v[138:139]
	s_mov_b32 m0, s64
	ds_read_b128 v[186:189], v175 offset:16384
	ds_read_b128 v[190:193], v175 offset:17408
	ds_read_b128 v[196:199], v175 offset:18432
	ds_read_b128 v[200:203], v175 offset:19456
	ds_read_b128 v[204:207], v175 offset:20480
	ds_read_b128 v[208:211], v175 offset:21504
	ds_read_b128 v[212:215], v175 offset:22528
	ds_read_b128 v[216:219], v175 offset:23552
	global_load_lds_dwordx4 v[168:169], off
	s_add_i32 m0, s64, 0x2000
	v_lshl_add_u64 v[220:221], s[62:63], 0, v[142:143]
	s_add_u32 s62, s62, s10
	s_addc_u32 s63, s63, s11
	s_add_i32 s64, s53, s42
	global_load_lds_dwordx4 v[220:221], off
	v_lshl_add_u64 v[222:223], s[62:63], 0, v[138:139]
	s_mov_b32 m0, s64
	v_lshl_add_u64 v[224:225], s[62:63], 0, v[142:143]
	global_load_lds_dwordx4 v[222:223], off
	s_add_i32 m0, s64, 0x2000
	v_lshl_add_u64 v[226:227], s[40:41], 0, v[136:137]
	global_load_lds_dwordx4 v[224:225], off
	s_mov_b32 m0, s43
	v_lshl_add_u64 v[228:229], s[40:41], 0, v[140:141]
	global_load_lds_dwordx4 v[226:227], off
	s_mov_b32 m0, s44
	s_nop 0
	global_load_lds_dwordx4 v[228:229], off
	s_waitcnt vmcnt(8)
	s_waitcnt lgkmcnt(0)
	s_barrier
; #define PG8_STAGE_T(bufoff, gbase, voff, AUX) do { _Pragma("unroll") for (int _i = 0; _i < 2; ++_i) \
;         __builtin_amdgcn_global_load_lds((const unsigned*)((const char*)(gbase) + (voff)[_i]), (PG8_LAS unsigned*)(lds + (bufoff) + ldsw + _i * 8192), 16, 0, AUX); } while (0)
; #define PG8_LDA(dst, b, h) do { _Pragma("unroll") for (int m = 0; m < 4; ++m) _Pragma("unroll") for (int k = 0; k < 2; ++k) dst[m][k] = *(const PG8_LAS bf16x8*)(lds + PG8_SA(b, h) + aoff + m * 2048 + k * 1024); } while (0)
; #define PG8_LDB(dst, b, h) do { _Pragma("unroll") for (int n = 0; n < 2; ++n) _Pragma("unroll") for (int k = 0; k < 2; ++k) dst[n][k] = *(const PG8_LAS bf16x8*)(lds + PG8_SB(b, h) + boff + n * 2048 + k * 1024); } while (0)
; #define PG8_MMA(ai, bj, At, Bt) do { __builtin_amdgcn_s_setprio(1); _Pragma("unroll") for (int m = 0; m < 4; ++m) _Pragma("unroll") for (int n = 0; n < 2; ++n) _Pragma("unroll") for (int k = 0; k < 2; ++k) \
;         acc[ai][bj][m][n] = __builtin_amdgcn_mfma_f32_16x16x32_bf16(Bt[n][k], At[m][k], acc[ai][bj][m][n], 0, 0, 0); __builtin_amdgcn_s_setprio(0); } while (0)
; #define PG8_WAIT_V(n) asm volatile("s_waitcnt vmcnt(" #n ")" ::: "memory")
; #define PG8_WAIT_L(n) asm volatile("s_waitcnt lgkmcnt(" #n ")" ::: "memory")
; #define PG8_BAR __builtin_amdgcn_s_barrier()
; #define PG8_SCHED __builtin_amdgcn_sched_barrier(0)
;     ...
;             if (!pe) { PG8_WAIT_V(8); } PG8_WAIT_L(0); PG8_BAR; PG8_MMA(1, 0, At, B0); PG8_MMA(1, 1, At, B1); PG8_BAR; PG8_SCHED;
;             PG8_LDB(B0, 1, 0); PG8_LDB(B1, 1, 1); PG8_SCHED; PG8_LDA(At, 1, 0); PG8_STAGE_T(PG8_SA(0, 1), a2 + hstep, voffA, AUX_A);
;             if (!pe) { PG8_WAIT_V(8); } PG8_WAIT_L(0); PG8_BAR; PG8_MMA(0, 0, At, B0); PG8_MMA(0, 1, At, B1); PG8_BAR; PG8_SCHED;
	s_waitcnt lgkmcnt(0)
	v_mfma_f32_16x16x32_bf16 v[60:63], v[128:131], v[186:189], v[60:63]
	v_mfma_f32_16x16x32_bf16 v[56:59], v[152:155], v[186:189], v[56:59]
	v_mfma_f32_16x16x32_bf16 v[44:47], v[128:131], v[196:199], v[44:47]
	v_mfma_f32_16x16x32_bf16 v[40:43], v[152:155], v[196:199], v[40:43]
	v_mfma_f32_16x16x32_bf16 v[28:31], v[128:131], v[204:207], v[28:31]
	v_mfma_f32_16x16x32_bf16 v[24:27], v[152:155], v[204:207], v[24:27]
	v_mfma_f32_16x16x32_bf16 v[12:15], v[128:131], v[212:215], v[12:15]
	v_mfma_f32_16x16x32_bf16 v[8:11], v[152:155], v[212:215], v[8:11]
	v_mfma_f32_16x16x32_bf16 v[60:63], v[132:135], v[190:193], v[60:63]
	v_mfma_f32_16x16x32_bf16 v[56:59], v[156:159], v[190:193], v[56:59]
	v_mfma_f32_16x16x32_bf16 v[44:47], v[132:135], v[200:203], v[44:47]
	v_mfma_f32_16x16x32_bf16 v[40:43], v[156:159], v[200:203], v[40:43]
	v_mfma_f32_16x16x32_bf16 v[28:31], v[132:135], v[208:211], v[28:31]
	v_mfma_f32_16x16x32_bf16 v[24:27], v[156:159], v[208:211], v[24:27]
	v_mfma_f32_16x16x32_bf16 v[12:15], v[132:135], v[216:219], v[12:15]
	v_mfma_f32_16x16x32_bf16 v[8:11], v[156:159], v[216:219], v[8:11]
	v_mfma_f32_16x16x32_bf16 v[52:55], v[160:163], v[186:189], v[52:55]
	v_mfma_f32_16x16x32_bf16 v[48:51], v[178:181], v[186:189], v[48:51]
	v_mfma_f32_16x16x32_bf16 v[36:39], v[160:163], v[196:199], v[36:39]
	v_mfma_f32_16x16x32_bf16 v[32:35], v[178:181], v[196:199], v[32:35]
	v_mfma_f32_16x16x32_bf16 v[20:23], v[160:163], v[204:207], v[20:23]
	v_mfma_f32_16x16x32_bf16 v[16:19], v[178:181], v[204:207], v[16:19]
	v_mfma_f32_16x16x32_bf16 v[4:7], v[160:163], v[212:215], v[4:7]
	v_mfma_f32_16x16x32_bf16 v[0:3], v[178:181], v[212:215], v[0:3]
	v_mfma_f32_16x16x32_bf16 v[52:55], v[164:167], v[190:193], v[52:55]
	v_mfma_f32_16x16x32_bf16 v[48:51], v[182:185], v[190:193], v[48:51]
	v_mfma_f32_16x16x32_bf16 v[36:39], v[164:167], v[200:203], v[36:39]
	v_mfma_f32_16x16x32_bf16 v[32:35], v[182:185], v[200:203], v[32:35]
	v_mfma_f32_16x16x32_bf16 v[20:23], v[164:167], v[208:211], v[20:23]
	v_mfma_f32_16x16x32_bf16 v[16:19], v[182:185], v[208:211], v[16:19]
	v_mfma_f32_16x16x32_bf16 v[4:7], v[164:167], v[216:219], v[4:7]
	v_mfma_f32_16x16x32_bf16 v[0:3], v[182:185], v[216:219], v[0:3]
	s_barrier
	s_add_i32 s62, 0, 0x18000
	s_add_i32 s63, 0, 0x1c000
	v_add_u32_e32 v156, s62, v171
	v_add_u32_e32 v177, s63, v171
	ds_read_b128 v[128:131], v156
	ds_read_b128 v[132:135], v156 offset:1024
	ds_read_b128 v[152:155], v156 offset:2048
	ds_read_b128 v[156:159], v156 offset:3072
	ds_read_b128 v[160:163], v177
	ds_read_b128 v[164:167], v177 offset:1024
	ds_read_b128 v[178:181], v177 offset:2048
	ds_read_b128 v[182:185], v177 offset:3072
	s_add_u32 s40, s40, s10
	s_addc_u32 s41, s41, s11
	s_mov_b32 m0, s45
	v_lshl_add_u64 v[230:231], s[40:41], 0, v[136:137]
	ds_read_b128 v[186:189], v175 offset:32768
	ds_read_b128 v[190:193], v175 offset:33792
	ds_read_b128 v[196:199], v175 offset:34816
	ds_read_b128 v[200:203], v175 offset:35840
	ds_read_b128 v[204:207], v175 offset:36864
	ds_read_b128 v[208:211], v175 offset:37888
	ds_read_b128 v[212:215], v175 offset:38912
	ds_read_b128 v[216:219], v175 offset:39936
	global_load_lds_dwordx4 v[230:231], off
	v_lshl_add_u64 v[230:231], s[40:41], 0, v[140:141]
	s_mov_b32 m0, s46
	s_nop 0
	global_load_lds_dwordx4 v[230:231], off
	s_waitcnt vmcnt(8)
	s_waitcnt lgkmcnt(0)
	s_barrier
	s_waitcnt lgkmcnt(0)
	v_mfma_f32_16x16x32_bf16 v[124:127], v[128:131], v[186:189], v[124:127]
	v_mfma_f32_16x16x32_bf16 v[120:123], v[152:155], v[186:189], v[120:123]
	v_mfma_f32_16x16x32_bf16 v[108:111], v[128:131], v[196:199], v[108:111]
	v_mfma_f32_16x16x32_bf16 v[104:107], v[152:155], v[196:199], v[104:107]
	v_mfma_f32_16x16x32_bf16 v[92:95], v[128:131], v[204:207], v[92:95]
	v_mfma_f32_16x16x32_bf16 v[88:91], v[152:155], v[204:207], v[88:91]
	v_mfma_f32_16x16x32_bf16 v[76:79], v[128:131], v[212:215], v[76:79]
	v_mfma_f32_16x16x32_bf16 v[72:75], v[152:155], v[212:215], v[72:75]
	v_mfma_f32_16x16x32_bf16 v[124:127], v[132:135], v[190:193], v[124:127]
	v_mfma_f32_16x16x32_bf16 v[120:123], v[156:159], v[190:193], v[120:123]
	v_mfma_f32_16x16x32_bf16 v[108:111], v[132:135], v[200:203], v[108:111]
	v_mfma_f32_16x16x32_bf16 v[104:107], v[156:159], v[200:203], v[104:107]
	v_mfma_f32_16x16x32_bf16 v[92:95], v[132:135], v[208:211], v[92:95]
	v_mfma_f32_16x16x32_bf16 v[88:91], v[156:159], v[208:211], v[88:91]
	v_mfma_f32_16x16x32_bf16 v[76:79], v[132:135], v[216:219], v[76:79]
	v_mfma_f32_16x16x32_bf16 v[72:75], v[156:159], v[216:219], v[72:75]
	v_mfma_f32_16x16x32_bf16 v[116:119], v[160:163], v[186:189], v[116:119]
	v_mfma_f32_16x16x32_bf16 v[112:115], v[178:181], v[186:189], v[112:115]
	v_mfma_f32_16x16x32_bf16 v[100:103], v[160:163], v[196:199], v[100:103]
	v_mfma_f32_16x16x32_bf16 v[96:99], v[178:181], v[196:199], v[96:99]
	v_mfma_f32_16x16x32_bf16 v[84:87], v[160:163], v[204:207], v[84:87]
	v_mfma_f32_16x16x32_bf16 v[80:83], v[178:181], v[204:207], v[80:83]
	v_mfma_f32_16x16x32_bf16 v[68:71], v[160:163], v[212:215], v[68:71]
	v_mfma_f32_16x16x32_bf16 v[64:67], v[178:181], v[212:215], v[64:67]
	v_mfma_f32_16x16x32_bf16 v[116:119], v[164:167], v[190:193], v[116:119]
	v_mfma_f32_16x16x32_bf16 v[112:115], v[182:185], v[190:193], v[112:115]
	v_mfma_f32_16x16x32_bf16 v[100:103], v[164:167], v[200:203], v[100:103]
	v_mfma_f32_16x16x32_bf16 v[96:99], v[182:185], v[200:203], v[96:99]
	v_mfma_f32_16x16x32_bf16 v[84:87], v[164:167], v[208:211], v[84:87]
	v_mfma_f32_16x16x32_bf16 v[80:83], v[182:185], v[208:211], v[80:83]
	v_mfma_f32_16x16x32_bf16 v[68:71], v[164:167], v[216:219], v[68:71]
	v_mfma_f32_16x16x32_bf16 v[64:67], v[182:185], v[216:219], v[64:67]
	s_barrier
; #define PG8_STAGE_T(bufoff, gbase, voff, AUX) do { _Pragma("unroll") for (int _i = 0; _i < 2; ++_i) \
;         __builtin_amdgcn_global_load_lds((const unsigned*)((const char*)(gbase) + (voff)[_i]), (PG8_LAS unsigned*)(lds + (bufoff) + ldsw + _i * 8192), 16, 0, AUX); } while (0)
; #define PG8_LDA(dst, b, h) do { _Pragma("unroll") for (int m = 0; m < 4; ++m) _Pragma("unroll") for (int k = 0; k < 2; ++k) dst[m][k] = *(const PG8_LAS bf16x8*)(lds + PG8_SA(b, h) + aoff + m * 2048 + k * 1024); } while (0)
; #define PG8_MMA(ai, bj, At, Bt) do { __builtin_amdgcn_s_setprio(1); _Pragma("unroll") for (int m = 0; m < 4; ++m) _Pragma("unroll") for (int n = 0; n < 2; ++n) _Pragma("unroll") for (int k = 0; k < 2; ++k) \
;         acc[ai][bj][m][n] = __builtin_amdgcn_mfma_f32_16x16x32_bf16(Bt[n][k], At[m][k], acc[ai][bj][m][n], 0, 0, 0); __builtin_amdgcn_s_setprio(0); } while (0)
; #define PG8_WAIT_V(n) asm volatile("s_waitcnt vmcnt(" #n ")" ::: "memory")
; #define PG8_WAIT_L(n) asm volatile("s_waitcnt lgkmcnt(" #n ")" ::: "memory")
; #define PG8_BAR __builtin_amdgcn_s_barrier()
; #define PG8_SCHED __builtin_amdgcn_sched_barrier(0)
;     ...
;         for (int t = 0; t < nt; t += 2) {
;     ...
;             PG8_LDA(At, 1, 1); PG8_STAGE_T(PG8_SB(1, 0), b3, voffB, AUX_B); PG8_STAGE_T(PG8_SB(1, 1), b3 + hstep, voffB, AUX_B); PG8_STAGE_T(PG8_SA(1, 0), a3, voffA, AUX_A);
;             PG8_WAIT_V(8); PG8_WAIT_L(0); PG8_BAR; PG8_MMA(1, 0, At, B0); PG8_MMA(1, 1, At, B1); PG8_BAR; PG8_SCHED;
	s_add_i32 s40, s62, s42
	v_lshl_add_u64 v[168:169], v[168:169], 0, s[24:25]
	s_mov_b32 m0, s40
	ds_read_b128 v[186:189], v175 offset:49152
	ds_read_b128 v[190:193], v175 offset:50176
	ds_read_b128 v[196:199], v175 offset:51200
	ds_read_b128 v[200:203], v175 offset:52224
	ds_read_b128 v[204:207], v175 offset:53248
	ds_read_b128 v[208:211], v175 offset:54272
	ds_read_b128 v[212:215], v175 offset:55296
	ds_read_b128 v[216:219], v175 offset:56320
	global_load_lds_dwordx4 v[168:169], off
	v_lshl_add_u64 v[168:169], v[220:221], 0, s[24:25]
	s_add_i32 m0, s40, 0x2000
	s_add_i32 s40, s63, s42
	global_load_lds_dwordx4 v[168:169], off
	v_lshl_add_u64 v[168:169], v[222:223], 0, s[24:25]
	s_mov_b32 m0, s40
	s_nop 0
	global_load_lds_dwordx4 v[168:169], off
	v_lshl_add_u64 v[168:169], v[224:225], 0, s[24:25]
	s_add_i32 m0, s40, 0x2000
	s_nop 0
	global_load_lds_dwordx4 v[168:169], off
	v_lshl_add_u64 v[168:169], v[226:227], 0, s[24:25]
	s_mov_b32 m0, s47
	s_nop 0
	global_load_lds_dwordx4 v[168:169], off
	v_lshl_add_u64 v[168:169], v[228:229], 0, s[24:25]
	s_mov_b32 m0, s48
	s_nop 0
	global_load_lds_dwordx4 v[168:169], off
	s_waitcnt vmcnt(8)
	s_waitcnt lgkmcnt(0)
	s_barrier
	s_waitcnt lgkmcnt(0)
	v_mfma_f32_16x16x32_bf16 v[60:63], v[128:131], v[186:189], v[60:63]
	v_mfma_f32_16x16x32_bf16 v[56:59], v[152:155], v[186:189], v[56:59]
	v_mfma_f32_16x16x32_bf16 v[44:47], v[128:131], v[196:199], v[44:47]
	v_mfma_f32_16x16x32_bf16 v[40:43], v[152:155], v[196:199], v[40:43]
	v_mfma_f32_16x16x32_bf16 v[28:31], v[128:131], v[204:207], v[28:31]
	v_mfma_f32_16x16x32_bf16 v[24:27], v[152:155], v[204:207], v[24:27]
	v_mfma_f32_16x16x32_bf16 v[12:15], v[128:131], v[212:215], v[12:15]
	v_mfma_f32_16x16x32_bf16 v[8:11], v[152:155], v[212:215], v[8:11]
	v_mfma_f32_16x16x32_bf16 v[60:63], v[132:135], v[190:193], v[60:63]
	v_mfma_f32_16x16x32_bf16 v[56:59], v[156:159], v[190:193], v[56:59]
	v_mfma_f32_16x16x32_bf16 v[44:47], v[132:135], v[200:203], v[44:47]
	v_mfma_f32_16x16x32_bf16 v[40:43], v[156:159], v[200:203], v[40:43]
	v_mfma_f32_16x16x32_bf16 v[28:31], v[132:135], v[208:211], v[28:31]
	v_mfma_f32_16x16x32_bf16 v[24:27], v[156:159], v[208:211], v[24:27]
	v_mfma_f32_16x16x32_bf16 v[12:15], v[132:135], v[216:219], v[12:15]
	v_mfma_f32_16x16x32_bf16 v[8:11], v[156:159], v[216:219], v[8:11]
	v_mfma_f32_16x16x32_bf16 v[52:55], v[160:163], v[186:189], v[52:55]
	v_mfma_f32_16x16x32_bf16 v[48:51], v[178:181], v[186:189], v[48:51]
	v_mfma_f32_16x16x32_bf16 v[36:39], v[160:163], v[196:199], v[36:39]
	v_mfma_f32_16x16x32_bf16 v[32:35], v[178:181], v[196:199], v[32:35]
	v_mfma_f32_16x16x32_bf16 v[20:23], v[160:163], v[204:207], v[20:23]
	v_mfma_f32_16x16x32_bf16 v[16:19], v[178:181], v[204:207], v[16:19]
	v_mfma_f32_16x16x32_bf16 v[4:7], v[160:163], v[212:215], v[4:7]
	v_mfma_f32_16x16x32_bf16 v[0:3], v[178:181], v[212:215], v[0:3]
	v_mfma_f32_16x16x32_bf16 v[52:55], v[164:167], v[190:193], v[52:55]
	v_mfma_f32_16x16x32_bf16 v[48:51], v[182:185], v[190:193], v[48:51]
	v_mfma_f32_16x16x32_bf16 v[36:39], v[164:167], v[200:203], v[36:39]
	v_mfma_f32_16x16x32_bf16 v[32:35], v[182:185], v[200:203], v[32:35]
	v_mfma_f32_16x16x32_bf16 v[20:23], v[164:167], v[208:211], v[20:23]
	v_mfma_f32_16x16x32_bf16 v[16:19], v[182:185], v[208:211], v[16:19]
	v_mfma_f32_16x16x32_bf16 v[4:7], v[164:167], v[216:219], v[4:7]
	v_mfma_f32_16x16x32_bf16 v[0:3], v[182:185], v[216:219], v[0:3]
	s_barrier
	s_add_u32 s38, s38, 0x100
	s_addc_u32 s39, s39, 0
	s_add_u32 s59, s59, 0x100
	s_addc_u32 s60, s60, 0
	s_cmp_ge_i32 s61, s49
	s_mov_b32 s40, s61
	s_cbranch_scc0 .LBB0_1389
